# GEMM K-loops: pointer-advance pair used as the M0 wait-state filler (one ds_read leaves each of two request clusters)
# speedup vs baseline: 1.0026x; 1.0026x over previous
; #define PG8_STAGE(bufoff, gbase, voff) do { _Pragma("unroll") for (int _i = 0; _i < 2; ++_i) \
;         __builtin_amdgcn_global_load_lds((const unsigned*)((const char*)(gbase) + (voff)[_i]), (PG8_LAS unsigned*)(lds + (bufoff) + ldsw + _i * 8192), 16, 0, 0); } while (0)
; #define PG8_LDA(dst, b, h) do { _Pragma("unroll") for (int m = 0; m < 4; ++m) _Pragma("unroll") for (int k = 0; k < 2; ++k) dst[m][k] = *(const PG8_LAS bf16x8*)(lds + PG8_SA(b, h) + aoff + m * 2048 + k * 1024); } while (0)
; #define PG8_LDB(dst, b, h) do { _Pragma("unroll") for (int n = 0; n < 2; ++n) _Pragma("unroll") for (int k = 0; k < 2; ++k) dst[n][k] = *(const PG8_LAS bf16x8*)(lds + PG8_SB(b, h) + boff + n * 2048 + k * 1024); } while (0)
; #define PG8_MMA(ai, bj, At, Bt) do { __builtin_amdgcn_s_setprio(1); _Pragma("unroll") for (int m = 0; m < 4; ++m) _Pragma("unroll") for (int n = 0; n < 2; ++n) _Pragma("unroll") for (int k = 0; k < 2; ++k) \
;         acc[ai][bj][m][n] = __builtin_amdgcn_mfma_f32_16x16x32_bf16(Bt[n][k], At[m][k], acc[ai][bj][m][n], 0, 0, 0); __builtin_amdgcn_s_setprio(0); } while (0)
; #define PG8_WAIT_V(n) asm volatile("s_waitcnt vmcnt(" #n ")" ::: "memory")
; #define PG8_WAIT_L(n) asm volatile("s_waitcnt lgkmcnt(" #n ")" ::: "memory")
; template <class Epi, class Sched, bool ALIGN_EPI = false, bool SP2 = false>
; __device__ __forceinline__ void gemm_phase(PG8_LAS unsigned char* lds, const Gemm g, const Sched& S, const Epi& E) {
;     ...
;             const bool last = (t == nt - 2);
;             const char* a1 = cA + (size_t)(t + 1) * kstep;
;             const char* a2 = last ? nA : cA + (size_t)(t + 2) * kstep; const char* b2 = last ? nB : cB + (size_t)(t + 2) * kstep;
;             const char* a3 = a2 + kstep; const char* b3 = b2 + kstep;
;             if (last && has_next) S.a_ready(nxt);
;             if constexpr (SP2) {
;             PG8_LDB(B0, 0, 0); PG8_LDB(B1, 0, 1); PG8_SCHED; PG8_LDA(At, 0, 0); PG8_STAGE(PG8_SA(1, 1), a1 + hstepA, voffA);
;             PG8_WAIT_V(8); PG8_WAIT_L(0); PG8_BAR; PG8_MMA(0, 0, At, B0); PG8_MMA(0, 1, At, B1); PG8_BAR; PG8_SCHED;
;             PG8_LDA(At, 0, 1); PG8_STAGE(PG8_SB(0, 0), b2, voffB); PG8_STAGE(PG8_SB(0, 1), b2 + hstep, voffB); PG8_STAGE(PG8_SA(0, 0), a2, voffA);
;             PG8_WAIT_V(8); PG8_WAIT_L(0); PG8_BAR; PG8_MMA(1, 0, At, B0); PG8_MMA(1, 1, At, B1); PG8_BAR; PG8_SCHED;
.LBB0_258:
	ds_read_b128 v[164:167], v161
	ds_read_b128 v[168:171], v161 offset:1024
	ds_read_b128 v[172:175], v161 offset:2048
	ds_read_b128 v[176:179], v161 offset:3072
	ds_read_b128 v[180:183], v162
	ds_read_b128 v[184:187], v162 offset:1024
	ds_read_b128 v[190:193], v162 offset:2048
	ds_read_b128 v[194:197], v162 offset:3072
	s_add_i32 s65, s36, 2
	s_add_u32 s66, s10, 0xfffc0080
	s_addc_u32 s37, s11, -1
	s_cmp_eq_u32 s56, s36
	s_cselect_b32 s36, s64, s66
	s_cselect_b32 s37, s29, s37
	s_cselect_b32 s67, s31, s39
	s_cselect_b32 s66, s30, s38
	s_add_i32 m0, s48, 0xc000
	ds_read_b128 v[198:201], v163
	ds_read_b128 v[202:205], v163 offset:1024
	ds_read_b128 v[206:209], v163 offset:2048
	ds_read_b128 v[210:213], v163 offset:3072
	ds_read_b128 v[214:217], v163 offset:4096
	ds_read_b128 v[218:221], v163 offset:5120
	ds_read_b128 v[222:225], v163 offset:6144
	global_load_lds_dwordx4 v138, s[10:11]
	s_add_i32 m0, s48, 0xe000
	ds_read_b128 v[226:229], v163 offset:7168
	global_load_lds_dwordx4 v142, s[10:11]
	s_waitcnt vmcnt(8) lgkmcnt(0)
	s_setprio 1
	s_barrier
	v_mfma_f32_16x16x32_bf16 v[124:127], v[164:167], v[198:201], v[124:127]
	v_mfma_f32_16x16x32_bf16 v[120:123], v[172:175], v[198:201], v[120:123]
	v_mfma_f32_16x16x32_bf16 v[108:111], v[164:167], v[206:209], v[108:111]
	v_mfma_f32_16x16x32_bf16 v[104:107], v[172:175], v[206:209], v[104:107]
	v_mfma_f32_16x16x32_bf16 v[92:95], v[164:167], v[214:217], v[92:95]
	v_mfma_f32_16x16x32_bf16 v[88:91], v[172:175], v[214:217], v[88:91]
	v_mfma_f32_16x16x32_bf16 v[76:79], v[164:167], v[222:225], v[76:79]
	v_mfma_f32_16x16x32_bf16 v[72:75], v[172:175], v[222:225], v[72:75]
	v_mfma_f32_16x16x32_bf16 v[124:127], v[168:171], v[202:205], v[124:127]
	v_mfma_f32_16x16x32_bf16 v[120:123], v[176:179], v[202:205], v[120:123]
	v_mfma_f32_16x16x32_bf16 v[108:111], v[168:171], v[210:213], v[108:111]
	v_mfma_f32_16x16x32_bf16 v[104:107], v[176:179], v[210:213], v[104:107]
	v_mfma_f32_16x16x32_bf16 v[92:95], v[168:171], v[218:221], v[92:95]
	v_mfma_f32_16x16x32_bf16 v[88:91], v[176:179], v[218:221], v[88:91]
	v_mfma_f32_16x16x32_bf16 v[76:79], v[168:171], v[226:229], v[76:79]
	v_mfma_f32_16x16x32_bf16 v[72:75], v[176:179], v[226:229], v[72:75]
	v_mfma_f32_16x16x32_bf16 v[116:119], v[180:183], v[198:201], v[116:119]
	v_mfma_f32_16x16x32_bf16 v[112:115], v[190:193], v[198:201], v[112:115]
	v_mfma_f32_16x16x32_bf16 v[100:103], v[180:183], v[206:209], v[100:103]
	v_mfma_f32_16x16x32_bf16 v[96:99], v[190:193], v[206:209], v[96:99]
	v_mfma_f32_16x16x32_bf16 v[84:87], v[180:183], v[214:217], v[84:87]
	v_mfma_f32_16x16x32_bf16 v[80:83], v[190:193], v[214:217], v[80:83]
	v_mfma_f32_16x16x32_bf16 v[68:71], v[180:183], v[222:225], v[68:71]
	v_mfma_f32_16x16x32_bf16 v[64:67], v[190:193], v[222:225], v[64:67]
	v_mfma_f32_16x16x32_bf16 v[116:119], v[184:187], v[202:205], v[116:119]
	v_mfma_f32_16x16x32_bf16 v[112:115], v[194:197], v[202:205], v[112:115]
	v_mfma_f32_16x16x32_bf16 v[100:103], v[184:187], v[210:213], v[100:103]
	v_mfma_f32_16x16x32_bf16 v[96:99], v[194:197], v[210:213], v[96:99]
	v_mfma_f32_16x16x32_bf16 v[84:87], v[184:187], v[218:221], v[84:87]
	v_mfma_f32_16x16x32_bf16 v[80:83], v[194:197], v[218:221], v[80:83]
	v_mfma_f32_16x16x32_bf16 v[68:71], v[184:187], v[226:229], v[68:71]
	v_mfma_f32_16x16x32_bf16 v[64:67], v[194:197], v[226:229], v[64:67]
	s_setprio 0
	s_barrier
	s_add_i32 s68, s57, s47
	s_mov_b32 m0, s68
	ds_read_b128 v[198:201], v163 offset:16384
	ds_read_b128 v[202:205], v163 offset:17408
	ds_read_b128 v[206:209], v163 offset:18432
	ds_read_b128 v[210:213], v163 offset:19456
	global_load_lds_dwordx4 v136, s[66:67]
	s_add_i32 m0, s68, 0x2000
	s_mov_b64 s[100:101], s[66:67]
	s_add_i32 s68, s58, s47
	global_load_lds_dwordx4 v134, s[66:67]
	s_mov_b32 m0, s68
	s_add_u32 s66, s66, s16
	s_addc_u32 s67, s67, s17
	global_load_lds_dwordx4 v136, s[66:67]
	s_add_i32 m0, s68, 0x2000
	ds_read_b128 v[222:225], v163 offset:22528
	global_load_lds_dwordx4 v134, s[66:67]
	s_mov_b32 m0, s48
	ds_read_b128 v[218:221], v163 offset:21504
	global_load_lds_dwordx4 v128, s[36:37]
	s_mov_b32 m0, s49
	ds_read_b128 v[214:217], v163 offset:20480
	global_load_lds_dwordx4 v130, s[36:37]
	ds_read_b128 v[226:229], v163 offset:23552
	s_waitcnt vmcnt(8) lgkmcnt(0)
	s_setprio 1
	s_barrier
	v_mfma_f32_16x16x32_bf16 v[60:63], v[164:167], v[198:201], v[60:63]
	v_mfma_f32_16x16x32_bf16 v[56:59], v[172:175], v[198:201], v[56:59]
	v_mfma_f32_16x16x32_bf16 v[44:47], v[164:167], v[206:209], v[44:47]
	v_mfma_f32_16x16x32_bf16 v[40:43], v[172:175], v[206:209], v[40:43]
	v_mfma_f32_16x16x32_bf16 v[28:31], v[164:167], v[214:217], v[28:31]
	v_mfma_f32_16x16x32_bf16 v[24:27], v[172:175], v[214:217], v[24:27]
	v_mfma_f32_16x16x32_bf16 v[12:15], v[164:167], v[222:225], v[12:15]
	v_mfma_f32_16x16x32_bf16 v[8:11], v[172:175], v[222:225], v[8:11]
	v_mfma_f32_16x16x32_bf16 v[60:63], v[168:171], v[202:205], v[60:63]
	v_mfma_f32_16x16x32_bf16 v[56:59], v[176:179], v[202:205], v[56:59]
	v_mfma_f32_16x16x32_bf16 v[44:47], v[168:171], v[210:213], v[44:47]
	v_mfma_f32_16x16x32_bf16 v[40:43], v[176:179], v[210:213], v[40:43]
	v_mfma_f32_16x16x32_bf16 v[28:31], v[168:171], v[218:221], v[28:31]
	v_mfma_f32_16x16x32_bf16 v[24:27], v[176:179], v[218:221], v[24:27]
	v_mfma_f32_16x16x32_bf16 v[12:15], v[168:171], v[226:229], v[12:15]
	v_mfma_f32_16x16x32_bf16 v[8:11], v[176:179], v[226:229], v[8:11]
	v_mfma_f32_16x16x32_bf16 v[52:55], v[180:183], v[198:201], v[52:55]
	v_mfma_f32_16x16x32_bf16 v[48:51], v[190:193], v[198:201], v[48:51]
	v_mfma_f32_16x16x32_bf16 v[36:39], v[180:183], v[206:209], v[36:39]
	v_mfma_f32_16x16x32_bf16 v[32:35], v[190:193], v[206:209], v[32:35]
	v_mfma_f32_16x16x32_bf16 v[20:23], v[180:183], v[214:217], v[20:23]
	v_mfma_f32_16x16x32_bf16 v[16:19], v[190:193], v[214:217], v[16:19]
	v_mfma_f32_16x16x32_bf16 v[4:7], v[180:183], v[222:225], v[4:7]
	v_mfma_f32_16x16x32_bf16 v[0:3], v[190:193], v[222:225], v[0:3]
	v_mfma_f32_16x16x32_bf16 v[52:55], v[184:187], v[202:205], v[52:55]
	v_mfma_f32_16x16x32_bf16 v[48:51], v[194:197], v[202:205], v[48:51]
	v_mfma_f32_16x16x32_bf16 v[36:39], v[184:187], v[210:213], v[36:39]
	v_mfma_f32_16x16x32_bf16 v[32:35], v[194:197], v[210:213], v[32:35]
	v_mfma_f32_16x16x32_bf16 v[20:23], v[184:187], v[218:221], v[20:23]
	v_mfma_f32_16x16x32_bf16 v[16:19], v[194:197], v[218:221], v[16:19]
	v_mfma_f32_16x16x32_bf16 v[4:7], v[184:187], v[226:229], v[4:7]
	v_mfma_f32_16x16x32_bf16 v[0:3], v[194:197], v[226:229], v[0:3]
	s_setprio 0
	s_barrier
; #define PG8_STAGE(bufoff, gbase, voff) do { _Pragma("unroll") for (int _i = 0; _i < 2; ++_i) \
;         __builtin_amdgcn_global_load_lds((const unsigned*)((const char*)(gbase) + (voff)[_i]), (PG8_LAS unsigned*)(lds + (bufoff) + ldsw + _i * 8192), 16, 0, 0); } while (0)
; #define PG8_LDA(dst, b, h) do { _Pragma("unroll") for (int m = 0; m < 4; ++m) _Pragma("unroll") for (int k = 0; k < 2; ++k) dst[m][k] = *(const PG8_LAS bf16x8*)(lds + PG8_SA(b, h) + aoff + m * 2048 + k * 1024); } while (0)
; #define PG8_LDB(dst, b, h) do { _Pragma("unroll") for (int n = 0; n < 2; ++n) _Pragma("unroll") for (int k = 0; k < 2; ++k) dst[n][k] = *(const PG8_LAS bf16x8*)(lds + PG8_SB(b, h) + boff + n * 2048 + k * 1024); } while (0)
; #define PG8_MMA(ai, bj, At, Bt) do { __builtin_amdgcn_s_setprio(1); _Pragma("unroll") for (int m = 0; m < 4; ++m) _Pragma("unroll") for (int n = 0; n < 2; ++n) _Pragma("unroll") for (int k = 0; k < 2; ++k) \
;         acc[ai][bj][m][n] = __builtin_amdgcn_mfma_f32_16x16x32_bf16(Bt[n][k], At[m][k], acc[ai][bj][m][n], 0, 0, 0); __builtin_amdgcn_s_setprio(0); } while (0)
; #define PG8_WAIT_V(n) asm volatile("s_waitcnt vmcnt(" #n ")" ::: "memory")
; #define PG8_WAIT_L(n) asm volatile("s_waitcnt lgkmcnt(" #n ")" ::: "memory")
; #define PG8_BAR __builtin_amdgcn_s_barrier()
; #define PG8_SCHED __builtin_amdgcn_sched_barrier(0)
; template <class Epi, class Sched, bool ALIGN_EPI = false, bool SP2 = false>
; __device__ __forceinline__ void gemm_phase(PG8_LAS unsigned char* lds, const Gemm g, const Sched& S, const Epi& E) {
;     ...
;         for (int t = 0; t < nt; t += 2) {
;     ...
;             PG8_LDB(B0, 1, 0); PG8_LDB(B1, 1, 1); PG8_SCHED; PG8_LDA(At, 1, 0); PG8_STAGE(PG8_SA(0, 1), a2 + hstepA, voffA);
;             PG8_WAIT_V(8); PG8_WAIT_L(0); PG8_BAR; PG8_MMA(0, 0, At, B0); PG8_MMA(0, 1, At, B1); PG8_BAR; PG8_SCHED;
;             PG8_LDA(At, 1, 1); PG8_STAGE(PG8_SB(1, 0), b3, voffB); PG8_STAGE(PG8_SB(1, 1), b3 + hstep, voffB); PG8_STAGE(PG8_SA(1, 0), a3, voffA);
;             PG8_WAIT_V(8); PG8_WAIT_L(0); PG8_BAR; PG8_MMA(1, 0, At, B0); PG8_MMA(1, 1, At, B1); PG8_BAR; PG8_SCHED;
	s_add_i32 s66, 0, 0x18000
	s_add_i32 s67, 0, 0x1c000
	v_add_u32_e32 v176, s66, v159
	v_add_u32_e32 v189, s67, v159
	ds_read_b128 v[164:167], v176
	ds_read_b128 v[168:171], v176 offset:1024
	ds_read_b128 v[172:175], v176 offset:2048
	ds_read_b128 v[176:179], v176 offset:3072
	ds_read_b128 v[180:183], v189
	ds_read_b128 v[184:187], v189 offset:1024
	ds_read_b128 v[190:193], v189 offset:2048
	ds_read_b128 v[194:197], v189 offset:3072
	s_mov_b64 vcc, s[36:37]
	s_add_u32 s36, s36, 0x40000
	s_addc_u32 s37, s37, 0
	s_mov_b32 m0, s50
	ds_read_b128 v[198:201], v163 offset:32768
	ds_read_b128 v[202:205], v163 offset:33792
	ds_read_b128 v[206:209], v163 offset:34816
	ds_read_b128 v[210:213], v163 offset:35840
	ds_read_b128 v[214:217], v163 offset:36864
	ds_read_b128 v[218:221], v163 offset:37888
	ds_read_b128 v[222:225], v163 offset:38912
	global_load_lds_dwordx4 v128, s[36:37]
	s_mov_b32 m0, s51
	ds_read_b128 v[226:229], v163 offset:39936
	global_load_lds_dwordx4 v130, s[36:37]
	s_waitcnt vmcnt(8) lgkmcnt(0)
	s_setprio 1
	s_barrier
	v_mfma_f32_16x16x32_bf16 v[124:127], v[164:167], v[198:201], v[124:127]
	v_mfma_f32_16x16x32_bf16 v[120:123], v[172:175], v[198:201], v[120:123]
	v_mfma_f32_16x16x32_bf16 v[108:111], v[164:167], v[206:209], v[108:111]
	v_mfma_f32_16x16x32_bf16 v[104:107], v[172:175], v[206:209], v[104:107]
	v_mfma_f32_16x16x32_bf16 v[92:95], v[164:167], v[214:217], v[92:95]
	v_mfma_f32_16x16x32_bf16 v[88:91], v[172:175], v[214:217], v[88:91]
	v_mfma_f32_16x16x32_bf16 v[76:79], v[164:167], v[222:225], v[76:79]
	v_mfma_f32_16x16x32_bf16 v[72:75], v[172:175], v[222:225], v[72:75]
	v_mfma_f32_16x16x32_bf16 v[124:127], v[168:171], v[202:205], v[124:127]
	v_mfma_f32_16x16x32_bf16 v[120:123], v[176:179], v[202:205], v[120:123]
	v_mfma_f32_16x16x32_bf16 v[108:111], v[168:171], v[210:213], v[108:111]
	v_mfma_f32_16x16x32_bf16 v[104:107], v[176:179], v[210:213], v[104:107]
	v_mfma_f32_16x16x32_bf16 v[92:95], v[168:171], v[218:221], v[92:95]
	v_mfma_f32_16x16x32_bf16 v[88:91], v[176:179], v[218:221], v[88:91]
	v_mfma_f32_16x16x32_bf16 v[76:79], v[168:171], v[226:229], v[76:79]
	v_mfma_f32_16x16x32_bf16 v[72:75], v[176:179], v[226:229], v[72:75]
	v_mfma_f32_16x16x32_bf16 v[116:119], v[180:183], v[198:201], v[116:119]
	v_mfma_f32_16x16x32_bf16 v[112:115], v[190:193], v[198:201], v[112:115]
	v_mfma_f32_16x16x32_bf16 v[100:103], v[180:183], v[206:209], v[100:103]
	v_mfma_f32_16x16x32_bf16 v[96:99], v[190:193], v[206:209], v[96:99]
	v_mfma_f32_16x16x32_bf16 v[84:87], v[180:183], v[214:217], v[84:87]
	v_mfma_f32_16x16x32_bf16 v[80:83], v[190:193], v[214:217], v[80:83]
	v_mfma_f32_16x16x32_bf16 v[68:71], v[180:183], v[222:225], v[68:71]
	v_mfma_f32_16x16x32_bf16 v[64:67], v[190:193], v[222:225], v[64:67]
	v_mfma_f32_16x16x32_bf16 v[116:119], v[184:187], v[202:205], v[116:119]
	v_mfma_f32_16x16x32_bf16 v[112:115], v[194:197], v[202:205], v[112:115]
	v_mfma_f32_16x16x32_bf16 v[100:103], v[184:187], v[210:213], v[100:103]
	v_mfma_f32_16x16x32_bf16 v[96:99], v[194:197], v[210:213], v[96:99]
	v_mfma_f32_16x16x32_bf16 v[84:87], v[184:187], v[218:221], v[84:87]
	v_mfma_f32_16x16x32_bf16 v[80:83], v[194:197], v[218:221], v[80:83]
	v_mfma_f32_16x16x32_bf16 v[68:71], v[184:187], v[226:229], v[68:71]
	v_mfma_f32_16x16x32_bf16 v[64:67], v[194:197], v[226:229], v[64:67]
	s_setprio 0
	s_barrier
	s_add_i32 s36, s66, s47
	s_add_i32 m0, s36, 0xffffff80
	ds_read_b128 v[198:201], v163 offset:49152
	ds_read_b128 v[202:205], v163 offset:50176
	ds_read_b128 v[206:209], v163 offset:51200
	ds_read_b128 v[210:213], v163 offset:52224
	global_load_lds_dwordx4 v136, s[100:101] offset:128
	s_add_i32 m0, s36, 0x1f80
	s_add_i32 s36, s67, s47
	global_load_lds_dwordx4 v134, s[100:101] offset:128
	s_add_i32 m0, s36, 0xffffff80
	s_add_u32 s100, s100, s16
	s_addc_u32 s101, s101, s17
	global_load_lds_dwordx4 v136, s[100:101] offset:128
	s_add_i32 m0, s36, 0x1f80
	ds_read_b128 v[222:225], v163 offset:55296
	global_load_lds_dwordx4 v134, s[100:101] offset:128
	s_add_i32 m0, s52, 0xffffff80
	ds_read_b128 v[218:221], v163 offset:54272
	global_load_lds_dwordx4 v128, vcc offset:128
	s_add_i32 m0, s53, 0xffffff80
	ds_read_b128 v[214:217], v163 offset:53248
	global_load_lds_dwordx4 v130, vcc offset:128
	ds_read_b128 v[226:229], v163 offset:56320
	s_waitcnt vmcnt(8) lgkmcnt(0)
	s_setprio 1
	s_barrier
	v_mfma_f32_16x16x32_bf16 v[60:63], v[164:167], v[198:201], v[60:63]
	v_mfma_f32_16x16x32_bf16 v[56:59], v[172:175], v[198:201], v[56:59]
	v_mfma_f32_16x16x32_bf16 v[44:47], v[164:167], v[206:209], v[44:47]
	v_mfma_f32_16x16x32_bf16 v[40:43], v[172:175], v[206:209], v[40:43]
	v_mfma_f32_16x16x32_bf16 v[28:31], v[164:167], v[214:217], v[28:31]
	v_mfma_f32_16x16x32_bf16 v[24:27], v[172:175], v[214:217], v[24:27]
	v_mfma_f32_16x16x32_bf16 v[12:15], v[164:167], v[222:225], v[12:15]
	v_mfma_f32_16x16x32_bf16 v[8:11], v[172:175], v[222:225], v[8:11]
	v_mfma_f32_16x16x32_bf16 v[60:63], v[168:171], v[202:205], v[60:63]
	v_mfma_f32_16x16x32_bf16 v[56:59], v[176:179], v[202:205], v[56:59]
	v_mfma_f32_16x16x32_bf16 v[44:47], v[168:171], v[210:213], v[44:47]
	v_mfma_f32_16x16x32_bf16 v[40:43], v[176:179], v[210:213], v[40:43]
	v_mfma_f32_16x16x32_bf16 v[28:31], v[168:171], v[218:221], v[28:31]
	v_mfma_f32_16x16x32_bf16 v[24:27], v[176:179], v[218:221], v[24:27]
	v_mfma_f32_16x16x32_bf16 v[12:15], v[168:171], v[226:229], v[12:15]
	v_mfma_f32_16x16x32_bf16 v[8:11], v[176:179], v[226:229], v[8:11]
	v_mfma_f32_16x16x32_bf16 v[52:55], v[180:183], v[198:201], v[52:55]
	v_mfma_f32_16x16x32_bf16 v[48:51], v[190:193], v[198:201], v[48:51]
	v_mfma_f32_16x16x32_bf16 v[36:39], v[180:183], v[206:209], v[36:39]
	v_mfma_f32_16x16x32_bf16 v[32:35], v[190:193], v[206:209], v[32:35]
	v_mfma_f32_16x16x32_bf16 v[20:23], v[180:183], v[214:217], v[20:23]
	v_mfma_f32_16x16x32_bf16 v[16:19], v[190:193], v[214:217], v[16:19]
	v_mfma_f32_16x16x32_bf16 v[4:7], v[180:183], v[222:225], v[4:7]
	v_mfma_f32_16x16x32_bf16 v[0:3], v[190:193], v[222:225], v[0:3]
	v_mfma_f32_16x16x32_bf16 v[52:55], v[184:187], v[202:205], v[52:55]
	v_mfma_f32_16x16x32_bf16 v[48:51], v[194:197], v[202:205], v[48:51]
	v_mfma_f32_16x16x32_bf16 v[36:39], v[184:187], v[210:213], v[36:39]
	v_mfma_f32_16x16x32_bf16 v[32:35], v[194:197], v[210:213], v[32:35]
	v_mfma_f32_16x16x32_bf16 v[20:23], v[184:187], v[218:221], v[20:23]
	v_mfma_f32_16x16x32_bf16 v[16:19], v[194:197], v[218:221], v[16:19]
	v_mfma_f32_16x16x32_bf16 v[4:7], v[184:187], v[226:229], v[4:7]
	v_mfma_f32_16x16x32_bf16 v[0:3], v[194:197], v[226:229], v[0:3]
	s_setprio 0
	s_barrier
	s_add_u32 s10, s10, 0x100
	s_addc_u32 s11, s11, 0
	s_add_u32 s38, s38, 0x100
	s_addc_u32 s39, s39, 0
	s_cmp_ge_i32 s65, s54
	s_mov_b32 s36, s65
	s_cbranch_scc0 .LBB0_258

; #define PG8_STAGE(bufoff, gbase, voff) do { _Pragma("unroll") for (int _i = 0; _i < 2; ++_i) \
;         __builtin_amdgcn_global_load_lds((const unsigned*)((const char*)(gbase) + (voff)[_i]), (PG8_LAS unsigned*)(lds + (bufoff) + ldsw + _i * 8192), 16, 0, 0); } while (0)
; #define PG8_LDA(dst, b, h) do { _Pragma("unroll") for (int m = 0; m < 4; ++m) _Pragma("unroll") for (int k = 0; k < 2; ++k) dst[m][k] = *(const PG8_LAS bf16x8*)(lds + PG8_SA(b, h) + aoff + m * 2048 + k * 1024); } while (0)
; #define PG8_LDB(dst, b, h) do { _Pragma("unroll") for (int n = 0; n < 2; ++n) _Pragma("unroll") for (int k = 0; k < 2; ++k) dst[n][k] = *(const PG8_LAS bf16x8*)(lds + PG8_SB(b, h) + boff + n * 2048 + k * 1024); } while (0)
; #define PG8_MMA(ai, bj, At, Bt) do { __builtin_amdgcn_s_setprio(1); _Pragma("unroll") for (int m = 0; m < 4; ++m) _Pragma("unroll") for (int n = 0; n < 2; ++n) _Pragma("unroll") for (int k = 0; k < 2; ++k) \
;         acc[ai][bj][m][n] = __builtin_amdgcn_mfma_f32_16x16x32_bf16(Bt[n][k], At[m][k], acc[ai][bj][m][n], 0, 0, 0); __builtin_amdgcn_s_setprio(0); } while (0)
; #define PG8_WAIT_V(n) asm volatile("s_waitcnt vmcnt(" #n ")" ::: "memory")
; #define PG8_WAIT_L(n) asm volatile("s_waitcnt lgkmcnt(" #n ")" ::: "memory")
; template <class Epi, class Sched, bool ALIGN_EPI = false, bool SP2 = false>
; __device__ __forceinline__ void gemm_phase(PG8_LAS unsigned char* lds, const Gemm g, const Sched& S, const Epi& E) {
;     ...
;             const bool last = (t == nt - 2);
;             const char* a1 = cA + (size_t)(t + 1) * kstep;
;             const char* a2 = last ? nA : cA + (size_t)(t + 2) * kstep; const char* b2 = last ? nB : cB + (size_t)(t + 2) * kstep;
;             const char* a3 = a2 + kstep; const char* b3 = b2 + kstep;
;             if (last && has_next) S.a_ready(nxt);
;             if constexpr (SP2) {
;             PG8_LDB(B0, 0, 0); PG8_LDB(B1, 0, 1); PG8_SCHED; PG8_LDA(At, 0, 0); PG8_STAGE(PG8_SA(1, 1), a1 + hstepA, voffA);
;             PG8_WAIT_V(8); PG8_WAIT_L(0); PG8_BAR; PG8_MMA(0, 0, At, B0); PG8_MMA(0, 1, At, B1); PG8_BAR; PG8_SCHED;
;             PG8_LDA(At, 0, 1); PG8_STAGE(PG8_SB(0, 0), b2, voffB); PG8_STAGE(PG8_SB(0, 1), b2 + hstep, voffB); PG8_STAGE(PG8_SA(0, 0), a2, voffA);
;             PG8_WAIT_V(8); PG8_WAIT_L(0); PG8_BAR; PG8_MMA(1, 0, At, B0); PG8_MMA(1, 1, At, B1); PG8_BAR; PG8_SCHED;
.LBB0_282:
	ds_read_b128 v[148:151], v144
	ds_read_b128 v[152:155], v144 offset:1024
	ds_read_b128 v[156:159], v144 offset:2048
	ds_read_b128 v[160:163], v144 offset:3072
	ds_read_b128 v[164:167], v145
	ds_read_b128 v[168:171], v145 offset:1024
	ds_read_b128 v[172:175], v145 offset:2048
	ds_read_b128 v[176:179], v145 offset:3072
	s_add_i32 s61, s34, 2
	s_add_u32 s62, s30, 0xfffc0080
	s_addc_u32 s35, s31, -1
	s_cmp_eq_u32 s52, s34
	s_cselect_b32 s34, s36, s62
	s_cselect_b32 s35, s5, s35
	s_cselect_b32 s63, s27, s60
	s_cselect_b32 s62, s26, s37
	s_add_i32 m0, s33, 0xc000
	ds_read_b128 v[180:183], v146
	ds_read_b128 v[184:187], v146 offset:1024
	ds_read_b128 v[190:193], v146 offset:2048
	ds_read_b128 v[194:197], v146 offset:3072
	ds_read_b128 v[198:201], v146 offset:4096
	ds_read_b128 v[202:205], v146 offset:5120
	ds_read_b128 v[206:209], v146 offset:6144
	global_load_lds_dwordx4 v138, s[30:31]
	s_add_i32 m0, s33, 0xe000
	ds_read_b128 v[210:213], v146 offset:7168
	global_load_lds_dwordx4 v140, s[30:31]
	s_waitcnt vmcnt(8) lgkmcnt(0)
	s_setprio 1
	s_barrier
	v_mfma_f32_16x16x32_bf16 v[124:127], v[148:151], v[180:183], v[124:127]
	v_mfma_f32_16x16x32_bf16 v[120:123], v[156:159], v[180:183], v[120:123]
	v_mfma_f32_16x16x32_bf16 v[108:111], v[148:151], v[190:193], v[108:111]
	v_mfma_f32_16x16x32_bf16 v[104:107], v[156:159], v[190:193], v[104:107]
	v_mfma_f32_16x16x32_bf16 v[92:95], v[148:151], v[198:201], v[92:95]
	v_mfma_f32_16x16x32_bf16 v[88:91], v[156:159], v[198:201], v[88:91]
	v_mfma_f32_16x16x32_bf16 v[76:79], v[148:151], v[206:209], v[76:79]
	v_mfma_f32_16x16x32_bf16 v[72:75], v[156:159], v[206:209], v[72:75]
	v_mfma_f32_16x16x32_bf16 v[124:127], v[152:155], v[184:187], v[124:127]
	v_mfma_f32_16x16x32_bf16 v[120:123], v[160:163], v[184:187], v[120:123]
	v_mfma_f32_16x16x32_bf16 v[108:111], v[152:155], v[194:197], v[108:111]
	v_mfma_f32_16x16x32_bf16 v[104:107], v[160:163], v[194:197], v[104:107]
	v_mfma_f32_16x16x32_bf16 v[92:95], v[152:155], v[202:205], v[92:95]
	v_mfma_f32_16x16x32_bf16 v[88:91], v[160:163], v[202:205], v[88:91]
	v_mfma_f32_16x16x32_bf16 v[76:79], v[152:155], v[210:213], v[76:79]
	v_mfma_f32_16x16x32_bf16 v[72:75], v[160:163], v[210:213], v[72:75]
	v_mfma_f32_16x16x32_bf16 v[116:119], v[164:167], v[180:183], v[116:119]
	v_mfma_f32_16x16x32_bf16 v[112:115], v[172:175], v[180:183], v[112:115]
	v_mfma_f32_16x16x32_bf16 v[100:103], v[164:167], v[190:193], v[100:103]
	v_mfma_f32_16x16x32_bf16 v[96:99], v[172:175], v[190:193], v[96:99]
	v_mfma_f32_16x16x32_bf16 v[84:87], v[164:167], v[198:201], v[84:87]
	v_mfma_f32_16x16x32_bf16 v[80:83], v[172:175], v[198:201], v[80:83]
	v_mfma_f32_16x16x32_bf16 v[68:71], v[164:167], v[206:209], v[68:71]
	v_mfma_f32_16x16x32_bf16 v[64:67], v[172:175], v[206:209], v[64:67]
	v_mfma_f32_16x16x32_bf16 v[116:119], v[168:171], v[184:187], v[116:119]
	v_mfma_f32_16x16x32_bf16 v[112:115], v[176:179], v[184:187], v[112:115]
	v_mfma_f32_16x16x32_bf16 v[100:103], v[168:171], v[194:197], v[100:103]
	v_mfma_f32_16x16x32_bf16 v[96:99], v[176:179], v[194:197], v[96:99]
	v_mfma_f32_16x16x32_bf16 v[84:87], v[168:171], v[202:205], v[84:87]
	v_mfma_f32_16x16x32_bf16 v[80:83], v[176:179], v[202:205], v[80:83]
	v_mfma_f32_16x16x32_bf16 v[68:71], v[168:171], v[210:213], v[68:71]
	v_mfma_f32_16x16x32_bf16 v[64:67], v[176:179], v[210:213], v[64:67]
	s_setprio 0
	s_barrier
	s_add_i32 s64, s53, s44
	s_mov_b32 m0, s64
	ds_read_b128 v[180:183], v146 offset:16384
	ds_read_b128 v[184:187], v146 offset:17408
	ds_read_b128 v[190:193], v146 offset:18432
	ds_read_b128 v[194:197], v146 offset:19456
	global_load_lds_dwordx4 v132, s[62:63]
	s_add_i32 m0, s64, 0x2000
	s_mov_b64 s[100:101], s[62:63]
	s_add_i32 s64, s54, s44
	global_load_lds_dwordx4 v134, s[62:63]
	s_mov_b32 m0, s64
	s_add_u32 s62, s62, s16
	s_addc_u32 s63, s63, s17
	global_load_lds_dwordx4 v132, s[62:63]
	s_add_i32 m0, s64, 0x2000
	ds_read_b128 v[206:209], v146 offset:22528
	global_load_lds_dwordx4 v134, s[62:63]
	s_mov_b32 m0, s33
	ds_read_b128 v[202:205], v146 offset:21504
	global_load_lds_dwordx4 v128, s[34:35]
	s_mov_b32 m0, s43
	ds_read_b128 v[198:201], v146 offset:20480
	global_load_lds_dwordx4 v130, s[34:35]
	ds_read_b128 v[210:213], v146 offset:23552
	s_waitcnt vmcnt(8) lgkmcnt(0)
	s_setprio 1
	s_barrier
	v_mfma_f32_16x16x32_bf16 v[60:63], v[148:151], v[180:183], v[60:63]
	v_mfma_f32_16x16x32_bf16 v[56:59], v[156:159], v[180:183], v[56:59]
	v_mfma_f32_16x16x32_bf16 v[44:47], v[148:151], v[190:193], v[44:47]
	v_mfma_f32_16x16x32_bf16 v[40:43], v[156:159], v[190:193], v[40:43]
	v_mfma_f32_16x16x32_bf16 v[28:31], v[148:151], v[198:201], v[28:31]
	v_mfma_f32_16x16x32_bf16 v[24:27], v[156:159], v[198:201], v[24:27]
	v_mfma_f32_16x16x32_bf16 v[12:15], v[148:151], v[206:209], v[12:15]
	v_mfma_f32_16x16x32_bf16 v[8:11], v[156:159], v[206:209], v[8:11]
	v_mfma_f32_16x16x32_bf16 v[60:63], v[152:155], v[184:187], v[60:63]
	v_mfma_f32_16x16x32_bf16 v[56:59], v[160:163], v[184:187], v[56:59]
	v_mfma_f32_16x16x32_bf16 v[44:47], v[152:155], v[194:197], v[44:47]
	v_mfma_f32_16x16x32_bf16 v[40:43], v[160:163], v[194:197], v[40:43]
	v_mfma_f32_16x16x32_bf16 v[28:31], v[152:155], v[202:205], v[28:31]
	v_mfma_f32_16x16x32_bf16 v[24:27], v[160:163], v[202:205], v[24:27]
	v_mfma_f32_16x16x32_bf16 v[12:15], v[152:155], v[210:213], v[12:15]
	v_mfma_f32_16x16x32_bf16 v[8:11], v[160:163], v[210:213], v[8:11]
	v_mfma_f32_16x16x32_bf16 v[52:55], v[164:167], v[180:183], v[52:55]
	v_mfma_f32_16x16x32_bf16 v[48:51], v[172:175], v[180:183], v[48:51]
	v_mfma_f32_16x16x32_bf16 v[36:39], v[164:167], v[190:193], v[36:39]
	v_mfma_f32_16x16x32_bf16 v[32:35], v[172:175], v[190:193], v[32:35]
	v_mfma_f32_16x16x32_bf16 v[20:23], v[164:167], v[198:201], v[20:23]
	v_mfma_f32_16x16x32_bf16 v[16:19], v[172:175], v[198:201], v[16:19]
	v_mfma_f32_16x16x32_bf16 v[4:7], v[164:167], v[206:209], v[4:7]
	v_mfma_f32_16x16x32_bf16 v[0:3], v[172:175], v[206:209], v[0:3]
	v_mfma_f32_16x16x32_bf16 v[52:55], v[168:171], v[184:187], v[52:55]
	v_mfma_f32_16x16x32_bf16 v[48:51], v[176:179], v[184:187], v[48:51]
	v_mfma_f32_16x16x32_bf16 v[36:39], v[168:171], v[194:197], v[36:39]
	v_mfma_f32_16x16x32_bf16 v[32:35], v[176:179], v[194:197], v[32:35]
	v_mfma_f32_16x16x32_bf16 v[20:23], v[168:171], v[202:205], v[20:23]
	v_mfma_f32_16x16x32_bf16 v[16:19], v[176:179], v[202:205], v[16:19]
	v_mfma_f32_16x16x32_bf16 v[4:7], v[168:171], v[210:213], v[4:7]
	v_mfma_f32_16x16x32_bf16 v[0:3], v[176:179], v[210:213], v[0:3]
	s_setprio 0
	s_barrier
; #define PG8_STAGE(bufoff, gbase, voff) do { _Pragma("unroll") for (int _i = 0; _i < 2; ++_i) \
;         __builtin_amdgcn_global_load_lds((const unsigned*)((const char*)(gbase) + (voff)[_i]), (PG8_LAS unsigned*)(lds + (bufoff) + ldsw + _i * 8192), 16, 0, 0); } while (0)
; #define PG8_LDA(dst, b, h) do { _Pragma("unroll") for (int m = 0; m < 4; ++m) _Pragma("unroll") for (int k = 0; k < 2; ++k) dst[m][k] = *(const PG8_LAS bf16x8*)(lds + PG8_SA(b, h) + aoff + m * 2048 + k * 1024); } while (0)
; #define PG8_LDB(dst, b, h) do { _Pragma("unroll") for (int n = 0; n < 2; ++n) _Pragma("unroll") for (int k = 0; k < 2; ++k) dst[n][k] = *(const PG8_LAS bf16x8*)(lds + PG8_SB(b, h) + boff + n * 2048 + k * 1024); } while (0)
; #define PG8_MMA(ai, bj, At, Bt) do { __builtin_amdgcn_s_setprio(1); _Pragma("unroll") for (int m = 0; m < 4; ++m) _Pragma("unroll") for (int n = 0; n < 2; ++n) _Pragma("unroll") for (int k = 0; k < 2; ++k) \
;         acc[ai][bj][m][n] = __builtin_amdgcn_mfma_f32_16x16x32_bf16(Bt[n][k], At[m][k], acc[ai][bj][m][n], 0, 0, 0); __builtin_amdgcn_s_setprio(0); } while (0)
; #define PG8_WAIT_V(n) asm volatile("s_waitcnt vmcnt(" #n ")" ::: "memory")
; #define PG8_WAIT_L(n) asm volatile("s_waitcnt lgkmcnt(" #n ")" ::: "memory")
; #define PG8_BAR __builtin_amdgcn_s_barrier()
; #define PG8_SCHED __builtin_amdgcn_sched_barrier(0)
; template <class Epi, class Sched, bool ALIGN_EPI = false, bool SP2 = false>
; __device__ __forceinline__ void gemm_phase(PG8_LAS unsigned char* lds, const Gemm g, const Sched& S, const Epi& E) {
;     ...
;         for (int t = 0; t < nt; t += 2) {
;     ...
;             PG8_LDB(B0, 1, 0); PG8_LDB(B1, 1, 1); PG8_SCHED; PG8_LDA(At, 1, 0); PG8_STAGE(PG8_SA(0, 1), a2 + hstepA, voffA);
;             PG8_WAIT_V(8); PG8_WAIT_L(0); PG8_BAR; PG8_MMA(0, 0, At, B0); PG8_MMA(0, 1, At, B1); PG8_BAR; PG8_SCHED;
;             PG8_LDA(At, 1, 1); PG8_STAGE(PG8_SB(1, 0), b3, voffB); PG8_STAGE(PG8_SB(1, 1), b3 + hstep, voffB); PG8_STAGE(PG8_SA(1, 0), a3, voffA);
;             PG8_WAIT_V(8); PG8_WAIT_L(0); PG8_BAR; PG8_MMA(1, 0, At, B0); PG8_MMA(1, 1, At, B1); PG8_BAR; PG8_SCHED;
	s_add_i32 s62, 0, 0x18000
	v_add_u32_e32 v147, s62, v142
	s_add_i32 s63, 0, 0x1c000
	ds_read_b128 v[148:151], v147
	ds_read_b128 v[152:155], v147 offset:1024
	ds_read_b128 v[156:159], v147 offset:2048
	ds_read_b128 v[160:163], v147 offset:3072
	v_add_u32_e32 v147, s63, v142
	ds_read_b128 v[164:167], v147
	ds_read_b128 v[168:171], v147 offset:1024
	ds_read_b128 v[172:175], v147 offset:2048
	ds_read_b128 v[176:179], v147 offset:3072
	s_mov_b64 vcc, s[34:35]
	s_add_u32 s34, s34, 0x40000
	s_addc_u32 s35, s35, 0
	s_mov_b32 m0, s45
	ds_read_b128 v[180:183], v146 offset:32768
	ds_read_b128 v[184:187], v146 offset:33792
	ds_read_b128 v[190:193], v146 offset:34816
	ds_read_b128 v[194:197], v146 offset:35840
	ds_read_b128 v[198:201], v146 offset:36864
	ds_read_b128 v[202:205], v146 offset:37888
	ds_read_b128 v[206:209], v146 offset:38912
	global_load_lds_dwordx4 v128, s[34:35]
	s_mov_b32 m0, s47
	ds_read_b128 v[210:213], v146 offset:39936
	global_load_lds_dwordx4 v130, s[34:35]
	s_waitcnt vmcnt(8) lgkmcnt(0)
	s_setprio 1
	s_barrier
	v_mfma_f32_16x16x32_bf16 v[124:127], v[148:151], v[180:183], v[124:127]
	v_mfma_f32_16x16x32_bf16 v[120:123], v[156:159], v[180:183], v[120:123]
	v_mfma_f32_16x16x32_bf16 v[108:111], v[148:151], v[190:193], v[108:111]
	v_mfma_f32_16x16x32_bf16 v[104:107], v[156:159], v[190:193], v[104:107]
	v_mfma_f32_16x16x32_bf16 v[92:95], v[148:151], v[198:201], v[92:95]
	v_mfma_f32_16x16x32_bf16 v[88:91], v[156:159], v[198:201], v[88:91]
	v_mfma_f32_16x16x32_bf16 v[76:79], v[148:151], v[206:209], v[76:79]
	v_mfma_f32_16x16x32_bf16 v[72:75], v[156:159], v[206:209], v[72:75]
	v_mfma_f32_16x16x32_bf16 v[124:127], v[152:155], v[184:187], v[124:127]
	v_mfma_f32_16x16x32_bf16 v[120:123], v[160:163], v[184:187], v[120:123]
	v_mfma_f32_16x16x32_bf16 v[108:111], v[152:155], v[194:197], v[108:111]
	v_mfma_f32_16x16x32_bf16 v[104:107], v[160:163], v[194:197], v[104:107]
	v_mfma_f32_16x16x32_bf16 v[92:95], v[152:155], v[202:205], v[92:95]
	v_mfma_f32_16x16x32_bf16 v[88:91], v[160:163], v[202:205], v[88:91]
	v_mfma_f32_16x16x32_bf16 v[76:79], v[152:155], v[210:213], v[76:79]
	v_mfma_f32_16x16x32_bf16 v[72:75], v[160:163], v[210:213], v[72:75]
	v_mfma_f32_16x16x32_bf16 v[116:119], v[164:167], v[180:183], v[116:119]
	v_mfma_f32_16x16x32_bf16 v[112:115], v[172:175], v[180:183], v[112:115]
	v_mfma_f32_16x16x32_bf16 v[100:103], v[164:167], v[190:193], v[100:103]
	v_mfma_f32_16x16x32_bf16 v[96:99], v[172:175], v[190:193], v[96:99]
	v_mfma_f32_16x16x32_bf16 v[84:87], v[164:167], v[198:201], v[84:87]
	v_mfma_f32_16x16x32_bf16 v[80:83], v[172:175], v[198:201], v[80:83]
	v_mfma_f32_16x16x32_bf16 v[68:71], v[164:167], v[206:209], v[68:71]
	v_mfma_f32_16x16x32_bf16 v[64:67], v[172:175], v[206:209], v[64:67]
	v_mfma_f32_16x16x32_bf16 v[116:119], v[168:171], v[184:187], v[116:119]
	v_mfma_f32_16x16x32_bf16 v[112:115], v[176:179], v[184:187], v[112:115]
	v_mfma_f32_16x16x32_bf16 v[100:103], v[168:171], v[194:197], v[100:103]
	v_mfma_f32_16x16x32_bf16 v[96:99], v[176:179], v[194:197], v[96:99]
	v_mfma_f32_16x16x32_bf16 v[84:87], v[168:171], v[202:205], v[84:87]
	v_mfma_f32_16x16x32_bf16 v[80:83], v[176:179], v[202:205], v[80:83]
	v_mfma_f32_16x16x32_bf16 v[68:71], v[168:171], v[210:213], v[68:71]
	v_mfma_f32_16x16x32_bf16 v[64:67], v[176:179], v[210:213], v[64:67]
	s_setprio 0
	s_barrier
	s_add_i32 s34, s62, s44
	s_add_i32 m0, s34, 0xffffff80
	ds_read_b128 v[180:183], v146 offset:49152
	ds_read_b128 v[184:187], v146 offset:50176
	ds_read_b128 v[190:193], v146 offset:51200
	ds_read_b128 v[194:197], v146 offset:52224
	global_load_lds_dwordx4 v132, s[100:101] offset:128
	s_add_i32 m0, s34, 0x1f80
	s_add_i32 s34, s63, s44
	global_load_lds_dwordx4 v134, s[100:101] offset:128
	s_add_i32 m0, s34, 0xffffff80
	s_add_u32 s100, s100, s16
	s_addc_u32 s101, s101, s17
	global_load_lds_dwordx4 v132, s[100:101] offset:128
	s_add_i32 m0, s34, 0x1f80
	ds_read_b128 v[206:209], v146 offset:55296
	global_load_lds_dwordx4 v134, s[100:101] offset:128
	s_add_i32 m0, s48, 0xffffff80
	ds_read_b128 v[202:205], v146 offset:54272
	global_load_lds_dwordx4 v128, vcc offset:128
	s_add_i32 m0, s49, 0xffffff80
	ds_read_b128 v[198:201], v146 offset:53248
	global_load_lds_dwordx4 v130, vcc offset:128
	ds_read_b128 v[210:213], v146 offset:56320
	s_waitcnt vmcnt(8) lgkmcnt(0)
	s_setprio 1
	s_barrier
	v_mfma_f32_16x16x32_bf16 v[60:63], v[148:151], v[180:183], v[60:63]
	v_mfma_f32_16x16x32_bf16 v[56:59], v[156:159], v[180:183], v[56:59]
	v_mfma_f32_16x16x32_bf16 v[44:47], v[148:151], v[190:193], v[44:47]
	v_mfma_f32_16x16x32_bf16 v[40:43], v[156:159], v[190:193], v[40:43]
	v_mfma_f32_16x16x32_bf16 v[28:31], v[148:151], v[198:201], v[28:31]
	v_mfma_f32_16x16x32_bf16 v[24:27], v[156:159], v[198:201], v[24:27]
	v_mfma_f32_16x16x32_bf16 v[12:15], v[148:151], v[206:209], v[12:15]
	v_mfma_f32_16x16x32_bf16 v[8:11], v[156:159], v[206:209], v[8:11]
	v_mfma_f32_16x16x32_bf16 v[60:63], v[152:155], v[184:187], v[60:63]
	v_mfma_f32_16x16x32_bf16 v[56:59], v[160:163], v[184:187], v[56:59]
	v_mfma_f32_16x16x32_bf16 v[44:47], v[152:155], v[194:197], v[44:47]
	v_mfma_f32_16x16x32_bf16 v[40:43], v[160:163], v[194:197], v[40:43]
	v_mfma_f32_16x16x32_bf16 v[28:31], v[152:155], v[202:205], v[28:31]
	v_mfma_f32_16x16x32_bf16 v[24:27], v[160:163], v[202:205], v[24:27]
	v_mfma_f32_16x16x32_bf16 v[12:15], v[152:155], v[210:213], v[12:15]
	v_mfma_f32_16x16x32_bf16 v[8:11], v[160:163], v[210:213], v[8:11]
	v_mfma_f32_16x16x32_bf16 v[52:55], v[164:167], v[180:183], v[52:55]
	v_mfma_f32_16x16x32_bf16 v[48:51], v[172:175], v[180:183], v[48:51]
	v_mfma_f32_16x16x32_bf16 v[36:39], v[164:167], v[190:193], v[36:39]
	v_mfma_f32_16x16x32_bf16 v[32:35], v[172:175], v[190:193], v[32:35]
	v_mfma_f32_16x16x32_bf16 v[20:23], v[164:167], v[198:201], v[20:23]
	v_mfma_f32_16x16x32_bf16 v[16:19], v[172:175], v[198:201], v[16:19]
	v_mfma_f32_16x16x32_bf16 v[4:7], v[164:167], v[206:209], v[4:7]
	v_mfma_f32_16x16x32_bf16 v[0:3], v[172:175], v[206:209], v[0:3]
	v_mfma_f32_16x16x32_bf16 v[52:55], v[168:171], v[184:187], v[52:55]
	v_mfma_f32_16x16x32_bf16 v[48:51], v[176:179], v[184:187], v[48:51]
	v_mfma_f32_16x16x32_bf16 v[36:39], v[168:171], v[194:197], v[36:39]
	v_mfma_f32_16x16x32_bf16 v[32:35], v[176:179], v[194:197], v[32:35]
	v_mfma_f32_16x16x32_bf16 v[20:23], v[168:171], v[202:205], v[20:23]
	v_mfma_f32_16x16x32_bf16 v[16:19], v[176:179], v[202:205], v[16:19]
	v_mfma_f32_16x16x32_bf16 v[4:7], v[168:171], v[210:213], v[4:7]
	v_mfma_f32_16x16x32_bf16 v[0:3], v[176:179], v[210:213], v[0:3]
	s_setprio 0
	s_barrier
	s_add_u32 s30, s30, 0x100
	s_addc_u32 s31, s31, 0
	s_add_u32 s37, s37, 0x100
	s_addc_u32 s60, s60, 0
	s_cmp_ge_i32 s61, s50
	s_mov_b32 s34, s61
	s_cbranch_scc0 .LBB0_282

; #define PG8_STAGE(bufoff, gbase, voff) do { _Pragma("unroll") for (int _i = 0; _i < 2; ++_i) \
;         __builtin_amdgcn_global_load_lds((const unsigned*)((const char*)(gbase) + (voff)[_i]), (PG8_LAS unsigned*)(lds + (bufoff) + ldsw + _i * 8192), 16, 0, 0); } while (0)
; #define PG8_LDA(dst, b, h) do { _Pragma("unroll") for (int m = 0; m < 4; ++m) _Pragma("unroll") for (int k = 0; k < 2; ++k) dst[m][k] = *(const PG8_LAS bf16x8*)(lds + PG8_SA(b, h) + aoff + m * 2048 + k * 1024); } while (0)
; #define PG8_LDB(dst, b, h) do { _Pragma("unroll") for (int n = 0; n < 2; ++n) _Pragma("unroll") for (int k = 0; k < 2; ++k) dst[n][k] = *(const PG8_LAS bf16x8*)(lds + PG8_SB(b, h) + boff + n * 2048 + k * 1024); } while (0)
; #define PG8_MMA(ai, bj, At, Bt) do { __builtin_amdgcn_s_setprio(1); _Pragma("unroll") for (int m = 0; m < 4; ++m) _Pragma("unroll") for (int n = 0; n < 2; ++n) _Pragma("unroll") for (int k = 0; k < 2; ++k) \
;         acc[ai][bj][m][n] = __builtin_amdgcn_mfma_f32_16x16x32_bf16(Bt[n][k], At[m][k], acc[ai][bj][m][n], 0, 0, 0); __builtin_amdgcn_s_setprio(0); } while (0)
; #define PG8_WAIT_V(n) asm volatile("s_waitcnt vmcnt(" #n ")" ::: "memory")
; #define PG8_WAIT_L(n) asm volatile("s_waitcnt lgkmcnt(" #n ")" ::: "memory")
; template <class Epi, class Sched, bool ALIGN_EPI = false, bool SP2 = false>
; __device__ __forceinline__ void gemm_phase(PG8_LAS unsigned char* lds, const Gemm g, const Sched& S, const Epi& E) {
;     ...
;             const bool last = (t == nt - 2);
;             const char* a1 = cA + (size_t)(t + 1) * kstep;
;             const char* a2 = last ? nA : cA + (size_t)(t + 2) * kstep; const char* b2 = last ? nB : cB + (size_t)(t + 2) * kstep;
;             const char* a3 = a2 + kstep; const char* b3 = b2 + kstep;
;             if (last && has_next) S.a_ready(nxt);
;             if constexpr (SP2) {
;             PG8_LDB(B0, 0, 0); PG8_LDB(B1, 0, 1); PG8_SCHED; PG8_LDA(At, 0, 0); PG8_STAGE(PG8_SA(1, 1), a1 + hstepA, voffA);
;             PG8_WAIT_V(8); PG8_WAIT_L(0); PG8_BAR; PG8_MMA(0, 0, At, B0); PG8_MMA(0, 1, At, B1); PG8_BAR; PG8_SCHED;
;             PG8_LDA(At, 0, 1); PG8_STAGE(PG8_SB(0, 0), b2, voffB); PG8_STAGE(PG8_SB(0, 1), b2 + hstep, voffB); PG8_STAGE(PG8_SA(0, 0), a2, voffA);
;             PG8_WAIT_V(8); PG8_WAIT_L(0); PG8_BAR; PG8_MMA(1, 0, At, B0); PG8_MMA(1, 1, At, B1); PG8_BAR; PG8_SCHED;
.LBB0_368:
	ds_read_b128 v[154:157], v150
	ds_read_b128 v[158:161], v150 offset:1024
	ds_read_b128 v[162:165], v150 offset:2048
	ds_read_b128 v[166:169], v150 offset:3072
	ds_read_b128 v[170:173], v151
	ds_read_b128 v[174:177], v151 offset:1024
	ds_read_b128 v[178:181], v151 offset:2048
	ds_read_b128 v[182:185], v151 offset:3072
	s_add_i32 s64, s28, 2
	s_add_u32 s65, s26, 0xfffe0080
	s_addc_u32 s29, s27, -1
	s_cmp_eq_u32 s50, s28
	s_cselect_b32 s28, s30, s65
	s_cselect_b32 s29, s13, s29
	s_cselect_b32 s67, s21, s63
	s_cselect_b32 s66, s20, s62
	s_mov_b32 m0, s54
	ds_read_b128 v[190:193], v152
	ds_read_b128 v[194:197], v152 offset:1024
	ds_read_b128 v[198:201], v152 offset:2048
	ds_read_b128 v[202:205], v152 offset:3072
	ds_read_b128 v[206:209], v152 offset:4096
	ds_read_b128 v[210:213], v152 offset:5120
	ds_read_b128 v[214:217], v152 offset:6144
	global_load_lds_dwordx4 v138, s[26:27]
	s_mov_b32 m0, s55
	ds_read_b128 v[218:221], v152 offset:7168
	global_load_lds_dwordx4 v140, s[26:27]
	s_waitcnt vmcnt(8) lgkmcnt(0)
	s_setprio 1
	s_barrier
	v_mfma_f32_16x16x32_bf16 v[124:127], v[154:157], v[190:193], v[124:127]
	v_mfma_f32_16x16x32_bf16 v[120:123], v[162:165], v[190:193], v[120:123]
	v_mfma_f32_16x16x32_bf16 v[108:111], v[154:157], v[198:201], v[108:111]
	v_mfma_f32_16x16x32_bf16 v[104:107], v[162:165], v[198:201], v[104:107]
	v_mfma_f32_16x16x32_bf16 v[92:95], v[154:157], v[206:209], v[92:95]
	v_mfma_f32_16x16x32_bf16 v[88:91], v[162:165], v[206:209], v[88:91]
	v_mfma_f32_16x16x32_bf16 v[76:79], v[154:157], v[214:217], v[76:79]
	v_mfma_f32_16x16x32_bf16 v[72:75], v[162:165], v[214:217], v[72:75]
	v_mfma_f32_16x16x32_bf16 v[124:127], v[158:161], v[194:197], v[124:127]
	v_mfma_f32_16x16x32_bf16 v[120:123], v[166:169], v[194:197], v[120:123]
	v_mfma_f32_16x16x32_bf16 v[108:111], v[158:161], v[202:205], v[108:111]
	v_mfma_f32_16x16x32_bf16 v[104:107], v[166:169], v[202:205], v[104:107]
	v_mfma_f32_16x16x32_bf16 v[92:95], v[158:161], v[210:213], v[92:95]
	v_mfma_f32_16x16x32_bf16 v[88:91], v[166:169], v[210:213], v[88:91]
	v_mfma_f32_16x16x32_bf16 v[76:79], v[158:161], v[218:221], v[76:79]
	v_mfma_f32_16x16x32_bf16 v[72:75], v[166:169], v[218:221], v[72:75]
	v_mfma_f32_16x16x32_bf16 v[116:119], v[170:173], v[190:193], v[116:119]
	v_mfma_f32_16x16x32_bf16 v[112:115], v[178:181], v[190:193], v[112:115]
	v_mfma_f32_16x16x32_bf16 v[100:103], v[170:173], v[198:201], v[100:103]
	v_mfma_f32_16x16x32_bf16 v[96:99], v[178:181], v[198:201], v[96:99]
	v_mfma_f32_16x16x32_bf16 v[84:87], v[170:173], v[206:209], v[84:87]
	v_mfma_f32_16x16x32_bf16 v[80:83], v[178:181], v[206:209], v[80:83]
	v_mfma_f32_16x16x32_bf16 v[68:71], v[170:173], v[214:217], v[68:71]
	v_mfma_f32_16x16x32_bf16 v[64:67], v[178:181], v[214:217], v[64:67]
	v_mfma_f32_16x16x32_bf16 v[116:119], v[174:177], v[194:197], v[116:119]
	v_mfma_f32_16x16x32_bf16 v[112:115], v[182:185], v[194:197], v[112:115]
	v_mfma_f32_16x16x32_bf16 v[100:103], v[174:177], v[202:205], v[100:103]
	v_mfma_f32_16x16x32_bf16 v[96:99], v[182:185], v[202:205], v[96:99]
	v_mfma_f32_16x16x32_bf16 v[84:87], v[174:177], v[210:213], v[84:87]
	v_mfma_f32_16x16x32_bf16 v[80:83], v[182:185], v[210:213], v[80:83]
	v_mfma_f32_16x16x32_bf16 v[68:71], v[174:177], v[218:221], v[68:71]
	v_mfma_f32_16x16x32_bf16 v[64:67], v[182:185], v[218:221], v[64:67]
	s_setprio 0
	s_barrier
	s_mov_b32 m0, s56
	s_mov_b64 s[100:101], s[66:67]
	ds_read_b128 v[190:193], v152 offset:16384
	ds_read_b128 v[194:197], v152 offset:17408
	ds_read_b128 v[198:201], v152 offset:18432
	global_load_lds_dwordx4 v134, s[66:67]
	s_mov_b32 m0, s57
	ds_read_b128 v[218:221], v152 offset:23552
	global_load_lds_dwordx4 v132, s[66:67]
	s_mov_b32 m0, s58
	s_add_u32 s66, s66, s4
	s_addc_u32 s67, s67, s5
	global_load_lds_dwordx4 v134, s[66:67]
	s_mov_b32 m0, s59
	ds_read_b128 v[210:213], v152 offset:21504
	global_load_lds_dwordx4 v132, s[66:67]
	s_mov_b32 m0, s38
	ds_read_b128 v[206:209], v152 offset:20480
	global_load_lds_dwordx4 v130, s[28:29]
	s_mov_b32 m0, s39
	ds_read_b128 v[202:205], v152 offset:19456
	global_load_lds_dwordx4 v128, s[28:29]
	ds_read_b128 v[214:217], v152 offset:22528
	s_waitcnt vmcnt(8) lgkmcnt(0)
	s_setprio 1
	s_barrier
	v_mfma_f32_16x16x32_bf16 v[60:63], v[154:157], v[190:193], v[60:63]
	v_mfma_f32_16x16x32_bf16 v[56:59], v[162:165], v[190:193], v[56:59]
	v_mfma_f32_16x16x32_bf16 v[44:47], v[154:157], v[198:201], v[44:47]
	v_mfma_f32_16x16x32_bf16 v[40:43], v[162:165], v[198:201], v[40:43]
	v_mfma_f32_16x16x32_bf16 v[28:31], v[154:157], v[206:209], v[28:31]
	v_mfma_f32_16x16x32_bf16 v[24:27], v[162:165], v[206:209], v[24:27]
	v_mfma_f32_16x16x32_bf16 v[12:15], v[154:157], v[214:217], v[12:15]
	v_mfma_f32_16x16x32_bf16 v[8:11], v[162:165], v[214:217], v[8:11]
	v_mfma_f32_16x16x32_bf16 v[60:63], v[158:161], v[194:197], v[60:63]
	v_mfma_f32_16x16x32_bf16 v[56:59], v[166:169], v[194:197], v[56:59]
	v_mfma_f32_16x16x32_bf16 v[44:47], v[158:161], v[202:205], v[44:47]
	v_mfma_f32_16x16x32_bf16 v[40:43], v[166:169], v[202:205], v[40:43]
	v_mfma_f32_16x16x32_bf16 v[28:31], v[158:161], v[210:213], v[28:31]
	v_mfma_f32_16x16x32_bf16 v[24:27], v[166:169], v[210:213], v[24:27]
	v_mfma_f32_16x16x32_bf16 v[12:15], v[158:161], v[218:221], v[12:15]
	v_mfma_f32_16x16x32_bf16 v[8:11], v[166:169], v[218:221], v[8:11]
	v_mfma_f32_16x16x32_bf16 v[52:55], v[170:173], v[190:193], v[52:55]
	v_mfma_f32_16x16x32_bf16 v[48:51], v[178:181], v[190:193], v[48:51]
	v_mfma_f32_16x16x32_bf16 v[36:39], v[170:173], v[198:201], v[36:39]
	v_mfma_f32_16x16x32_bf16 v[32:35], v[178:181], v[198:201], v[32:35]
	v_mfma_f32_16x16x32_bf16 v[20:23], v[170:173], v[206:209], v[20:23]
	v_mfma_f32_16x16x32_bf16 v[16:19], v[178:181], v[206:209], v[16:19]
	v_mfma_f32_16x16x32_bf16 v[4:7], v[170:173], v[214:217], v[4:7]
	v_mfma_f32_16x16x32_bf16 v[0:3], v[178:181], v[214:217], v[0:3]
	v_mfma_f32_16x16x32_bf16 v[52:55], v[174:177], v[194:197], v[52:55]
	v_mfma_f32_16x16x32_bf16 v[48:51], v[182:185], v[194:197], v[48:51]
	v_mfma_f32_16x16x32_bf16 v[36:39], v[174:177], v[202:205], v[36:39]
	v_mfma_f32_16x16x32_bf16 v[32:35], v[182:185], v[202:205], v[32:35]
	v_mfma_f32_16x16x32_bf16 v[20:23], v[174:177], v[210:213], v[20:23]
	v_mfma_f32_16x16x32_bf16 v[16:19], v[182:185], v[210:213], v[16:19]
	v_mfma_f32_16x16x32_bf16 v[4:7], v[174:177], v[218:221], v[4:7]
	v_mfma_f32_16x16x32_bf16 v[0:3], v[182:185], v[218:221], v[0:3]
	s_setprio 0
	s_barrier
; #define PG8_STAGE(bufoff, gbase, voff) do { _Pragma("unroll") for (int _i = 0; _i < 2; ++_i) \
;         __builtin_amdgcn_global_load_lds((const unsigned*)((const char*)(gbase) + (voff)[_i]), (PG8_LAS unsigned*)(lds + (bufoff) + ldsw + _i * 8192), 16, 0, 0); } while (0)
; #define PG8_LDA(dst, b, h) do { _Pragma("unroll") for (int m = 0; m < 4; ++m) _Pragma("unroll") for (int k = 0; k < 2; ++k) dst[m][k] = *(const PG8_LAS bf16x8*)(lds + PG8_SA(b, h) + aoff + m * 2048 + k * 1024); } while (0)
; #define PG8_LDB(dst, b, h) do { _Pragma("unroll") for (int n = 0; n < 2; ++n) _Pragma("unroll") for (int k = 0; k < 2; ++k) dst[n][k] = *(const PG8_LAS bf16x8*)(lds + PG8_SB(b, h) + boff + n * 2048 + k * 1024); } while (0)
; #define PG8_MMA(ai, bj, At, Bt) do { __builtin_amdgcn_s_setprio(1); _Pragma("unroll") for (int m = 0; m < 4; ++m) _Pragma("unroll") for (int n = 0; n < 2; ++n) _Pragma("unroll") for (int k = 0; k < 2; ++k) \
;         acc[ai][bj][m][n] = __builtin_amdgcn_mfma_f32_16x16x32_bf16(Bt[n][k], At[m][k], acc[ai][bj][m][n], 0, 0, 0); __builtin_amdgcn_s_setprio(0); } while (0)
; #define PG8_WAIT_V(n) asm volatile("s_waitcnt vmcnt(" #n ")" ::: "memory")
; #define PG8_WAIT_L(n) asm volatile("s_waitcnt lgkmcnt(" #n ")" ::: "memory")
; #define PG8_BAR __builtin_amdgcn_s_barrier()
; #define PG8_SCHED __builtin_amdgcn_sched_barrier(0)
; template <class Epi, class Sched, bool ALIGN_EPI = false, bool SP2 = false>
; __device__ __forceinline__ void gemm_phase(PG8_LAS unsigned char* lds, const Gemm g, const Sched& S, const Epi& E) {
;     ...
;         for (int t = 0; t < nt; t += 2) {
;     ...
;             PG8_LDB(B0, 1, 0); PG8_LDB(B1, 1, 1); PG8_SCHED; PG8_LDA(At, 1, 0); PG8_STAGE(PG8_SA(0, 1), a2 + hstepA, voffA);
;             PG8_WAIT_V(8); PG8_WAIT_L(0); PG8_BAR; PG8_MMA(0, 0, At, B0); PG8_MMA(0, 1, At, B1); PG8_BAR; PG8_SCHED;
;             PG8_LDA(At, 1, 1); PG8_STAGE(PG8_SB(1, 0), b3, voffB); PG8_STAGE(PG8_SB(1, 1), b3 + hstep, voffB); PG8_STAGE(PG8_SA(1, 0), a3, voffA);
;             PG8_WAIT_V(8); PG8_WAIT_L(0); PG8_BAR; PG8_MMA(1, 0, At, B0); PG8_MMA(1, 1, At, B1); PG8_BAR; PG8_SCHED;
	s_add_i32 s65, 0, 0x18000
	s_add_i32 s66, 0, 0x1c000
	v_add_u32_e32 v166, s65, v149
	v_add_u32_e32 v182, s66, v149
	ds_read_b128 v[154:157], v166
	ds_read_b128 v[158:161], v166 offset:1024
	ds_read_b128 v[162:165], v166 offset:2048
	ds_read_b128 v[166:169], v166 offset:3072
	ds_read_b128 v[170:173], v182
	ds_read_b128 v[174:177], v182 offset:1024
	ds_read_b128 v[178:181], v182 offset:2048
	ds_read_b128 v[182:185], v182 offset:3072
	s_mov_b64 vcc, s[28:29]
	s_add_u32 s28, s28, 0x20000
	s_addc_u32 s29, s29, 0
	s_mov_b32 m0, s40
	ds_read_b128 v[190:193], v152 offset:32768
	ds_read_b128 v[194:197], v152 offset:33792
	ds_read_b128 v[198:201], v152 offset:34816
	ds_read_b128 v[202:205], v152 offset:35840
	ds_read_b128 v[206:209], v152 offset:36864
	ds_read_b128 v[210:213], v152 offset:37888
	ds_read_b128 v[214:217], v152 offset:38912
	global_load_lds_dwordx4 v130, s[28:29]
	s_mov_b32 m0, s41
	ds_read_b128 v[218:221], v152 offset:39936
	global_load_lds_dwordx4 v128, s[28:29]
	s_waitcnt vmcnt(8) lgkmcnt(0)
	s_setprio 1
	s_barrier
	v_mfma_f32_16x16x32_bf16 v[124:127], v[154:157], v[190:193], v[124:127]
	v_mfma_f32_16x16x32_bf16 v[120:123], v[162:165], v[190:193], v[120:123]
	v_mfma_f32_16x16x32_bf16 v[108:111], v[154:157], v[198:201], v[108:111]
	v_mfma_f32_16x16x32_bf16 v[104:107], v[162:165], v[198:201], v[104:107]
	v_mfma_f32_16x16x32_bf16 v[92:95], v[154:157], v[206:209], v[92:95]
	v_mfma_f32_16x16x32_bf16 v[88:91], v[162:165], v[206:209], v[88:91]
	v_mfma_f32_16x16x32_bf16 v[76:79], v[154:157], v[214:217], v[76:79]
	v_mfma_f32_16x16x32_bf16 v[72:75], v[162:165], v[214:217], v[72:75]
	v_mfma_f32_16x16x32_bf16 v[124:127], v[158:161], v[194:197], v[124:127]
	v_mfma_f32_16x16x32_bf16 v[120:123], v[166:169], v[194:197], v[120:123]
	v_mfma_f32_16x16x32_bf16 v[108:111], v[158:161], v[202:205], v[108:111]
	v_mfma_f32_16x16x32_bf16 v[104:107], v[166:169], v[202:205], v[104:107]
	v_mfma_f32_16x16x32_bf16 v[92:95], v[158:161], v[210:213], v[92:95]
	v_mfma_f32_16x16x32_bf16 v[88:91], v[166:169], v[210:213], v[88:91]
	v_mfma_f32_16x16x32_bf16 v[76:79], v[158:161], v[218:221], v[76:79]
	v_mfma_f32_16x16x32_bf16 v[72:75], v[166:169], v[218:221], v[72:75]
	v_mfma_f32_16x16x32_bf16 v[116:119], v[170:173], v[190:193], v[116:119]
	v_mfma_f32_16x16x32_bf16 v[112:115], v[178:181], v[190:193], v[112:115]
	v_mfma_f32_16x16x32_bf16 v[100:103], v[170:173], v[198:201], v[100:103]
	v_mfma_f32_16x16x32_bf16 v[96:99], v[178:181], v[198:201], v[96:99]
	v_mfma_f32_16x16x32_bf16 v[84:87], v[170:173], v[206:209], v[84:87]
	v_mfma_f32_16x16x32_bf16 v[80:83], v[178:181], v[206:209], v[80:83]
	v_mfma_f32_16x16x32_bf16 v[68:71], v[170:173], v[214:217], v[68:71]
	v_mfma_f32_16x16x32_bf16 v[64:67], v[178:181], v[214:217], v[64:67]
	v_mfma_f32_16x16x32_bf16 v[116:119], v[174:177], v[194:197], v[116:119]
	v_mfma_f32_16x16x32_bf16 v[112:115], v[182:185], v[194:197], v[112:115]
	v_mfma_f32_16x16x32_bf16 v[100:103], v[174:177], v[202:205], v[100:103]
	v_mfma_f32_16x16x32_bf16 v[96:99], v[182:185], v[202:205], v[96:99]
	v_mfma_f32_16x16x32_bf16 v[84:87], v[174:177], v[210:213], v[84:87]
	v_mfma_f32_16x16x32_bf16 v[80:83], v[182:185], v[210:213], v[80:83]
	v_mfma_f32_16x16x32_bf16 v[68:71], v[174:177], v[218:221], v[68:71]
	v_mfma_f32_16x16x32_bf16 v[64:67], v[182:185], v[218:221], v[64:67]
	s_setprio 0
	s_barrier
	s_add_i32 s28, s65, s37
	s_add_i32 m0, s28, 0xffffff80
	ds_read_b128 v[190:193], v152 offset:49152
	ds_read_b128 v[194:197], v152 offset:50176
	ds_read_b128 v[198:201], v152 offset:51200
	ds_read_b128 v[202:205], v152 offset:52224
	global_load_lds_dwordx4 v134, s[100:101] offset:128
	s_add_i32 m0, s28, 0x1f80
	s_add_i32 s28, s66, s37
	global_load_lds_dwordx4 v132, s[100:101] offset:128
	s_add_i32 m0, s28, 0xffffff80
	s_add_u32 s100, s100, s4
	s_addc_u32 s101, s101, s5
	global_load_lds_dwordx4 v134, s[100:101] offset:128
	s_add_i32 m0, s28, 0x1f80
	ds_read_b128 v[214:217], v152 offset:55296
	global_load_lds_dwordx4 v132, s[100:101] offset:128
	s_add_i32 m0, s43, 0xffffff80
	ds_read_b128 v[210:213], v152 offset:54272
	global_load_lds_dwordx4 v130, vcc offset:128
	s_add_i32 m0, s44, 0xffffff80
	ds_read_b128 v[206:209], v152 offset:53248
	global_load_lds_dwordx4 v128, vcc offset:128
	ds_read_b128 v[218:221], v152 offset:56320
	s_waitcnt vmcnt(8) lgkmcnt(0)
	s_setprio 1
	s_barrier
	v_mfma_f32_16x16x32_bf16 v[60:63], v[154:157], v[190:193], v[60:63]
	v_mfma_f32_16x16x32_bf16 v[56:59], v[162:165], v[190:193], v[56:59]
	v_mfma_f32_16x16x32_bf16 v[44:47], v[154:157], v[198:201], v[44:47]
	v_mfma_f32_16x16x32_bf16 v[40:43], v[162:165], v[198:201], v[40:43]
	v_mfma_f32_16x16x32_bf16 v[28:31], v[154:157], v[206:209], v[28:31]
	v_mfma_f32_16x16x32_bf16 v[24:27], v[162:165], v[206:209], v[24:27]
	v_mfma_f32_16x16x32_bf16 v[12:15], v[154:157], v[214:217], v[12:15]
	v_mfma_f32_16x16x32_bf16 v[8:11], v[162:165], v[214:217], v[8:11]
	v_mfma_f32_16x16x32_bf16 v[60:63], v[158:161], v[194:197], v[60:63]
	v_mfma_f32_16x16x32_bf16 v[56:59], v[166:169], v[194:197], v[56:59]
	v_mfma_f32_16x16x32_bf16 v[44:47], v[158:161], v[202:205], v[44:47]
	v_mfma_f32_16x16x32_bf16 v[40:43], v[166:169], v[202:205], v[40:43]
	v_mfma_f32_16x16x32_bf16 v[28:31], v[158:161], v[210:213], v[28:31]
	v_mfma_f32_16x16x32_bf16 v[24:27], v[166:169], v[210:213], v[24:27]
	v_mfma_f32_16x16x32_bf16 v[12:15], v[158:161], v[218:221], v[12:15]
	v_mfma_f32_16x16x32_bf16 v[8:11], v[166:169], v[218:221], v[8:11]
	v_mfma_f32_16x16x32_bf16 v[52:55], v[170:173], v[190:193], v[52:55]
	v_mfma_f32_16x16x32_bf16 v[48:51], v[178:181], v[190:193], v[48:51]
	v_mfma_f32_16x16x32_bf16 v[36:39], v[170:173], v[198:201], v[36:39]
	v_mfma_f32_16x16x32_bf16 v[32:35], v[178:181], v[198:201], v[32:35]
	v_mfma_f32_16x16x32_bf16 v[20:23], v[170:173], v[206:209], v[20:23]
	v_mfma_f32_16x16x32_bf16 v[16:19], v[178:181], v[206:209], v[16:19]
	v_mfma_f32_16x16x32_bf16 v[4:7], v[170:173], v[214:217], v[4:7]
	v_mfma_f32_16x16x32_bf16 v[0:3], v[178:181], v[214:217], v[0:3]
	v_mfma_f32_16x16x32_bf16 v[52:55], v[174:177], v[194:197], v[52:55]
	v_mfma_f32_16x16x32_bf16 v[48:51], v[182:185], v[194:197], v[48:51]
	v_mfma_f32_16x16x32_bf16 v[36:39], v[174:177], v[202:205], v[36:39]
	v_mfma_f32_16x16x32_bf16 v[32:35], v[182:185], v[202:205], v[32:35]
	v_mfma_f32_16x16x32_bf16 v[20:23], v[174:177], v[210:213], v[20:23]
	v_mfma_f32_16x16x32_bf16 v[16:19], v[182:185], v[210:213], v[16:19]
	v_mfma_f32_16x16x32_bf16 v[4:7], v[174:177], v[218:221], v[4:7]
	v_mfma_f32_16x16x32_bf16 v[0:3], v[182:185], v[218:221], v[0:3]
	s_setprio 0
	s_barrier
	s_add_u32 s26, s26, 0x100
	s_addc_u32 s27, s27, 0
	s_add_u32 s62, s62, 0x100
	s_addc_u32 s63, s63, 0
	s_cmp_ge_i32 s64, s48
	s_mov_b32 s28, s64
	s_cbranch_scc0 .LBB0_368

; #define PG8_STAGE(bufoff, gbase, voff) do { _Pragma("unroll") for (int _i = 0; _i < 2; ++_i) \
;         __builtin_amdgcn_global_load_lds((const unsigned*)((const char*)(gbase) + (voff)[_i]), (PG8_LAS unsigned*)(lds + (bufoff) + ldsw + _i * 8192), 16, 0, 0); } while (0)
; #define PG8_LDA(dst, b, h) do { _Pragma("unroll") for (int m = 0; m < 4; ++m) _Pragma("unroll") for (int k = 0; k < 2; ++k) dst[m][k] = *(const PG8_LAS bf16x8*)(lds + PG8_SA(b, h) + aoff + m * 2048 + k * 1024); } while (0)
; #define PG8_LDB(dst, b, h) do { _Pragma("unroll") for (int n = 0; n < 2; ++n) _Pragma("unroll") for (int k = 0; k < 2; ++k) dst[n][k] = *(const PG8_LAS bf16x8*)(lds + PG8_SB(b, h) + boff + n * 2048 + k * 1024); } while (0)
; #define PG8_MMA(ai, bj, At, Bt) do { __builtin_amdgcn_s_setprio(1); _Pragma("unroll") for (int m = 0; m < 4; ++m) _Pragma("unroll") for (int n = 0; n < 2; ++n) _Pragma("unroll") for (int k = 0; k < 2; ++k) \
;         acc[ai][bj][m][n] = __builtin_amdgcn_mfma_f32_16x16x32_bf16(Bt[n][k], At[m][k], acc[ai][bj][m][n], 0, 0, 0); __builtin_amdgcn_s_setprio(0); } while (0)
; #define PG8_WAIT_V(n) asm volatile("s_waitcnt vmcnt(" #n ")" ::: "memory")
; #define PG8_WAIT_L(n) asm volatile("s_waitcnt lgkmcnt(" #n ")" ::: "memory")
; template <class Epi, class Sched, bool ALIGN_EPI = false, bool SP2 = false>
; __device__ __forceinline__ void gemm_phase(PG8_LAS unsigned char* lds, const Gemm g, const Sched& S, const Epi& E) {
;     ...
;             const bool last = (t == nt - 2);
;             const char* a1 = cA + (size_t)(t + 1) * kstep;
;             const char* a2 = last ? nA : cA + (size_t)(t + 2) * kstep; const char* b2 = last ? nB : cB + (size_t)(t + 2) * kstep;
;             const char* a3 = a2 + kstep; const char* b3 = b2 + kstep;
;             if (last && has_next) S.a_ready(nxt);
;             if constexpr (SP2) {
;             PG8_LDB(B0, 0, 0); PG8_LDB(B1, 0, 1); PG8_SCHED; PG8_LDA(At, 0, 0); PG8_STAGE(PG8_SA(1, 1), a1 + hstepA, voffA);
;             PG8_WAIT_V(8); PG8_WAIT_L(0); PG8_BAR; PG8_MMA(0, 0, At, B0); PG8_MMA(0, 1, At, B1); PG8_BAR; PG8_SCHED;
;             PG8_LDA(At, 0, 1); PG8_STAGE(PG8_SB(0, 0), b2, voffB); PG8_STAGE(PG8_SB(0, 1), b2 + hstep, voffB); PG8_STAGE(PG8_SA(0, 0), a2, voffA);
;             PG8_WAIT_V(8); PG8_WAIT_L(0); PG8_BAR; PG8_MMA(1, 0, At, B0); PG8_MMA(1, 1, At, B1); PG8_BAR; PG8_SCHED;
.LBB0_523:
	ds_read_b128 v[154:157], v149
	ds_read_b128 v[158:161], v149 offset:1024
	ds_read_b128 v[162:165], v149 offset:2048
	ds_read_b128 v[166:169], v149 offset:3072
	ds_read_b128 v[170:173], v150
	ds_read_b128 v[174:177], v150 offset:1024
	ds_read_b128 v[178:181], v150 offset:2048
	ds_read_b128 v[182:185], v150 offset:3072
	s_add_i32 s61, s30, 2
	s_add_u32 s62, s4, 0xfffe0080
	s_addc_u32 s31, s5, -1
	s_cmp_eq_u32 s52, s30
	s_cselect_b32 s30, s34, s62
	s_cselect_b32 s31, s15, s31
	s_cselect_b32 s63, s25, s60
	s_cselect_b32 s62, s24, s59
	s_add_i32 m0, s41, 0xc000
	ds_read_b128 v[190:193], v151
	ds_read_b128 v[194:197], v151 offset:1024
	ds_read_b128 v[198:201], v151 offset:2048
	ds_read_b128 v[202:205], v151 offset:3072
	ds_read_b128 v[206:209], v151 offset:4096
	ds_read_b128 v[210:213], v151 offset:5120
	ds_read_b128 v[214:217], v151 offset:6144
	global_load_lds_dwordx4 v138, s[4:5]
	s_add_i32 m0, s41, 0xe000
	ds_read_b128 v[218:221], v151 offset:7168
	global_load_lds_dwordx4 v140, s[4:5]
	s_waitcnt vmcnt(8) lgkmcnt(0)
	s_setprio 1
	s_barrier
	v_mfma_f32_16x16x32_bf16 v[124:127], v[154:157], v[190:193], v[124:127]
	v_mfma_f32_16x16x32_bf16 v[120:123], v[162:165], v[190:193], v[120:123]
	v_mfma_f32_16x16x32_bf16 v[108:111], v[154:157], v[198:201], v[108:111]
	v_mfma_f32_16x16x32_bf16 v[104:107], v[162:165], v[198:201], v[104:107]
	v_mfma_f32_16x16x32_bf16 v[92:95], v[154:157], v[206:209], v[92:95]
	v_mfma_f32_16x16x32_bf16 v[88:91], v[162:165], v[206:209], v[88:91]
	v_mfma_f32_16x16x32_bf16 v[76:79], v[154:157], v[214:217], v[76:79]
	v_mfma_f32_16x16x32_bf16 v[72:75], v[162:165], v[214:217], v[72:75]
	v_mfma_f32_16x16x32_bf16 v[124:127], v[158:161], v[194:197], v[124:127]
	v_mfma_f32_16x16x32_bf16 v[120:123], v[166:169], v[194:197], v[120:123]
	v_mfma_f32_16x16x32_bf16 v[108:111], v[158:161], v[202:205], v[108:111]
	v_mfma_f32_16x16x32_bf16 v[104:107], v[166:169], v[202:205], v[104:107]
	v_mfma_f32_16x16x32_bf16 v[92:95], v[158:161], v[210:213], v[92:95]
	v_mfma_f32_16x16x32_bf16 v[88:91], v[166:169], v[210:213], v[88:91]
	v_mfma_f32_16x16x32_bf16 v[76:79], v[158:161], v[218:221], v[76:79]
	v_mfma_f32_16x16x32_bf16 v[72:75], v[166:169], v[218:221], v[72:75]
	v_mfma_f32_16x16x32_bf16 v[116:119], v[170:173], v[190:193], v[116:119]
	v_mfma_f32_16x16x32_bf16 v[112:115], v[178:181], v[190:193], v[112:115]
	v_mfma_f32_16x16x32_bf16 v[100:103], v[170:173], v[198:201], v[100:103]
	v_mfma_f32_16x16x32_bf16 v[96:99], v[178:181], v[198:201], v[96:99]
	v_mfma_f32_16x16x32_bf16 v[84:87], v[170:173], v[206:209], v[84:87]
	v_mfma_f32_16x16x32_bf16 v[80:83], v[178:181], v[206:209], v[80:83]
	v_mfma_f32_16x16x32_bf16 v[68:71], v[170:173], v[214:217], v[68:71]
	v_mfma_f32_16x16x32_bf16 v[64:67], v[178:181], v[214:217], v[64:67]
	v_mfma_f32_16x16x32_bf16 v[116:119], v[174:177], v[194:197], v[116:119]
	v_mfma_f32_16x16x32_bf16 v[112:115], v[182:185], v[194:197], v[112:115]
	v_mfma_f32_16x16x32_bf16 v[100:103], v[174:177], v[202:205], v[100:103]
	v_mfma_f32_16x16x32_bf16 v[96:99], v[182:185], v[202:205], v[96:99]
	v_mfma_f32_16x16x32_bf16 v[84:87], v[174:177], v[210:213], v[84:87]
	v_mfma_f32_16x16x32_bf16 v[80:83], v[182:185], v[210:213], v[80:83]
	v_mfma_f32_16x16x32_bf16 v[68:71], v[174:177], v[218:221], v[68:71]
	v_mfma_f32_16x16x32_bf16 v[64:67], v[182:185], v[218:221], v[64:67]
	s_setprio 0
	s_barrier
	s_add_i32 s64, s54, s40
	s_mov_b32 m0, s64
	ds_read_b128 v[190:193], v151 offset:16384
	ds_read_b128 v[194:197], v151 offset:17408
	ds_read_b128 v[198:201], v151 offset:18432
	ds_read_b128 v[202:205], v151 offset:19456
	global_load_lds_dwordx4 v134, s[62:63]
	s_add_i32 m0, s64, 0x2000
	s_mov_b64 s[100:101], s[62:63]
	s_add_i32 s64, s55, s40
	global_load_lds_dwordx4 v132, s[62:63]
	s_mov_b32 m0, s64
	s_add_u32 s62, s62, s10
	s_addc_u32 s63, s63, s11
	global_load_lds_dwordx4 v134, s[62:63]
	s_add_i32 m0, s64, 0x2000
	ds_read_b128 v[214:217], v151 offset:22528
	global_load_lds_dwordx4 v132, s[62:63]
	s_mov_b32 m0, s41
	ds_read_b128 v[210:213], v151 offset:21504
	global_load_lds_dwordx4 v130, s[30:31]
	s_mov_b32 m0, s42
	ds_read_b128 v[206:209], v151 offset:20480
	global_load_lds_dwordx4 v128, s[30:31]
	ds_read_b128 v[218:221], v151 offset:23552
	s_waitcnt vmcnt(8) lgkmcnt(0)
	s_setprio 1
	s_barrier
	v_mfma_f32_16x16x32_bf16 v[60:63], v[154:157], v[190:193], v[60:63]
	v_mfma_f32_16x16x32_bf16 v[56:59], v[162:165], v[190:193], v[56:59]
	v_mfma_f32_16x16x32_bf16 v[44:47], v[154:157], v[198:201], v[44:47]
	v_mfma_f32_16x16x32_bf16 v[40:43], v[162:165], v[198:201], v[40:43]
	v_mfma_f32_16x16x32_bf16 v[28:31], v[154:157], v[206:209], v[28:31]
	v_mfma_f32_16x16x32_bf16 v[24:27], v[162:165], v[206:209], v[24:27]
	v_mfma_f32_16x16x32_bf16 v[12:15], v[154:157], v[214:217], v[12:15]
	v_mfma_f32_16x16x32_bf16 v[8:11], v[162:165], v[214:217], v[8:11]
	v_mfma_f32_16x16x32_bf16 v[60:63], v[158:161], v[194:197], v[60:63]
	v_mfma_f32_16x16x32_bf16 v[56:59], v[166:169], v[194:197], v[56:59]
	v_mfma_f32_16x16x32_bf16 v[44:47], v[158:161], v[202:205], v[44:47]
	v_mfma_f32_16x16x32_bf16 v[40:43], v[166:169], v[202:205], v[40:43]
	v_mfma_f32_16x16x32_bf16 v[28:31], v[158:161], v[210:213], v[28:31]
	v_mfma_f32_16x16x32_bf16 v[24:27], v[166:169], v[210:213], v[24:27]
	v_mfma_f32_16x16x32_bf16 v[12:15], v[158:161], v[218:221], v[12:15]
	v_mfma_f32_16x16x32_bf16 v[8:11], v[166:169], v[218:221], v[8:11]
	v_mfma_f32_16x16x32_bf16 v[52:55], v[170:173], v[190:193], v[52:55]
	v_mfma_f32_16x16x32_bf16 v[48:51], v[178:181], v[190:193], v[48:51]
	v_mfma_f32_16x16x32_bf16 v[36:39], v[170:173], v[198:201], v[36:39]
	v_mfma_f32_16x16x32_bf16 v[32:35], v[178:181], v[198:201], v[32:35]
	v_mfma_f32_16x16x32_bf16 v[20:23], v[170:173], v[206:209], v[20:23]
	v_mfma_f32_16x16x32_bf16 v[16:19], v[178:181], v[206:209], v[16:19]
	v_mfma_f32_16x16x32_bf16 v[4:7], v[170:173], v[214:217], v[4:7]
	v_mfma_f32_16x16x32_bf16 v[0:3], v[178:181], v[214:217], v[0:3]
	v_mfma_f32_16x16x32_bf16 v[52:55], v[174:177], v[194:197], v[52:55]
	v_mfma_f32_16x16x32_bf16 v[48:51], v[182:185], v[194:197], v[48:51]
	v_mfma_f32_16x16x32_bf16 v[36:39], v[174:177], v[202:205], v[36:39]
	v_mfma_f32_16x16x32_bf16 v[32:35], v[182:185], v[202:205], v[32:35]
	v_mfma_f32_16x16x32_bf16 v[20:23], v[174:177], v[210:213], v[20:23]
	v_mfma_f32_16x16x32_bf16 v[16:19], v[182:185], v[210:213], v[16:19]
	v_mfma_f32_16x16x32_bf16 v[4:7], v[174:177], v[218:221], v[4:7]
	v_mfma_f32_16x16x32_bf16 v[0:3], v[182:185], v[218:221], v[0:3]
	s_setprio 0
	s_barrier
; #define PG8_STAGE(bufoff, gbase, voff) do { _Pragma("unroll") for (int _i = 0; _i < 2; ++_i) \
;         __builtin_amdgcn_global_load_lds((const unsigned*)((const char*)(gbase) + (voff)[_i]), (PG8_LAS unsigned*)(lds + (bufoff) + ldsw + _i * 8192), 16, 0, 0); } while (0)
; #define PG8_LDA(dst, b, h) do { _Pragma("unroll") for (int m = 0; m < 4; ++m) _Pragma("unroll") for (int k = 0; k < 2; ++k) dst[m][k] = *(const PG8_LAS bf16x8*)(lds + PG8_SA(b, h) + aoff + m * 2048 + k * 1024); } while (0)
; #define PG8_LDB(dst, b, h) do { _Pragma("unroll") for (int n = 0; n < 2; ++n) _Pragma("unroll") for (int k = 0; k < 2; ++k) dst[n][k] = *(const PG8_LAS bf16x8*)(lds + PG8_SB(b, h) + boff + n * 2048 + k * 1024); } while (0)
; #define PG8_MMA(ai, bj, At, Bt) do { __builtin_amdgcn_s_setprio(1); _Pragma("unroll") for (int m = 0; m < 4; ++m) _Pragma("unroll") for (int n = 0; n < 2; ++n) _Pragma("unroll") for (int k = 0; k < 2; ++k) \
;         acc[ai][bj][m][n] = __builtin_amdgcn_mfma_f32_16x16x32_bf16(Bt[n][k], At[m][k], acc[ai][bj][m][n], 0, 0, 0); __builtin_amdgcn_s_setprio(0); } while (0)
; #define PG8_WAIT_V(n) asm volatile("s_waitcnt vmcnt(" #n ")" ::: "memory")
; #define PG8_WAIT_L(n) asm volatile("s_waitcnt lgkmcnt(" #n ")" ::: "memory")
; #define PG8_BAR __builtin_amdgcn_s_barrier()
; #define PG8_SCHED __builtin_amdgcn_sched_barrier(0)
; template <class Epi, class Sched, bool ALIGN_EPI = false, bool SP2 = false>
; __device__ __forceinline__ void gemm_phase(PG8_LAS unsigned char* lds, const Gemm g, const Sched& S, const Epi& E) {
;     ...
;         for (int t = 0; t < nt; t += 2) {
;     ...
;             PG8_LDB(B0, 1, 0); PG8_LDB(B1, 1, 1); PG8_SCHED; PG8_LDA(At, 1, 0); PG8_STAGE(PG8_SA(0, 1), a2 + hstepA, voffA);
;             PG8_WAIT_V(8); PG8_WAIT_L(0); PG8_BAR; PG8_MMA(0, 0, At, B0); PG8_MMA(0, 1, At, B1); PG8_BAR; PG8_SCHED;
;             PG8_LDA(At, 1, 1); PG8_STAGE(PG8_SB(1, 0), b3, voffB); PG8_STAGE(PG8_SB(1, 1), b3 + hstep, voffB); PG8_STAGE(PG8_SA(1, 0), a3, voffA);
;             PG8_WAIT_V(8); PG8_WAIT_L(0); PG8_BAR; PG8_MMA(1, 0, At, B0); PG8_MMA(1, 1, At, B1); PG8_BAR; PG8_SCHED;
	s_add_i32 s62, 0, 0x18000
	s_add_i32 s63, 0, 0x1c000
	v_add_u32_e32 v166, s62, v147
	v_add_u32_e32 v182, s63, v147
	ds_read_b128 v[154:157], v166
	ds_read_b128 v[158:161], v166 offset:1024
	ds_read_b128 v[162:165], v166 offset:2048
	ds_read_b128 v[166:169], v166 offset:3072
	ds_read_b128 v[170:173], v182
	ds_read_b128 v[174:177], v182 offset:1024
	ds_read_b128 v[178:181], v182 offset:2048
	ds_read_b128 v[182:185], v182 offset:3072
	s_mov_b64 vcc, s[30:31]
	s_add_u32 s30, s30, 0x20000
	s_addc_u32 s31, s31, 0
	s_mov_b32 m0, s43
	ds_read_b128 v[190:193], v151 offset:32768
	ds_read_b128 v[194:197], v151 offset:33792
	ds_read_b128 v[198:201], v151 offset:34816
	ds_read_b128 v[202:205], v151 offset:35840
	ds_read_b128 v[206:209], v151 offset:36864
	ds_read_b128 v[210:213], v151 offset:37888
	ds_read_b128 v[214:217], v151 offset:38912
	global_load_lds_dwordx4 v130, s[30:31]
	s_mov_b32 m0, s44
	ds_read_b128 v[218:221], v151 offset:39936
	global_load_lds_dwordx4 v128, s[30:31]
	s_waitcnt vmcnt(8) lgkmcnt(0)
	s_setprio 1
	s_barrier
	v_mfma_f32_16x16x32_bf16 v[124:127], v[154:157], v[190:193], v[124:127]
	v_mfma_f32_16x16x32_bf16 v[120:123], v[162:165], v[190:193], v[120:123]
	v_mfma_f32_16x16x32_bf16 v[108:111], v[154:157], v[198:201], v[108:111]
	v_mfma_f32_16x16x32_bf16 v[104:107], v[162:165], v[198:201], v[104:107]
	v_mfma_f32_16x16x32_bf16 v[92:95], v[154:157], v[206:209], v[92:95]
	v_mfma_f32_16x16x32_bf16 v[88:91], v[162:165], v[206:209], v[88:91]
	v_mfma_f32_16x16x32_bf16 v[76:79], v[154:157], v[214:217], v[76:79]
	v_mfma_f32_16x16x32_bf16 v[72:75], v[162:165], v[214:217], v[72:75]
	v_mfma_f32_16x16x32_bf16 v[124:127], v[158:161], v[194:197], v[124:127]
	v_mfma_f32_16x16x32_bf16 v[120:123], v[166:169], v[194:197], v[120:123]
	v_mfma_f32_16x16x32_bf16 v[108:111], v[158:161], v[202:205], v[108:111]
	v_mfma_f32_16x16x32_bf16 v[104:107], v[166:169], v[202:205], v[104:107]
	v_mfma_f32_16x16x32_bf16 v[92:95], v[158:161], v[210:213], v[92:95]
	v_mfma_f32_16x16x32_bf16 v[88:91], v[166:169], v[210:213], v[88:91]
	v_mfma_f32_16x16x32_bf16 v[76:79], v[158:161], v[218:221], v[76:79]
	v_mfma_f32_16x16x32_bf16 v[72:75], v[166:169], v[218:221], v[72:75]
	v_mfma_f32_16x16x32_bf16 v[116:119], v[170:173], v[190:193], v[116:119]
	v_mfma_f32_16x16x32_bf16 v[112:115], v[178:181], v[190:193], v[112:115]
	v_mfma_f32_16x16x32_bf16 v[100:103], v[170:173], v[198:201], v[100:103]
	v_mfma_f32_16x16x32_bf16 v[96:99], v[178:181], v[198:201], v[96:99]
	v_mfma_f32_16x16x32_bf16 v[84:87], v[170:173], v[206:209], v[84:87]
	v_mfma_f32_16x16x32_bf16 v[80:83], v[178:181], v[206:209], v[80:83]
	v_mfma_f32_16x16x32_bf16 v[68:71], v[170:173], v[214:217], v[68:71]
	v_mfma_f32_16x16x32_bf16 v[64:67], v[178:181], v[214:217], v[64:67]
	v_mfma_f32_16x16x32_bf16 v[116:119], v[174:177], v[194:197], v[116:119]
	v_mfma_f32_16x16x32_bf16 v[112:115], v[182:185], v[194:197], v[112:115]
	v_mfma_f32_16x16x32_bf16 v[100:103], v[174:177], v[202:205], v[100:103]
	v_mfma_f32_16x16x32_bf16 v[96:99], v[182:185], v[202:205], v[96:99]
	v_mfma_f32_16x16x32_bf16 v[84:87], v[174:177], v[210:213], v[84:87]
	v_mfma_f32_16x16x32_bf16 v[80:83], v[182:185], v[210:213], v[80:83]
	v_mfma_f32_16x16x32_bf16 v[68:71], v[174:177], v[218:221], v[68:71]
	v_mfma_f32_16x16x32_bf16 v[64:67], v[182:185], v[218:221], v[64:67]
	s_setprio 0
	s_barrier
	s_add_i32 s30, s62, s40
	s_add_i32 m0, s30, 0xffffff80
	ds_read_b128 v[190:193], v151 offset:49152
	ds_read_b128 v[194:197], v151 offset:50176
	ds_read_b128 v[198:201], v151 offset:51200
	ds_read_b128 v[202:205], v151 offset:52224
	global_load_lds_dwordx4 v134, s[100:101] offset:128
	s_add_i32 m0, s30, 0x1f80
	s_add_i32 s30, s63, s40
	global_load_lds_dwordx4 v132, s[100:101] offset:128
	s_add_i32 m0, s30, 0xffffff80
	s_add_u32 s100, s100, s10
	s_addc_u32 s101, s101, s11
	global_load_lds_dwordx4 v134, s[100:101] offset:128
	s_add_i32 m0, s30, 0x1f80
	ds_read_b128 v[214:217], v151 offset:55296
	global_load_lds_dwordx4 v132, s[100:101] offset:128
	s_add_i32 m0, s48, 0xffffff80
	ds_read_b128 v[210:213], v151 offset:54272
	global_load_lds_dwordx4 v130, vcc offset:128
	s_add_i32 m0, s49, 0xffffff80
	ds_read_b128 v[206:209], v151 offset:53248
	global_load_lds_dwordx4 v128, vcc offset:128
	ds_read_b128 v[218:221], v151 offset:56320
	s_waitcnt vmcnt(8) lgkmcnt(0)
	s_setprio 1
	s_barrier
	v_mfma_f32_16x16x32_bf16 v[60:63], v[154:157], v[190:193], v[60:63]
	v_mfma_f32_16x16x32_bf16 v[56:59], v[162:165], v[190:193], v[56:59]
	v_mfma_f32_16x16x32_bf16 v[44:47], v[154:157], v[198:201], v[44:47]
	v_mfma_f32_16x16x32_bf16 v[40:43], v[162:165], v[198:201], v[40:43]
	v_mfma_f32_16x16x32_bf16 v[28:31], v[154:157], v[206:209], v[28:31]
	v_mfma_f32_16x16x32_bf16 v[24:27], v[162:165], v[206:209], v[24:27]
	v_mfma_f32_16x16x32_bf16 v[12:15], v[154:157], v[214:217], v[12:15]
	v_mfma_f32_16x16x32_bf16 v[8:11], v[162:165], v[214:217], v[8:11]
	v_mfma_f32_16x16x32_bf16 v[60:63], v[158:161], v[194:197], v[60:63]
	v_mfma_f32_16x16x32_bf16 v[56:59], v[166:169], v[194:197], v[56:59]
	v_mfma_f32_16x16x32_bf16 v[44:47], v[158:161], v[202:205], v[44:47]
	v_mfma_f32_16x16x32_bf16 v[40:43], v[166:169], v[202:205], v[40:43]
	v_mfma_f32_16x16x32_bf16 v[28:31], v[158:161], v[210:213], v[28:31]
	v_mfma_f32_16x16x32_bf16 v[24:27], v[166:169], v[210:213], v[24:27]
	v_mfma_f32_16x16x32_bf16 v[12:15], v[158:161], v[218:221], v[12:15]
	v_mfma_f32_16x16x32_bf16 v[8:11], v[166:169], v[218:221], v[8:11]
	v_mfma_f32_16x16x32_bf16 v[52:55], v[170:173], v[190:193], v[52:55]
	v_mfma_f32_16x16x32_bf16 v[48:51], v[178:181], v[190:193], v[48:51]
	v_mfma_f32_16x16x32_bf16 v[36:39], v[170:173], v[198:201], v[36:39]
	v_mfma_f32_16x16x32_bf16 v[32:35], v[178:181], v[198:201], v[32:35]
	v_mfma_f32_16x16x32_bf16 v[20:23], v[170:173], v[206:209], v[20:23]
	v_mfma_f32_16x16x32_bf16 v[16:19], v[178:181], v[206:209], v[16:19]
	v_mfma_f32_16x16x32_bf16 v[4:7], v[170:173], v[214:217], v[4:7]
	v_mfma_f32_16x16x32_bf16 v[0:3], v[178:181], v[214:217], v[0:3]
	v_mfma_f32_16x16x32_bf16 v[52:55], v[174:177], v[194:197], v[52:55]
	v_mfma_f32_16x16x32_bf16 v[48:51], v[182:185], v[194:197], v[48:51]
	v_mfma_f32_16x16x32_bf16 v[36:39], v[174:177], v[202:205], v[36:39]
	v_mfma_f32_16x16x32_bf16 v[32:35], v[182:185], v[202:205], v[32:35]
	v_mfma_f32_16x16x32_bf16 v[20:23], v[174:177], v[210:213], v[20:23]
	v_mfma_f32_16x16x32_bf16 v[16:19], v[182:185], v[210:213], v[16:19]
	v_mfma_f32_16x16x32_bf16 v[4:7], v[174:177], v[218:221], v[4:7]
	v_mfma_f32_16x16x32_bf16 v[0:3], v[182:185], v[218:221], v[0:3]
	s_setprio 0
	s_barrier
	s_add_u32 s4, s4, 0x100
	s_addc_u32 s5, s5, 0
	s_add_u32 s59, s59, 0x100
	s_addc_u32 s60, s60, 0
	s_cmp_ge_i32 s61, s51
	s_mov_b32 s30, s61
	s_cbranch_scc0 .LBB0_523

; #define PG8_STAGE(bufoff, gbase, voff) do { _Pragma("unroll") for (int _i = 0; _i < 2; ++_i) \
;         __builtin_amdgcn_global_load_lds((const unsigned*)((const char*)(gbase) + (voff)[_i]), (PG8_LAS unsigned*)(lds + (bufoff) + ldsw + _i * 8192), 16, 0, 0); } while (0)
; #define PG8_LDA(dst, b, h) do { _Pragma("unroll") for (int m = 0; m < 4; ++m) _Pragma("unroll") for (int k = 0; k < 2; ++k) dst[m][k] = *(const PG8_LAS bf16x8*)(lds + PG8_SA(b, h) + aoff + m * 2048 + k * 1024); } while (0)
; #define PG8_LDB(dst, b, h) do { _Pragma("unroll") for (int n = 0; n < 2; ++n) _Pragma("unroll") for (int k = 0; k < 2; ++k) dst[n][k] = *(const PG8_LAS bf16x8*)(lds + PG8_SB(b, h) + boff + n * 2048 + k * 1024); } while (0)
; #define PG8_WAIT_V(n) asm volatile("s_waitcnt vmcnt(" #n ")" ::: "memory")
; #define PG8_WAIT_L(n) asm volatile("s_waitcnt lgkmcnt(" #n ")" ::: "memory")
; #define PG8_BAR __builtin_amdgcn_s_barrier()
; #define PG8_SCHED __builtin_amdgcn_sched_barrier(0)
; template <class Epi, class Sched, bool ALIGN_EPI = false, bool SP2 = false>
; __device__ __forceinline__ void gemm_phase(PG8_LAS unsigned char* lds, const Gemm g, const Sched& S, const Epi& E) {
;     ...
;         const char* nA = has_next ? (const char*)g.A + (size_t)nxt.pm * tstepA : cA; const char* nB = has_next ? (const char*)g.Bt + (size_t)nxt.pn * tstep : cB;
;         for (int t = 0; t < nt; t += 2) {
;             const bool last = (t == nt - 2);
;             const char* a1 = cA + (size_t)(t + 1) * kstep;
;             const char* a2 = last ? nA : cA + (size_t)(t + 2) * kstep; const char* b2 = last ? nB : cB + (size_t)(t + 2) * kstep;
;             const char* a3 = a2 + kstep; const char* b3 = b2 + kstep;
;             if (last && has_next) S.a_ready(nxt);
;             if constexpr (SP2) {
;             PG8_LDB(B0, 0, 0); PG8_LDB(B1, 0, 1); PG8_SCHED; PG8_LDA(At, 0, 0); PG8_STAGE(PG8_SA(1, 1), a1 + hstepA, voffA);
;             PG8_WAIT_V(8); PG8_WAIT_L(0); PG8_BAR; PG8_MMA(0, 0, At, B0); PG8_MMA(0, 1, At, B1); PG8_BAR; PG8_SCHED;
;             PG8_LDA(At, 0, 1); PG8_STAGE(PG8_SB(0, 0), b2, voffB); PG8_STAGE(PG8_SB(0, 1), b2 + hstep, voffB); PG8_STAGE(PG8_SA(0, 0), a2, voffA);
;             PG8_WAIT_V(8); PG8_WAIT_L(0); PG8_BAR; PG8_MMA(1, 0, At, B0); PG8_MMA(1, 1, At, B1); PG8_BAR; PG8_SCHED;
.LBB0_601:
	ds_read_b128 v[150:153], v147
	ds_read_b128 v[154:157], v147 offset:1024
	ds_read_b128 v[158:161], v147 offset:2048
	ds_read_b128 v[162:165], v147 offset:3072
	ds_read_b128 v[166:169], v148
	ds_read_b128 v[170:173], v148 offset:1024
	ds_read_b128 v[174:177], v148 offset:2048
	ds_read_b128 v[178:181], v148 offset:3072
	s_add_i32 s60, s30, 2
	s_add_u32 s61, s10, 0xfffc0080
	s_addc_u32 s31, s11, -1
	s_cmp_eq_u32 s51, s30
	s_cselect_b32 s30, s59, s61
	s_cselect_b32 s31, s23, s31
	s_cselect_b32 s63, s25, s35
	s_cselect_b32 s62, s24, s34
	s_add_i32 m0, s29, 0xc000
	ds_read_b128 v[182:185], v149
	ds_read_b128 v[190:193], v149 offset:1024
	ds_read_b128 v[194:197], v149 offset:2048
	ds_read_b128 v[198:201], v149 offset:3072
	ds_read_b128 v[202:205], v149 offset:4096
	ds_read_b128 v[206:209], v149 offset:5120
	ds_read_b128 v[210:213], v149 offset:6144
	global_load_lds_dwordx4 v136, s[10:11]
	s_add_i32 m0, s29, 0xe000
	ds_read_b128 v[214:217], v149 offset:7168
	global_load_lds_dwordx4 v138, s[10:11]
	s_waitcnt vmcnt(8) lgkmcnt(0)
	s_setprio 1
	s_barrier
	v_mfma_f32_16x16x32_bf16 v[120:123], v[150:153], v[182:185], v[120:123]
	v_mfma_f32_16x16x32_bf16 v[112:115], v[158:161], v[182:185], v[112:115]
	v_mfma_f32_16x16x32_bf16 v[104:107], v[150:153], v[194:197], v[104:107]
	v_mfma_f32_16x16x32_bf16 v[96:99], v[158:161], v[194:197], v[96:99]
	v_mfma_f32_16x16x32_bf16 v[88:91], v[150:153], v[202:205], v[88:91]
	v_mfma_f32_16x16x32_bf16 v[80:83], v[158:161], v[202:205], v[80:83]
	v_mfma_f32_16x16x32_bf16 v[72:75], v[150:153], v[210:213], v[72:75]
	v_mfma_f32_16x16x32_bf16 v[64:67], v[158:161], v[210:213], v[64:67]
	v_mfma_f32_16x16x32_bf16 v[120:123], v[154:157], v[190:193], v[120:123]
	v_mfma_f32_16x16x32_bf16 v[112:115], v[162:165], v[190:193], v[112:115]
	v_mfma_f32_16x16x32_bf16 v[104:107], v[154:157], v[198:201], v[104:107]
	v_mfma_f32_16x16x32_bf16 v[96:99], v[162:165], v[198:201], v[96:99]
	v_mfma_f32_16x16x32_bf16 v[88:91], v[154:157], v[206:209], v[88:91]
	v_mfma_f32_16x16x32_bf16 v[80:83], v[162:165], v[206:209], v[80:83]
	v_mfma_f32_16x16x32_bf16 v[72:75], v[154:157], v[214:217], v[72:75]
	v_mfma_f32_16x16x32_bf16 v[64:67], v[162:165], v[214:217], v[64:67]
	v_mfma_f32_16x16x32_bf16 v[124:127], v[166:169], v[182:185], v[124:127]
	v_mfma_f32_16x16x32_bf16 v[116:119], v[174:177], v[182:185], v[116:119]
	v_mfma_f32_16x16x32_bf16 v[108:111], v[166:169], v[194:197], v[108:111]
	v_mfma_f32_16x16x32_bf16 v[100:103], v[174:177], v[194:197], v[100:103]
	v_mfma_f32_16x16x32_bf16 v[92:95], v[166:169], v[202:205], v[92:95]
	v_mfma_f32_16x16x32_bf16 v[84:87], v[174:177], v[202:205], v[84:87]
	v_mfma_f32_16x16x32_bf16 v[76:79], v[166:169], v[210:213], v[76:79]
	v_mfma_f32_16x16x32_bf16 v[68:71], v[174:177], v[210:213], v[68:71]
	v_mfma_f32_16x16x32_bf16 v[124:127], v[170:173], v[190:193], v[124:127]
	v_mfma_f32_16x16x32_bf16 v[116:119], v[178:181], v[190:193], v[116:119]
	v_mfma_f32_16x16x32_bf16 v[108:111], v[170:173], v[198:201], v[108:111]
	v_mfma_f32_16x16x32_bf16 v[100:103], v[178:181], v[198:201], v[100:103]
	v_mfma_f32_16x16x32_bf16 v[92:95], v[170:173], v[206:209], v[92:95]
	v_mfma_f32_16x16x32_bf16 v[84:87], v[178:181], v[206:209], v[84:87]
	v_mfma_f32_16x16x32_bf16 v[76:79], v[170:173], v[214:217], v[76:79]
	v_mfma_f32_16x16x32_bf16 v[68:71], v[178:181], v[214:217], v[68:71]
	s_setprio 0
	s_barrier
	s_add_i32 s61, s52, s38
	s_mov_b32 m0, s61
	ds_read_b128 v[182:185], v149 offset:16384
	ds_read_b128 v[190:193], v149 offset:17408
	ds_read_b128 v[194:197], v149 offset:18432
	ds_read_b128 v[198:201], v149 offset:19456
	global_load_lds_dwordx4 v134, s[62:63]
	s_add_i32 m0, s61, 0x2000
	s_mov_b64 s[100:101], s[62:63]
	s_add_i32 s61, s53, s38
	global_load_lds_dwordx4 v132, s[62:63]
	s_mov_b32 m0, s61
	s_add_u32 s62, s62, s4
	s_addc_u32 s63, s63, s5
	global_load_lds_dwordx4 v134, s[62:63]
	s_add_i32 m0, s61, 0x2000
	ds_read_b128 v[210:213], v149 offset:22528
	global_load_lds_dwordx4 v132, s[62:63]
	s_mov_b32 m0, s29
	ds_read_b128 v[206:209], v149 offset:21504
	global_load_lds_dwordx4 v128, s[30:31]
	s_mov_b32 m0, s41
	ds_read_b128 v[202:205], v149 offset:20480
	global_load_lds_dwordx4 v130, s[30:31]
	ds_read_b128 v[214:217], v149 offset:23552
	s_waitcnt vmcnt(8) lgkmcnt(0)
	s_setprio 1
	s_barrier
	v_mfma_f32_16x16x32_bf16 v[56:59], v[150:153], v[182:185], v[56:59]
	v_mfma_f32_16x16x32_bf16 v[48:51], v[158:161], v[182:185], v[48:51]
	v_mfma_f32_16x16x32_bf16 v[40:43], v[150:153], v[194:197], v[40:43]
	v_mfma_f32_16x16x32_bf16 v[32:35], v[158:161], v[194:197], v[32:35]
	v_mfma_f32_16x16x32_bf16 v[24:27], v[150:153], v[202:205], v[24:27]
	v_mfma_f32_16x16x32_bf16 v[16:19], v[158:161], v[202:205], v[16:19]
	v_mfma_f32_16x16x32_bf16 v[8:11], v[150:153], v[210:213], v[8:11]
	v_mfma_f32_16x16x32_bf16 v[0:3], v[158:161], v[210:213], v[0:3]
	v_mfma_f32_16x16x32_bf16 v[56:59], v[154:157], v[190:193], v[56:59]
	v_mfma_f32_16x16x32_bf16 v[48:51], v[162:165], v[190:193], v[48:51]
	v_mfma_f32_16x16x32_bf16 v[40:43], v[154:157], v[198:201], v[40:43]
	v_mfma_f32_16x16x32_bf16 v[32:35], v[162:165], v[198:201], v[32:35]
	v_mfma_f32_16x16x32_bf16 v[24:27], v[154:157], v[206:209], v[24:27]
	v_mfma_f32_16x16x32_bf16 v[16:19], v[162:165], v[206:209], v[16:19]
	v_mfma_f32_16x16x32_bf16 v[8:11], v[154:157], v[214:217], v[8:11]
	v_mfma_f32_16x16x32_bf16 v[0:3], v[162:165], v[214:217], v[0:3]
	v_mfma_f32_16x16x32_bf16 v[60:63], v[166:169], v[182:185], v[60:63]
	v_mfma_f32_16x16x32_bf16 v[52:55], v[174:177], v[182:185], v[52:55]
	v_mfma_f32_16x16x32_bf16 v[44:47], v[166:169], v[194:197], v[44:47]
	v_mfma_f32_16x16x32_bf16 v[36:39], v[174:177], v[194:197], v[36:39]
	v_mfma_f32_16x16x32_bf16 v[28:31], v[166:169], v[202:205], v[28:31]
	v_mfma_f32_16x16x32_bf16 v[20:23], v[174:177], v[202:205], v[20:23]
	v_mfma_f32_16x16x32_bf16 v[12:15], v[166:169], v[210:213], v[12:15]
	v_mfma_f32_16x16x32_bf16 v[4:7], v[174:177], v[210:213], v[4:7]
	v_mfma_f32_16x16x32_bf16 v[60:63], v[170:173], v[190:193], v[60:63]
	v_mfma_f32_16x16x32_bf16 v[52:55], v[178:181], v[190:193], v[52:55]
	v_mfma_f32_16x16x32_bf16 v[44:47], v[170:173], v[198:201], v[44:47]
	v_mfma_f32_16x16x32_bf16 v[36:39], v[178:181], v[198:201], v[36:39]
	v_mfma_f32_16x16x32_bf16 v[28:31], v[170:173], v[206:209], v[28:31]
	v_mfma_f32_16x16x32_bf16 v[20:23], v[178:181], v[206:209], v[20:23]
	v_mfma_f32_16x16x32_bf16 v[12:15], v[170:173], v[214:217], v[12:15]
	v_mfma_f32_16x16x32_bf16 v[4:7], v[178:181], v[214:217], v[4:7]
	s_setprio 0
	s_barrier
; #define PG8_STAGE(bufoff, gbase, voff) do { _Pragma("unroll") for (int _i = 0; _i < 2; ++_i) \
;         __builtin_amdgcn_global_load_lds((const unsigned*)((const char*)(gbase) + (voff)[_i]), (PG8_LAS unsigned*)(lds + (bufoff) + ldsw + _i * 8192), 16, 0, 0); } while (0)
; #define PG8_LDA(dst, b, h) do { _Pragma("unroll") for (int m = 0; m < 4; ++m) _Pragma("unroll") for (int k = 0; k < 2; ++k) dst[m][k] = *(const PG8_LAS bf16x8*)(lds + PG8_SA(b, h) + aoff + m * 2048 + k * 1024); } while (0)
; #define PG8_LDB(dst, b, h) do { _Pragma("unroll") for (int n = 0; n < 2; ++n) _Pragma("unroll") for (int k = 0; k < 2; ++k) dst[n][k] = *(const PG8_LAS bf16x8*)(lds + PG8_SB(b, h) + boff + n * 2048 + k * 1024); } while (0)
; #define PG8_MMA(ai, bj, At, Bt) do { __builtin_amdgcn_s_setprio(1); _Pragma("unroll") for (int m = 0; m < 4; ++m) _Pragma("unroll") for (int n = 0; n < 2; ++n) _Pragma("unroll") for (int k = 0; k < 2; ++k) \
;         acc[ai][bj][m][n] = __builtin_amdgcn_mfma_f32_16x16x32_bf16(Bt[n][k], At[m][k], acc[ai][bj][m][n], 0, 0, 0); __builtin_amdgcn_s_setprio(0); } while (0)
; #define PG8_WAIT_V(n) asm volatile("s_waitcnt vmcnt(" #n ")" ::: "memory")
; #define PG8_WAIT_L(n) asm volatile("s_waitcnt lgkmcnt(" #n ")" ::: "memory")
; #define PG8_BAR __builtin_amdgcn_s_barrier()
; #define PG8_SCHED __builtin_amdgcn_sched_barrier(0)
; template <class Epi, class Sched, bool ALIGN_EPI = false, bool SP2 = false>
; __device__ __forceinline__ void gemm_phase(PG8_LAS unsigned char* lds, const Gemm g, const Sched& S, const Epi& E) {
;     ...
;             PG8_LDB(B0, 1, 0); PG8_LDB(B1, 1, 1); PG8_SCHED; PG8_LDA(At, 1, 0); PG8_STAGE(PG8_SA(0, 1), a2 + hstepA, voffA);
;             PG8_WAIT_V(8); PG8_WAIT_L(0); PG8_BAR; PG8_MMA(0, 0, At, B0); PG8_MMA(0, 1, At, B1); PG8_BAR; PG8_SCHED;
;             PG8_LDA(At, 1, 1); PG8_STAGE(PG8_SB(1, 0), b3, voffB); PG8_STAGE(PG8_SB(1, 1), b3 + hstep, voffB); PG8_STAGE(PG8_SA(1, 0), a3, voffA);
;             PG8_WAIT_V(8); PG8_WAIT_L(0); PG8_BAR; PG8_MMA(1, 0, At, B0); PG8_MMA(1, 1, At, B1); PG8_BAR; PG8_SCHED;
	s_add_i32 s61, 0, 0x18000
	s_add_i32 s62, 0, 0x1c000
	v_add_u32_e32 v162, s61, v145
	v_add_u32_e32 v178, s62, v145
	ds_read_b128 v[150:153], v162
	ds_read_b128 v[154:157], v162 offset:1024
	ds_read_b128 v[158:161], v162 offset:2048
	ds_read_b128 v[162:165], v162 offset:3072
	ds_read_b128 v[166:169], v178
	ds_read_b128 v[170:173], v178 offset:1024
	ds_read_b128 v[174:177], v178 offset:2048
	ds_read_b128 v[178:181], v178 offset:3072
	s_mov_b64 vcc, s[30:31]
	s_add_u32 s30, s30, 0x40000
	s_addc_u32 s31, s31, 0
	s_mov_b32 m0, s42
	ds_read_b128 v[182:185], v149 offset:32768
	ds_read_b128 v[190:193], v149 offset:33792
	ds_read_b128 v[194:197], v149 offset:34816
	ds_read_b128 v[198:201], v149 offset:35840
	ds_read_b128 v[202:205], v149 offset:36864
	ds_read_b128 v[206:209], v149 offset:37888
	ds_read_b128 v[210:213], v149 offset:38912
	global_load_lds_dwordx4 v128, s[30:31]
	s_mov_b32 m0, s43
	ds_read_b128 v[214:217], v149 offset:39936
	global_load_lds_dwordx4 v130, s[30:31]
	s_waitcnt vmcnt(8) lgkmcnt(0)
	s_setprio 1
	s_barrier
	v_mfma_f32_16x16x32_bf16 v[120:123], v[150:153], v[182:185], v[120:123]
	v_mfma_f32_16x16x32_bf16 v[112:115], v[158:161], v[182:185], v[112:115]
	v_mfma_f32_16x16x32_bf16 v[104:107], v[150:153], v[194:197], v[104:107]
	v_mfma_f32_16x16x32_bf16 v[96:99], v[158:161], v[194:197], v[96:99]
	v_mfma_f32_16x16x32_bf16 v[88:91], v[150:153], v[202:205], v[88:91]
	v_mfma_f32_16x16x32_bf16 v[80:83], v[158:161], v[202:205], v[80:83]
	v_mfma_f32_16x16x32_bf16 v[72:75], v[150:153], v[210:213], v[72:75]
	v_mfma_f32_16x16x32_bf16 v[64:67], v[158:161], v[210:213], v[64:67]
	v_mfma_f32_16x16x32_bf16 v[120:123], v[154:157], v[190:193], v[120:123]
	v_mfma_f32_16x16x32_bf16 v[112:115], v[162:165], v[190:193], v[112:115]
	v_mfma_f32_16x16x32_bf16 v[104:107], v[154:157], v[198:201], v[104:107]
	v_mfma_f32_16x16x32_bf16 v[96:99], v[162:165], v[198:201], v[96:99]
	v_mfma_f32_16x16x32_bf16 v[88:91], v[154:157], v[206:209], v[88:91]
	v_mfma_f32_16x16x32_bf16 v[80:83], v[162:165], v[206:209], v[80:83]
	v_mfma_f32_16x16x32_bf16 v[72:75], v[154:157], v[214:217], v[72:75]
	v_mfma_f32_16x16x32_bf16 v[64:67], v[162:165], v[214:217], v[64:67]
	v_mfma_f32_16x16x32_bf16 v[124:127], v[166:169], v[182:185], v[124:127]
	v_mfma_f32_16x16x32_bf16 v[116:119], v[174:177], v[182:185], v[116:119]
	v_mfma_f32_16x16x32_bf16 v[108:111], v[166:169], v[194:197], v[108:111]
	v_mfma_f32_16x16x32_bf16 v[100:103], v[174:177], v[194:197], v[100:103]
	v_mfma_f32_16x16x32_bf16 v[92:95], v[166:169], v[202:205], v[92:95]
	v_mfma_f32_16x16x32_bf16 v[84:87], v[174:177], v[202:205], v[84:87]
	v_mfma_f32_16x16x32_bf16 v[76:79], v[166:169], v[210:213], v[76:79]
	v_mfma_f32_16x16x32_bf16 v[68:71], v[174:177], v[210:213], v[68:71]
	v_mfma_f32_16x16x32_bf16 v[124:127], v[170:173], v[190:193], v[124:127]
	v_mfma_f32_16x16x32_bf16 v[116:119], v[178:181], v[190:193], v[116:119]
	v_mfma_f32_16x16x32_bf16 v[108:111], v[170:173], v[198:201], v[108:111]
	v_mfma_f32_16x16x32_bf16 v[100:103], v[178:181], v[198:201], v[100:103]
	v_mfma_f32_16x16x32_bf16 v[92:95], v[170:173], v[206:209], v[92:95]
	v_mfma_f32_16x16x32_bf16 v[84:87], v[178:181], v[206:209], v[84:87]
	v_mfma_f32_16x16x32_bf16 v[76:79], v[170:173], v[214:217], v[76:79]
	v_mfma_f32_16x16x32_bf16 v[68:71], v[178:181], v[214:217], v[68:71]
	s_setprio 0
	s_barrier
	s_add_i32 s30, s61, s38
	s_add_i32 m0, s30, 0xffffff80
	ds_read_b128 v[182:185], v149 offset:49152
	ds_read_b128 v[190:193], v149 offset:50176
	ds_read_b128 v[194:197], v149 offset:51200
	ds_read_b128 v[198:201], v149 offset:52224
	global_load_lds_dwordx4 v134, s[100:101] offset:128
	s_add_i32 m0, s30, 0x1f80
	s_add_i32 s30, s62, s38
	global_load_lds_dwordx4 v132, s[100:101] offset:128
	s_add_i32 m0, s30, 0xffffff80
	s_add_u32 s100, s100, s4
	s_addc_u32 s101, s101, s5
	global_load_lds_dwordx4 v134, s[100:101] offset:128
	s_add_i32 m0, s30, 0x1f80
	ds_read_b128 v[210:213], v149 offset:55296
	global_load_lds_dwordx4 v132, s[100:101] offset:128
	s_add_i32 m0, s47, 0xffffff80
	ds_read_b128 v[206:209], v149 offset:54272
	global_load_lds_dwordx4 v128, vcc offset:128
	s_add_i32 m0, s48, 0xffffff80
	ds_read_b128 v[202:205], v149 offset:53248
	global_load_lds_dwordx4 v130, vcc offset:128
	ds_read_b128 v[214:217], v149 offset:56320
	s_waitcnt vmcnt(8) lgkmcnt(0)
	s_setprio 1
	s_barrier
	v_mfma_f32_16x16x32_bf16 v[56:59], v[150:153], v[182:185], v[56:59]
	v_mfma_f32_16x16x32_bf16 v[48:51], v[158:161], v[182:185], v[48:51]
	v_mfma_f32_16x16x32_bf16 v[40:43], v[150:153], v[194:197], v[40:43]
	v_mfma_f32_16x16x32_bf16 v[32:35], v[158:161], v[194:197], v[32:35]
	v_mfma_f32_16x16x32_bf16 v[24:27], v[150:153], v[202:205], v[24:27]
	v_mfma_f32_16x16x32_bf16 v[16:19], v[158:161], v[202:205], v[16:19]
	v_mfma_f32_16x16x32_bf16 v[8:11], v[150:153], v[210:213], v[8:11]
	v_mfma_f32_16x16x32_bf16 v[0:3], v[158:161], v[210:213], v[0:3]
	v_mfma_f32_16x16x32_bf16 v[56:59], v[154:157], v[190:193], v[56:59]
	v_mfma_f32_16x16x32_bf16 v[48:51], v[162:165], v[190:193], v[48:51]
	v_mfma_f32_16x16x32_bf16 v[40:43], v[154:157], v[198:201], v[40:43]
	v_mfma_f32_16x16x32_bf16 v[32:35], v[162:165], v[198:201], v[32:35]
	v_mfma_f32_16x16x32_bf16 v[24:27], v[154:157], v[206:209], v[24:27]
	v_mfma_f32_16x16x32_bf16 v[16:19], v[162:165], v[206:209], v[16:19]
	v_mfma_f32_16x16x32_bf16 v[8:11], v[154:157], v[214:217], v[8:11]
	v_mfma_f32_16x16x32_bf16 v[0:3], v[162:165], v[214:217], v[0:3]
	v_mfma_f32_16x16x32_bf16 v[60:63], v[166:169], v[182:185], v[60:63]
	v_mfma_f32_16x16x32_bf16 v[52:55], v[174:177], v[182:185], v[52:55]
	v_mfma_f32_16x16x32_bf16 v[44:47], v[166:169], v[194:197], v[44:47]
	v_mfma_f32_16x16x32_bf16 v[36:39], v[174:177], v[194:197], v[36:39]
	v_mfma_f32_16x16x32_bf16 v[28:31], v[166:169], v[202:205], v[28:31]
	v_mfma_f32_16x16x32_bf16 v[20:23], v[174:177], v[202:205], v[20:23]
	v_mfma_f32_16x16x32_bf16 v[12:15], v[166:169], v[210:213], v[12:15]
	v_mfma_f32_16x16x32_bf16 v[4:7], v[174:177], v[210:213], v[4:7]
	v_mfma_f32_16x16x32_bf16 v[60:63], v[170:173], v[190:193], v[60:63]
	v_mfma_f32_16x16x32_bf16 v[52:55], v[178:181], v[190:193], v[52:55]
	v_mfma_f32_16x16x32_bf16 v[44:47], v[170:173], v[198:201], v[44:47]
	v_mfma_f32_16x16x32_bf16 v[36:39], v[178:181], v[198:201], v[36:39]
	v_mfma_f32_16x16x32_bf16 v[28:31], v[170:173], v[206:209], v[28:31]
	v_mfma_f32_16x16x32_bf16 v[20:23], v[178:181], v[206:209], v[20:23]
	v_mfma_f32_16x16x32_bf16 v[12:15], v[170:173], v[214:217], v[12:15]
	v_mfma_f32_16x16x32_bf16 v[4:7], v[178:181], v[214:217], v[4:7]
	s_setprio 0
	s_barrier
	s_add_u32 s10, s10, 0x100
	s_addc_u32 s11, s11, 0
	s_add_u32 s34, s34, 0x100
	s_addc_u32 s35, s35, 0
	s_cmp_ge_i32 s60, s50
	s_mov_b32 s30, s60
	s_cbranch_scc0 .LBB0_601

; #define PG8_STAGE(bufoff, gbase, voff) do { _Pragma("unroll") for (int _i = 0; _i < 2; ++_i) \
;         __builtin_amdgcn_global_load_lds((const unsigned*)((const char*)(gbase) + (voff)[_i]), (PG8_LAS unsigned*)(lds + (bufoff) + ldsw + _i * 8192), 16, 0, 0); } while (0)
; #define PG8_LDA(dst, b, h) do { _Pragma("unroll") for (int m = 0; m < 4; ++m) _Pragma("unroll") for (int k = 0; k < 2; ++k) dst[m][k] = *(const PG8_LAS bf16x8*)(lds + PG8_SA(b, h) + aoff + m * 2048 + k * 1024); } while (0)
; #define PG8_LDB(dst, b, h) do { _Pragma("unroll") for (int n = 0; n < 2; ++n) _Pragma("unroll") for (int k = 0; k < 2; ++k) dst[n][k] = *(const PG8_LAS bf16x8*)(lds + PG8_SB(b, h) + boff + n * 2048 + k * 1024); } while (0)
; #define PG8_WAIT_V(n) asm volatile("s_waitcnt vmcnt(" #n ")" ::: "memory")
; #define PG8_WAIT_L(n) asm volatile("s_waitcnt lgkmcnt(" #n ")" ::: "memory")
; #define PG8_BAR __builtin_amdgcn_s_barrier()
; #define PG8_SCHED __builtin_amdgcn_sched_barrier(0)
; template <class Epi, class Sched, bool ALIGN_EPI = false, bool SP2 = false>
; __device__ __forceinline__ void gemm_phase(PG8_LAS unsigned char* lds, const Gemm g, const Sched& S, const Epi& E) {
;     ...
;         const char* nA = has_next ? (const char*)g.A + (size_t)nxt.pm * tstepA : cA; const char* nB = has_next ? (const char*)g.Bt + (size_t)nxt.pn * tstep : cB;
;         for (int t = 0; t < nt; t += 2) {
;             const bool last = (t == nt - 2);
;             const char* a1 = cA + (size_t)(t + 1) * kstep;
;             const char* a2 = last ? nA : cA + (size_t)(t + 2) * kstep; const char* b2 = last ? nB : cB + (size_t)(t + 2) * kstep;
;             const char* a3 = a2 + kstep; const char* b3 = b2 + kstep;
;             if (last && has_next) S.a_ready(nxt);
;             if constexpr (SP2) {
;             PG8_LDB(B0, 0, 0); PG8_LDB(B1, 0, 1); PG8_SCHED; PG8_LDA(At, 0, 0); PG8_STAGE(PG8_SA(1, 1), a1 + hstepA, voffA);
;             PG8_WAIT_V(8); PG8_WAIT_L(0); PG8_BAR; PG8_MMA(0, 0, At, B0); PG8_MMA(0, 1, At, B1); PG8_BAR; PG8_SCHED;
;             PG8_LDA(At, 0, 1); PG8_STAGE(PG8_SB(0, 0), b2, voffB); PG8_STAGE(PG8_SB(0, 1), b2 + hstep, voffB); PG8_STAGE(PG8_SA(0, 0), a2, voffA);
;             PG8_WAIT_V(8); PG8_WAIT_L(0); PG8_BAR; PG8_MMA(1, 0, At, B0); PG8_MMA(1, 1, At, B1); PG8_BAR; PG8_SCHED;
.LBB0_681:
	ds_read_b128 v[128:131], v175
	ds_read_b128 v[132:135], v175 offset:1024
	ds_read_b128 v[136:139], v175 offset:2048
	ds_read_b128 v[140:143], v175 offset:3072
	ds_read_b128 v[162:165], v176
	ds_read_b128 v[166:169], v176 offset:1024
	ds_read_b128 v[180:183], v176 offset:2048
	ds_read_b128 v[184:187], v176 offset:3072
	s_add_i32 s71, s48, 2
	s_add_u32 s72, s8, 0xfffc0080
	s_addc_u32 s49, s9, -1
	s_cmp_eq_u32 s64, s48
	s_cselect_b32 s48, s70, s72
	s_cselect_b32 s49, s39, s49
	s_cselect_b32 s73, s41, s51
	s_cselect_b32 s72, s40, s50
	s_add_i32 m0, s45, 0xc000
	ds_read_b128 v[190:193], v177
	ds_read_b128 v[194:197], v177 offset:1024
	ds_read_b128 v[198:201], v177 offset:2048
	ds_read_b128 v[202:205], v177 offset:3072
	ds_read_b128 v[206:209], v177 offset:4096
	ds_read_b128 v[210:213], v177 offset:5120
	ds_read_b128 v[214:217], v177 offset:6144
	global_load_lds_dwordx4 v154, s[8:9]
	s_add_i32 m0, s45, 0xe000
	ds_read_b128 v[218:221], v177 offset:7168
	global_load_lds_dwordx4 v156, s[8:9]
	s_waitcnt vmcnt(8) lgkmcnt(0)
	s_setprio 1
	s_barrier
	v_mfma_f32_16x16x32_bf16 v[124:127], v[128:131], v[190:193], v[124:127]
	v_mfma_f32_16x16x32_bf16 v[120:123], v[136:139], v[190:193], v[120:123]
	v_mfma_f32_16x16x32_bf16 v[108:111], v[128:131], v[198:201], v[108:111]
	v_mfma_f32_16x16x32_bf16 v[104:107], v[136:139], v[198:201], v[104:107]
	v_mfma_f32_16x16x32_bf16 v[92:95], v[128:131], v[206:209], v[92:95]
	v_mfma_f32_16x16x32_bf16 v[88:91], v[136:139], v[206:209], v[88:91]
	v_mfma_f32_16x16x32_bf16 v[76:79], v[128:131], v[214:217], v[76:79]
	v_mfma_f32_16x16x32_bf16 v[72:75], v[136:139], v[214:217], v[72:75]
	v_mfma_f32_16x16x32_bf16 v[124:127], v[132:135], v[194:197], v[124:127]
	v_mfma_f32_16x16x32_bf16 v[120:123], v[140:143], v[194:197], v[120:123]
	v_mfma_f32_16x16x32_bf16 v[108:111], v[132:135], v[202:205], v[108:111]
	v_mfma_f32_16x16x32_bf16 v[104:107], v[140:143], v[202:205], v[104:107]
	v_mfma_f32_16x16x32_bf16 v[92:95], v[132:135], v[210:213], v[92:95]
	v_mfma_f32_16x16x32_bf16 v[88:91], v[140:143], v[210:213], v[88:91]
	v_mfma_f32_16x16x32_bf16 v[76:79], v[132:135], v[218:221], v[76:79]
	v_mfma_f32_16x16x32_bf16 v[72:75], v[140:143], v[218:221], v[72:75]
	v_mfma_f32_16x16x32_bf16 v[116:119], v[162:165], v[190:193], v[116:119]
	v_mfma_f32_16x16x32_bf16 v[112:115], v[180:183], v[190:193], v[112:115]
	v_mfma_f32_16x16x32_bf16 v[100:103], v[162:165], v[198:201], v[100:103]
	v_mfma_f32_16x16x32_bf16 v[96:99], v[180:183], v[198:201], v[96:99]
	v_mfma_f32_16x16x32_bf16 v[84:87], v[162:165], v[206:209], v[84:87]
	v_mfma_f32_16x16x32_bf16 v[80:83], v[180:183], v[206:209], v[80:83]
	v_mfma_f32_16x16x32_bf16 v[68:71], v[162:165], v[214:217], v[68:71]
	v_mfma_f32_16x16x32_bf16 v[64:67], v[180:183], v[214:217], v[64:67]
	v_mfma_f32_16x16x32_bf16 v[116:119], v[166:169], v[194:197], v[116:119]
	v_mfma_f32_16x16x32_bf16 v[112:115], v[184:187], v[194:197], v[112:115]
	v_mfma_f32_16x16x32_bf16 v[100:103], v[166:169], v[202:205], v[100:103]
	v_mfma_f32_16x16x32_bf16 v[96:99], v[184:187], v[202:205], v[96:99]
	v_mfma_f32_16x16x32_bf16 v[84:87], v[166:169], v[210:213], v[84:87]
	v_mfma_f32_16x16x32_bf16 v[80:83], v[184:187], v[210:213], v[80:83]
	v_mfma_f32_16x16x32_bf16 v[68:71], v[166:169], v[218:221], v[68:71]
	v_mfma_f32_16x16x32_bf16 v[64:67], v[184:187], v[218:221], v[64:67]
	s_setprio 0
	s_barrier
	s_add_i32 s74, s65, s53
	s_mov_b32 m0, s74
	ds_read_b128 v[190:193], v177 offset:16384
	ds_read_b128 v[194:197], v177 offset:17408
	ds_read_b128 v[198:201], v177 offset:18432
	ds_read_b128 v[202:205], v177 offset:19456
	global_load_lds_dwordx4 v150, s[72:73]
	s_add_i32 m0, s74, 0x2000
	s_mov_b64 s[100:101], s[72:73]
	s_add_i32 s74, s66, s53
	global_load_lds_dwordx4 v148, s[72:73]
	s_mov_b32 m0, s74
	s_add_u32 s72, s72, s10
	s_addc_u32 s73, s73, s11
	global_load_lds_dwordx4 v150, s[72:73]
	s_add_i32 m0, s74, 0x2000
	ds_read_b128 v[214:217], v177 offset:22528
	global_load_lds_dwordx4 v148, s[72:73]
	s_mov_b32 m0, s45
	ds_read_b128 v[210:213], v177 offset:21504
	global_load_lds_dwordx4 v144, s[48:49]
	s_mov_b32 m0, s55
	ds_read_b128 v[206:209], v177 offset:20480
	global_load_lds_dwordx4 v146, s[48:49]
	ds_read_b128 v[218:221], v177 offset:23552
	s_waitcnt vmcnt(8) lgkmcnt(0)
	s_setprio 1
	s_barrier
	v_mfma_f32_16x16x32_bf16 v[60:63], v[128:131], v[190:193], v[60:63]
	v_mfma_f32_16x16x32_bf16 v[56:59], v[136:139], v[190:193], v[56:59]
	v_mfma_f32_16x16x32_bf16 v[44:47], v[128:131], v[198:201], v[44:47]
	v_mfma_f32_16x16x32_bf16 v[40:43], v[136:139], v[198:201], v[40:43]
	v_mfma_f32_16x16x32_bf16 v[28:31], v[128:131], v[206:209], v[28:31]
	v_mfma_f32_16x16x32_bf16 v[24:27], v[136:139], v[206:209], v[24:27]
	v_mfma_f32_16x16x32_bf16 v[12:15], v[128:131], v[214:217], v[12:15]
	v_mfma_f32_16x16x32_bf16 v[8:11], v[136:139], v[214:217], v[8:11]
	v_mfma_f32_16x16x32_bf16 v[60:63], v[132:135], v[194:197], v[60:63]
	v_mfma_f32_16x16x32_bf16 v[56:59], v[140:143], v[194:197], v[56:59]
	v_mfma_f32_16x16x32_bf16 v[44:47], v[132:135], v[202:205], v[44:47]
	v_mfma_f32_16x16x32_bf16 v[40:43], v[140:143], v[202:205], v[40:43]
	v_mfma_f32_16x16x32_bf16 v[28:31], v[132:135], v[210:213], v[28:31]
	v_mfma_f32_16x16x32_bf16 v[24:27], v[140:143], v[210:213], v[24:27]
	v_mfma_f32_16x16x32_bf16 v[12:15], v[132:135], v[218:221], v[12:15]
	v_mfma_f32_16x16x32_bf16 v[8:11], v[140:143], v[218:221], v[8:11]
	v_mfma_f32_16x16x32_bf16 v[52:55], v[162:165], v[190:193], v[52:55]
	v_mfma_f32_16x16x32_bf16 v[48:51], v[180:183], v[190:193], v[48:51]
	v_mfma_f32_16x16x32_bf16 v[36:39], v[162:165], v[198:201], v[36:39]
	v_mfma_f32_16x16x32_bf16 v[32:35], v[180:183], v[198:201], v[32:35]
	v_mfma_f32_16x16x32_bf16 v[20:23], v[162:165], v[206:209], v[20:23]
	v_mfma_f32_16x16x32_bf16 v[16:19], v[180:183], v[206:209], v[16:19]
	v_mfma_f32_16x16x32_bf16 v[4:7], v[162:165], v[214:217], v[4:7]
	v_mfma_f32_16x16x32_bf16 v[0:3], v[180:183], v[214:217], v[0:3]
	v_mfma_f32_16x16x32_bf16 v[52:55], v[166:169], v[194:197], v[52:55]
	v_mfma_f32_16x16x32_bf16 v[48:51], v[184:187], v[194:197], v[48:51]
	v_mfma_f32_16x16x32_bf16 v[36:39], v[166:169], v[202:205], v[36:39]
	v_mfma_f32_16x16x32_bf16 v[32:35], v[184:187], v[202:205], v[32:35]
	v_mfma_f32_16x16x32_bf16 v[20:23], v[166:169], v[210:213], v[20:23]
	v_mfma_f32_16x16x32_bf16 v[16:19], v[184:187], v[210:213], v[16:19]
	v_mfma_f32_16x16x32_bf16 v[4:7], v[166:169], v[218:221], v[4:7]
	v_mfma_f32_16x16x32_bf16 v[0:3], v[184:187], v[218:221], v[0:3]
	s_setprio 0
	s_barrier
; #define PG8_STAGE(bufoff, gbase, voff) do { _Pragma("unroll") for (int _i = 0; _i < 2; ++_i) \
;         __builtin_amdgcn_global_load_lds((const unsigned*)((const char*)(gbase) + (voff)[_i]), (PG8_LAS unsigned*)(lds + (bufoff) + ldsw + _i * 8192), 16, 0, 0); } while (0)
; #define PG8_LDA(dst, b, h) do { _Pragma("unroll") for (int m = 0; m < 4; ++m) _Pragma("unroll") for (int k = 0; k < 2; ++k) dst[m][k] = *(const PG8_LAS bf16x8*)(lds + PG8_SA(b, h) + aoff + m * 2048 + k * 1024); } while (0)
; #define PG8_LDB(dst, b, h) do { _Pragma("unroll") for (int n = 0; n < 2; ++n) _Pragma("unroll") for (int k = 0; k < 2; ++k) dst[n][k] = *(const PG8_LAS bf16x8*)(lds + PG8_SB(b, h) + boff + n * 2048 + k * 1024); } while (0)
; #define PG8_MMA(ai, bj, At, Bt) do { __builtin_amdgcn_s_setprio(1); _Pragma("unroll") for (int m = 0; m < 4; ++m) _Pragma("unroll") for (int n = 0; n < 2; ++n) _Pragma("unroll") for (int k = 0; k < 2; ++k) \
;         acc[ai][bj][m][n] = __builtin_amdgcn_mfma_f32_16x16x32_bf16(Bt[n][k], At[m][k], acc[ai][bj][m][n], 0, 0, 0); __builtin_amdgcn_s_setprio(0); } while (0)
; #define PG8_WAIT_V(n) asm volatile("s_waitcnt vmcnt(" #n ")" ::: "memory")
; #define PG8_WAIT_L(n) asm volatile("s_waitcnt lgkmcnt(" #n ")" ::: "memory")
; #define PG8_BAR __builtin_amdgcn_s_barrier()
; #define PG8_SCHED __builtin_amdgcn_sched_barrier(0)
; template <class Epi, class Sched, bool ALIGN_EPI = false, bool SP2 = false>
; __device__ __forceinline__ void gemm_phase(PG8_LAS unsigned char* lds, const Gemm g, const Sched& S, const Epi& E) {
;     ...
;             PG8_LDB(B0, 1, 0); PG8_LDB(B1, 1, 1); PG8_SCHED; PG8_LDA(At, 1, 0); PG8_STAGE(PG8_SA(0, 1), a2 + hstepA, voffA);
;             PG8_WAIT_V(8); PG8_WAIT_L(0); PG8_BAR; PG8_MMA(0, 0, At, B0); PG8_MMA(0, 1, At, B1); PG8_BAR; PG8_SCHED;
;             PG8_LDA(At, 1, 1); PG8_STAGE(PG8_SB(1, 0), b3, voffB); PG8_STAGE(PG8_SB(1, 1), b3 + hstep, voffB); PG8_STAGE(PG8_SA(1, 0), a3, voffA);
;             PG8_WAIT_V(8); PG8_WAIT_L(0); PG8_BAR; PG8_MMA(1, 0, At, B0); PG8_MMA(1, 1, At, B1); PG8_BAR; PG8_SCHED;
	s_add_i32 s72, 0, 0x18000
	s_add_i32 s73, 0, 0x1c000
	v_add_u32_e32 v140, s72, v173
	v_add_u32_e32 v152, s73, v173
	ds_read_b128 v[128:131], v140
	ds_read_b128 v[132:135], v140 offset:1024
	ds_read_b128 v[136:139], v140 offset:2048
	ds_read_b128 v[140:143], v140 offset:3072
	ds_read_b128 v[162:165], v152
	ds_read_b128 v[166:169], v152 offset:1024
	ds_read_b128 v[180:183], v152 offset:2048
	ds_read_b128 v[184:187], v152 offset:3072
	s_mov_b64 vcc, s[48:49]
	s_add_u32 s48, s48, 0x40000
	s_addc_u32 s49, s49, 0
	s_mov_b32 m0, s56
	ds_read_b128 v[190:193], v177 offset:32768
	ds_read_b128 v[194:197], v177 offset:33792
	ds_read_b128 v[198:201], v177 offset:34816
	ds_read_b128 v[202:205], v177 offset:35840
	ds_read_b128 v[206:209], v177 offset:36864
	ds_read_b128 v[210:213], v177 offset:37888
	ds_read_b128 v[214:217], v177 offset:38912
	global_load_lds_dwordx4 v144, s[48:49]
	s_mov_b32 m0, s57
	ds_read_b128 v[218:221], v177 offset:39936
	global_load_lds_dwordx4 v146, s[48:49]
	s_waitcnt vmcnt(8) lgkmcnt(0)
	s_setprio 1
	s_barrier
	v_mfma_f32_16x16x32_bf16 v[124:127], v[128:131], v[190:193], v[124:127]
	v_mfma_f32_16x16x32_bf16 v[120:123], v[136:139], v[190:193], v[120:123]
	v_mfma_f32_16x16x32_bf16 v[108:111], v[128:131], v[198:201], v[108:111]
	v_mfma_f32_16x16x32_bf16 v[104:107], v[136:139], v[198:201], v[104:107]
	v_mfma_f32_16x16x32_bf16 v[92:95], v[128:131], v[206:209], v[92:95]
	v_mfma_f32_16x16x32_bf16 v[88:91], v[136:139], v[206:209], v[88:91]
	v_mfma_f32_16x16x32_bf16 v[76:79], v[128:131], v[214:217], v[76:79]
	v_mfma_f32_16x16x32_bf16 v[72:75], v[136:139], v[214:217], v[72:75]
	v_mfma_f32_16x16x32_bf16 v[124:127], v[132:135], v[194:197], v[124:127]
	v_mfma_f32_16x16x32_bf16 v[120:123], v[140:143], v[194:197], v[120:123]
	v_mfma_f32_16x16x32_bf16 v[108:111], v[132:135], v[202:205], v[108:111]
	v_mfma_f32_16x16x32_bf16 v[104:107], v[140:143], v[202:205], v[104:107]
	v_mfma_f32_16x16x32_bf16 v[92:95], v[132:135], v[210:213], v[92:95]
	v_mfma_f32_16x16x32_bf16 v[88:91], v[140:143], v[210:213], v[88:91]
	v_mfma_f32_16x16x32_bf16 v[76:79], v[132:135], v[218:221], v[76:79]
	v_mfma_f32_16x16x32_bf16 v[72:75], v[140:143], v[218:221], v[72:75]
	v_mfma_f32_16x16x32_bf16 v[116:119], v[162:165], v[190:193], v[116:119]
	v_mfma_f32_16x16x32_bf16 v[112:115], v[180:183], v[190:193], v[112:115]
	v_mfma_f32_16x16x32_bf16 v[100:103], v[162:165], v[198:201], v[100:103]
	v_mfma_f32_16x16x32_bf16 v[96:99], v[180:183], v[198:201], v[96:99]
	v_mfma_f32_16x16x32_bf16 v[84:87], v[162:165], v[206:209], v[84:87]
	v_mfma_f32_16x16x32_bf16 v[80:83], v[180:183], v[206:209], v[80:83]
	v_mfma_f32_16x16x32_bf16 v[68:71], v[162:165], v[214:217], v[68:71]
	v_mfma_f32_16x16x32_bf16 v[64:67], v[180:183], v[214:217], v[64:67]
	v_mfma_f32_16x16x32_bf16 v[116:119], v[166:169], v[194:197], v[116:119]
	v_mfma_f32_16x16x32_bf16 v[112:115], v[184:187], v[194:197], v[112:115]
	v_mfma_f32_16x16x32_bf16 v[100:103], v[166:169], v[202:205], v[100:103]
	v_mfma_f32_16x16x32_bf16 v[96:99], v[184:187], v[202:205], v[96:99]
	v_mfma_f32_16x16x32_bf16 v[84:87], v[166:169], v[210:213], v[84:87]
	v_mfma_f32_16x16x32_bf16 v[80:83], v[184:187], v[210:213], v[80:83]
	v_mfma_f32_16x16x32_bf16 v[68:71], v[166:169], v[218:221], v[68:71]
	v_mfma_f32_16x16x32_bf16 v[64:67], v[184:187], v[218:221], v[64:67]
	s_setprio 0
	s_barrier
	s_add_i32 s48, s72, s53
	s_add_i32 m0, s48, 0xffffff80
	ds_read_b128 v[190:193], v177 offset:49152
	ds_read_b128 v[194:197], v177 offset:50176
	ds_read_b128 v[198:201], v177 offset:51200
	ds_read_b128 v[202:205], v177 offset:52224
	global_load_lds_dwordx4 v150, s[100:101] offset:128
	s_add_i32 m0, s48, 0x1f80
	s_add_i32 s48, s73, s53
	global_load_lds_dwordx4 v148, s[100:101] offset:128
	s_add_i32 m0, s48, 0xffffff80
	s_add_u32 s100, s100, s10
	s_addc_u32 s101, s101, s11
	global_load_lds_dwordx4 v150, s[100:101] offset:128
	s_add_i32 m0, s48, 0x1f80
	ds_read_b128 v[214:217], v177 offset:55296
	global_load_lds_dwordx4 v148, s[100:101] offset:128
	s_add_i32 m0, s60, 0xffffff80
	ds_read_b128 v[210:213], v177 offset:54272
	global_load_lds_dwordx4 v144, vcc offset:128
	s_add_i32 m0, s61, 0xffffff80
	ds_read_b128 v[206:209], v177 offset:53248
	global_load_lds_dwordx4 v146, vcc offset:128
	ds_read_b128 v[218:221], v177 offset:56320
	s_waitcnt vmcnt(8) lgkmcnt(0)
	s_setprio 1
	s_barrier
	v_mfma_f32_16x16x32_bf16 v[60:63], v[128:131], v[190:193], v[60:63]
	v_mfma_f32_16x16x32_bf16 v[56:59], v[136:139], v[190:193], v[56:59]
	v_mfma_f32_16x16x32_bf16 v[44:47], v[128:131], v[198:201], v[44:47]
	v_mfma_f32_16x16x32_bf16 v[40:43], v[136:139], v[198:201], v[40:43]
	v_mfma_f32_16x16x32_bf16 v[28:31], v[128:131], v[206:209], v[28:31]
	v_mfma_f32_16x16x32_bf16 v[24:27], v[136:139], v[206:209], v[24:27]
	v_mfma_f32_16x16x32_bf16 v[12:15], v[128:131], v[214:217], v[12:15]
	v_mfma_f32_16x16x32_bf16 v[8:11], v[136:139], v[214:217], v[8:11]
	v_mfma_f32_16x16x32_bf16 v[60:63], v[132:135], v[194:197], v[60:63]
	v_mfma_f32_16x16x32_bf16 v[56:59], v[140:143], v[194:197], v[56:59]
	v_mfma_f32_16x16x32_bf16 v[44:47], v[132:135], v[202:205], v[44:47]
	v_mfma_f32_16x16x32_bf16 v[40:43], v[140:143], v[202:205], v[40:43]
	v_mfma_f32_16x16x32_bf16 v[28:31], v[132:135], v[210:213], v[28:31]
	v_mfma_f32_16x16x32_bf16 v[24:27], v[140:143], v[210:213], v[24:27]
	v_mfma_f32_16x16x32_bf16 v[12:15], v[132:135], v[218:221], v[12:15]
	v_mfma_f32_16x16x32_bf16 v[8:11], v[140:143], v[218:221], v[8:11]
	v_mfma_f32_16x16x32_bf16 v[52:55], v[162:165], v[190:193], v[52:55]
	v_mfma_f32_16x16x32_bf16 v[48:51], v[180:183], v[190:193], v[48:51]
	v_mfma_f32_16x16x32_bf16 v[36:39], v[162:165], v[198:201], v[36:39]
	v_mfma_f32_16x16x32_bf16 v[32:35], v[180:183], v[198:201], v[32:35]
	v_mfma_f32_16x16x32_bf16 v[20:23], v[162:165], v[206:209], v[20:23]
	v_mfma_f32_16x16x32_bf16 v[16:19], v[180:183], v[206:209], v[16:19]
	v_mfma_f32_16x16x32_bf16 v[4:7], v[162:165], v[214:217], v[4:7]
	v_mfma_f32_16x16x32_bf16 v[0:3], v[180:183], v[214:217], v[0:3]
	v_mfma_f32_16x16x32_bf16 v[52:55], v[166:169], v[194:197], v[52:55]
	v_mfma_f32_16x16x32_bf16 v[48:51], v[184:187], v[194:197], v[48:51]
	v_mfma_f32_16x16x32_bf16 v[36:39], v[166:169], v[202:205], v[36:39]
	v_mfma_f32_16x16x32_bf16 v[32:35], v[184:187], v[202:205], v[32:35]
	v_mfma_f32_16x16x32_bf16 v[20:23], v[166:169], v[210:213], v[20:23]
	v_mfma_f32_16x16x32_bf16 v[16:19], v[184:187], v[210:213], v[16:19]
	v_mfma_f32_16x16x32_bf16 v[4:7], v[166:169], v[218:221], v[4:7]
	v_mfma_f32_16x16x32_bf16 v[0:3], v[184:187], v[218:221], v[0:3]
	s_setprio 0
	s_barrier
	s_add_u32 s8, s8, 0x100
	s_addc_u32 s9, s9, 0
	s_add_u32 s50, s50, 0x100
	s_addc_u32 s51, s51, 0
	s_cmp_ge_i32 s71, s63
	s_mov_b32 s48, s71
	s_cbranch_scc0 .LBB0_681

; #define PG8_STAGE(bufoff, gbase, voff) do { _Pragma("unroll") for (int _i = 0; _i < 2; ++_i) \
;         __builtin_amdgcn_global_load_lds((const unsigned*)((const char*)(gbase) + (voff)[_i]), (PG8_LAS unsigned*)(lds + (bufoff) + ldsw + _i * 8192), 16, 0, 0); } while (0)
; #define PG8_LDA(dst, b, h) do { _Pragma("unroll") for (int m = 0; m < 4; ++m) _Pragma("unroll") for (int k = 0; k < 2; ++k) dst[m][k] = *(const PG8_LAS bf16x8*)(lds + PG8_SA(b, h) + aoff + m * 2048 + k * 1024); } while (0)
; #define PG8_LDB(dst, b, h) do { _Pragma("unroll") for (int n = 0; n < 2; ++n) _Pragma("unroll") for (int k = 0; k < 2; ++k) dst[n][k] = *(const PG8_LAS bf16x8*)(lds + PG8_SB(b, h) + boff + n * 2048 + k * 1024); } while (0)
; #define PG8_WAIT_V(n) asm volatile("s_waitcnt vmcnt(" #n ")" ::: "memory")
; #define PG8_WAIT_L(n) asm volatile("s_waitcnt lgkmcnt(" #n ")" ::: "memory")
; #define PG8_BAR __builtin_amdgcn_s_barrier()
; #define PG8_SCHED __builtin_amdgcn_sched_barrier(0)
; template <class Epi, class Sched, bool ALIGN_EPI = false, bool SP2 = false>
; __device__ __forceinline__ void gemm_phase(PG8_LAS unsigned char* lds, const Gemm g, const Sched& S, const Epi& E) {
;     ...
;         const char* nA = has_next ? (const char*)g.A + (size_t)nxt.pm * tstepA : cA; const char* nB = has_next ? (const char*)g.Bt + (size_t)nxt.pn * tstep : cB;
;         for (int t = 0; t < nt; t += 2) {
;             const bool last = (t == nt - 2);
;             const char* a1 = cA + (size_t)(t + 1) * kstep;
;             const char* a2 = last ? nA : cA + (size_t)(t + 2) * kstep; const char* b2 = last ? nB : cB + (size_t)(t + 2) * kstep;
;             const char* a3 = a2 + kstep; const char* b3 = b2 + kstep;
;             if (last && has_next) S.a_ready(nxt);
;             if constexpr (SP2) {
;             PG8_LDB(B0, 0, 0); PG8_LDB(B1, 0, 1); PG8_SCHED; PG8_LDA(At, 0, 0); PG8_STAGE(PG8_SA(1, 1), a1 + hstepA, voffA);
;             PG8_WAIT_V(8); PG8_WAIT_L(0); PG8_BAR; PG8_MMA(0, 0, At, B0); PG8_MMA(0, 1, At, B1); PG8_BAR; PG8_SCHED;
;             PG8_LDA(At, 0, 1); PG8_STAGE(PG8_SB(0, 0), b2, voffB); PG8_STAGE(PG8_SB(0, 1), b2 + hstep, voffB); PG8_STAGE(PG8_SA(0, 0), a2, voffA);
;             PG8_WAIT_V(8); PG8_WAIT_L(0); PG8_BAR; PG8_MMA(1, 0, At, B0); PG8_MMA(1, 1, At, B1); PG8_BAR; PG8_SCHED;
.LBB0_762:
	ds_read_b128 v[128:131], v169
	ds_read_b128 v[132:135], v169 offset:1024
	ds_read_b128 v[136:139], v169 offset:2048
	ds_read_b128 v[140:143], v169 offset:3072
	ds_read_b128 v[156:159], v170
	ds_read_b128 v[160:163], v170 offset:1024
	ds_read_b128 v[172:175], v170 offset:2048
	ds_read_b128 v[176:179], v170 offset:3072
	s_add_i32 s76, s48, 2
	s_add_u32 s77, s44, 0xfffc0080
	s_addc_u32 s49, s45, -1
	s_cmp_eq_u32 s70, s48
	s_cselect_b32 s48, s50, s77
	s_cselect_b32 s49, s37, s49
	s_cselect_b32 s79, s39, s75
	s_cselect_b32 s78, s38, s51
	s_add_i32 m0, s43, 0xc000
	ds_read_b128 v[180:183], v171
	ds_read_b128 v[184:187], v171 offset:1024
	ds_read_b128 v[190:193], v171 offset:2048
	ds_read_b128 v[194:197], v171 offset:3072
	ds_read_b128 v[198:201], v171 offset:4096
	ds_read_b128 v[202:205], v171 offset:5120
	ds_read_b128 v[206:209], v171 offset:6144
	global_load_lds_dwordx4 v152, s[44:45]
	s_add_i32 m0, s43, 0xe000
	ds_read_b128 v[210:213], v171 offset:7168
	global_load_lds_dwordx4 v154, s[44:45]
	s_waitcnt vmcnt(8) lgkmcnt(0)
	s_setprio 1
	s_barrier
	v_mfma_f32_16x16x32_bf16 v[124:127], v[128:131], v[180:183], v[124:127]
	v_mfma_f32_16x16x32_bf16 v[120:123], v[136:139], v[180:183], v[120:123]
	v_mfma_f32_16x16x32_bf16 v[108:111], v[128:131], v[190:193], v[108:111]
	v_mfma_f32_16x16x32_bf16 v[104:107], v[136:139], v[190:193], v[104:107]
	v_mfma_f32_16x16x32_bf16 v[92:95], v[128:131], v[198:201], v[92:95]
	v_mfma_f32_16x16x32_bf16 v[88:91], v[136:139], v[198:201], v[88:91]
	v_mfma_f32_16x16x32_bf16 v[76:79], v[128:131], v[206:209], v[76:79]
	v_mfma_f32_16x16x32_bf16 v[72:75], v[136:139], v[206:209], v[72:75]
	v_mfma_f32_16x16x32_bf16 v[124:127], v[132:135], v[184:187], v[124:127]
	v_mfma_f32_16x16x32_bf16 v[120:123], v[140:143], v[184:187], v[120:123]
	v_mfma_f32_16x16x32_bf16 v[108:111], v[132:135], v[194:197], v[108:111]
	v_mfma_f32_16x16x32_bf16 v[104:107], v[140:143], v[194:197], v[104:107]
	v_mfma_f32_16x16x32_bf16 v[92:95], v[132:135], v[202:205], v[92:95]
	v_mfma_f32_16x16x32_bf16 v[88:91], v[140:143], v[202:205], v[88:91]
	v_mfma_f32_16x16x32_bf16 v[76:79], v[132:135], v[210:213], v[76:79]
	v_mfma_f32_16x16x32_bf16 v[72:75], v[140:143], v[210:213], v[72:75]
	v_mfma_f32_16x16x32_bf16 v[116:119], v[156:159], v[180:183], v[116:119]
	v_mfma_f32_16x16x32_bf16 v[112:115], v[172:175], v[180:183], v[112:115]
	v_mfma_f32_16x16x32_bf16 v[100:103], v[156:159], v[190:193], v[100:103]
	v_mfma_f32_16x16x32_bf16 v[96:99], v[172:175], v[190:193], v[96:99]
	v_mfma_f32_16x16x32_bf16 v[84:87], v[156:159], v[198:201], v[84:87]
	v_mfma_f32_16x16x32_bf16 v[80:83], v[172:175], v[198:201], v[80:83]
	v_mfma_f32_16x16x32_bf16 v[68:71], v[156:159], v[206:209], v[68:71]
	v_mfma_f32_16x16x32_bf16 v[64:67], v[172:175], v[206:209], v[64:67]
	v_mfma_f32_16x16x32_bf16 v[116:119], v[160:163], v[184:187], v[116:119]
	v_mfma_f32_16x16x32_bf16 v[112:115], v[176:179], v[184:187], v[112:115]
	v_mfma_f32_16x16x32_bf16 v[100:103], v[160:163], v[194:197], v[100:103]
	v_mfma_f32_16x16x32_bf16 v[96:99], v[176:179], v[194:197], v[96:99]
	v_mfma_f32_16x16x32_bf16 v[84:87], v[160:163], v[202:205], v[84:87]
	v_mfma_f32_16x16x32_bf16 v[80:83], v[176:179], v[202:205], v[80:83]
	v_mfma_f32_16x16x32_bf16 v[68:71], v[160:163], v[210:213], v[68:71]
	v_mfma_f32_16x16x32_bf16 v[64:67], v[176:179], v[210:213], v[64:67]
	s_setprio 0
	s_barrier
	s_add_i32 s77, s71, s57
	s_mov_b32 m0, s77
	ds_read_b128 v[180:183], v171 offset:16384
	ds_read_b128 v[184:187], v171 offset:17408
	ds_read_b128 v[190:193], v171 offset:18432
	ds_read_b128 v[194:197], v171 offset:19456
	global_load_lds_dwordx4 v150, s[78:79]
	s_add_i32 m0, s77, 0x2000
	s_mov_b64 s[100:101], s[78:79]
	s_add_i32 s77, s72, s57
	global_load_lds_dwordx4 v148, s[78:79]
	s_mov_b32 m0, s77
	s_add_u32 s78, s78, s8
	s_addc_u32 s79, s79, s9
	global_load_lds_dwordx4 v150, s[78:79]
	s_add_i32 m0, s77, 0x2000
	ds_read_b128 v[206:209], v171 offset:22528
	global_load_lds_dwordx4 v148, s[78:79]
	s_mov_b32 m0, s43
	ds_read_b128 v[202:205], v171 offset:21504
	global_load_lds_dwordx4 v144, s[48:49]
	s_mov_b32 m0, s59
	ds_read_b128 v[198:201], v171 offset:20480
	global_load_lds_dwordx4 v146, s[48:49]
	ds_read_b128 v[210:213], v171 offset:23552
	s_waitcnt vmcnt(8) lgkmcnt(0)
	s_setprio 1
	s_barrier
	v_mfma_f32_16x16x32_bf16 v[60:63], v[128:131], v[180:183], v[60:63]
	v_mfma_f32_16x16x32_bf16 v[56:59], v[136:139], v[180:183], v[56:59]
	v_mfma_f32_16x16x32_bf16 v[44:47], v[128:131], v[190:193], v[44:47]
	v_mfma_f32_16x16x32_bf16 v[40:43], v[136:139], v[190:193], v[40:43]
	v_mfma_f32_16x16x32_bf16 v[28:31], v[128:131], v[198:201], v[28:31]
	v_mfma_f32_16x16x32_bf16 v[24:27], v[136:139], v[198:201], v[24:27]
	v_mfma_f32_16x16x32_bf16 v[12:15], v[128:131], v[206:209], v[12:15]
	v_mfma_f32_16x16x32_bf16 v[8:11], v[136:139], v[206:209], v[8:11]
	v_mfma_f32_16x16x32_bf16 v[60:63], v[132:135], v[184:187], v[60:63]
	v_mfma_f32_16x16x32_bf16 v[56:59], v[140:143], v[184:187], v[56:59]
	v_mfma_f32_16x16x32_bf16 v[44:47], v[132:135], v[194:197], v[44:47]
	v_mfma_f32_16x16x32_bf16 v[40:43], v[140:143], v[194:197], v[40:43]
	v_mfma_f32_16x16x32_bf16 v[28:31], v[132:135], v[202:205], v[28:31]
	v_mfma_f32_16x16x32_bf16 v[24:27], v[140:143], v[202:205], v[24:27]
	v_mfma_f32_16x16x32_bf16 v[12:15], v[132:135], v[210:213], v[12:15]
	v_mfma_f32_16x16x32_bf16 v[8:11], v[140:143], v[210:213], v[8:11]
	v_mfma_f32_16x16x32_bf16 v[52:55], v[156:159], v[180:183], v[52:55]
	v_mfma_f32_16x16x32_bf16 v[48:51], v[172:175], v[180:183], v[48:51]
	v_mfma_f32_16x16x32_bf16 v[36:39], v[156:159], v[190:193], v[36:39]
	v_mfma_f32_16x16x32_bf16 v[32:35], v[172:175], v[190:193], v[32:35]
	v_mfma_f32_16x16x32_bf16 v[20:23], v[156:159], v[198:201], v[20:23]
	v_mfma_f32_16x16x32_bf16 v[16:19], v[172:175], v[198:201], v[16:19]
	v_mfma_f32_16x16x32_bf16 v[4:7], v[156:159], v[206:209], v[4:7]
	v_mfma_f32_16x16x32_bf16 v[0:3], v[172:175], v[206:209], v[0:3]
	v_mfma_f32_16x16x32_bf16 v[52:55], v[160:163], v[184:187], v[52:55]
	v_mfma_f32_16x16x32_bf16 v[48:51], v[176:179], v[184:187], v[48:51]
	v_mfma_f32_16x16x32_bf16 v[36:39], v[160:163], v[194:197], v[36:39]
	v_mfma_f32_16x16x32_bf16 v[32:35], v[176:179], v[194:197], v[32:35]
	v_mfma_f32_16x16x32_bf16 v[20:23], v[160:163], v[202:205], v[20:23]
	v_mfma_f32_16x16x32_bf16 v[16:19], v[176:179], v[202:205], v[16:19]
	v_mfma_f32_16x16x32_bf16 v[4:7], v[160:163], v[210:213], v[4:7]
	v_mfma_f32_16x16x32_bf16 v[0:3], v[176:179], v[210:213], v[0:3]
	s_setprio 0
	s_barrier
; #define PG8_STAGE(bufoff, gbase, voff) do { _Pragma("unroll") for (int _i = 0; _i < 2; ++_i) \
;         __builtin_amdgcn_global_load_lds((const unsigned*)((const char*)(gbase) + (voff)[_i]), (PG8_LAS unsigned*)(lds + (bufoff) + ldsw + _i * 8192), 16, 0, 0); } while (0)
; #define PG8_LDA(dst, b, h) do { _Pragma("unroll") for (int m = 0; m < 4; ++m) _Pragma("unroll") for (int k = 0; k < 2; ++k) dst[m][k] = *(const PG8_LAS bf16x8*)(lds + PG8_SA(b, h) + aoff + m * 2048 + k * 1024); } while (0)
; #define PG8_LDB(dst, b, h) do { _Pragma("unroll") for (int n = 0; n < 2; ++n) _Pragma("unroll") for (int k = 0; k < 2; ++k) dst[n][k] = *(const PG8_LAS bf16x8*)(lds + PG8_SB(b, h) + boff + n * 2048 + k * 1024); } while (0)
; #define PG8_MMA(ai, bj, At, Bt) do { __builtin_amdgcn_s_setprio(1); _Pragma("unroll") for (int m = 0; m < 4; ++m) _Pragma("unroll") for (int n = 0; n < 2; ++n) _Pragma("unroll") for (int k = 0; k < 2; ++k) \
;         acc[ai][bj][m][n] = __builtin_amdgcn_mfma_f32_16x16x32_bf16(Bt[n][k], At[m][k], acc[ai][bj][m][n], 0, 0, 0); __builtin_amdgcn_s_setprio(0); } while (0)
; #define PG8_WAIT_V(n) asm volatile("s_waitcnt vmcnt(" #n ")" ::: "memory")
; #define PG8_WAIT_L(n) asm volatile("s_waitcnt lgkmcnt(" #n ")" ::: "memory")
; #define PG8_BAR __builtin_amdgcn_s_barrier()
; #define PG8_SCHED __builtin_amdgcn_sched_barrier(0)
; template <class Epi, class Sched, bool ALIGN_EPI = false, bool SP2 = false>
; __device__ __forceinline__ void gemm_phase(PG8_LAS unsigned char* lds, const Gemm g, const Sched& S, const Epi& E) {
;     ...
;             PG8_LDB(B0, 1, 0); PG8_LDB(B1, 1, 1); PG8_SCHED; PG8_LDA(At, 1, 0); PG8_STAGE(PG8_SA(0, 1), a2 + hstepA, voffA);
;             PG8_WAIT_V(8); PG8_WAIT_L(0); PG8_BAR; PG8_MMA(0, 0, At, B0); PG8_MMA(0, 1, At, B1); PG8_BAR; PG8_SCHED;
;             PG8_LDA(At, 1, 1); PG8_STAGE(PG8_SB(1, 0), b3, voffB); PG8_STAGE(PG8_SB(1, 1), b3 + hstep, voffB); PG8_STAGE(PG8_SA(1, 0), a3, voffA);
;             PG8_WAIT_V(8); PG8_WAIT_L(0); PG8_BAR; PG8_MMA(1, 0, At, B0); PG8_MMA(1, 1, At, B1); PG8_BAR; PG8_SCHED;
	s_add_i32 s77, 0, 0x18000
	s_add_i32 s78, 0, 0x1c000
	v_add_u32_e32 v140, s77, v167
	v_add_u32_e32 v176, s78, v167
	ds_read_b128 v[128:131], v140
	ds_read_b128 v[132:135], v140 offset:1024
	ds_read_b128 v[136:139], v140 offset:2048
	ds_read_b128 v[140:143], v140 offset:3072
	ds_read_b128 v[156:159], v176
	ds_read_b128 v[160:163], v176 offset:1024
	ds_read_b128 v[172:175], v176 offset:2048
	ds_read_b128 v[176:179], v176 offset:3072
	s_mov_b64 vcc, s[48:49]
	s_add_u32 s48, s48, 0x40000
	s_addc_u32 s49, s49, 0
	s_mov_b32 m0, s60
	ds_read_b128 v[180:183], v171 offset:32768
	ds_read_b128 v[184:187], v171 offset:33792
	ds_read_b128 v[190:193], v171 offset:34816
	ds_read_b128 v[194:197], v171 offset:35840
	ds_read_b128 v[198:201], v171 offset:36864
	ds_read_b128 v[202:205], v171 offset:37888
	ds_read_b128 v[206:209], v171 offset:38912
	global_load_lds_dwordx4 v144, s[48:49]
	s_mov_b32 m0, s61
	ds_read_b128 v[210:213], v171 offset:39936
	global_load_lds_dwordx4 v146, s[48:49]
	s_waitcnt vmcnt(8) lgkmcnt(0)
	s_setprio 1
	s_barrier
	v_mfma_f32_16x16x32_bf16 v[124:127], v[128:131], v[180:183], v[124:127]
	v_mfma_f32_16x16x32_bf16 v[120:123], v[136:139], v[180:183], v[120:123]
	v_mfma_f32_16x16x32_bf16 v[108:111], v[128:131], v[190:193], v[108:111]
	v_mfma_f32_16x16x32_bf16 v[104:107], v[136:139], v[190:193], v[104:107]
	v_mfma_f32_16x16x32_bf16 v[92:95], v[128:131], v[198:201], v[92:95]
	v_mfma_f32_16x16x32_bf16 v[88:91], v[136:139], v[198:201], v[88:91]
	v_mfma_f32_16x16x32_bf16 v[76:79], v[128:131], v[206:209], v[76:79]
	v_mfma_f32_16x16x32_bf16 v[72:75], v[136:139], v[206:209], v[72:75]
	v_mfma_f32_16x16x32_bf16 v[124:127], v[132:135], v[184:187], v[124:127]
	v_mfma_f32_16x16x32_bf16 v[120:123], v[140:143], v[184:187], v[120:123]
	v_mfma_f32_16x16x32_bf16 v[108:111], v[132:135], v[194:197], v[108:111]
	v_mfma_f32_16x16x32_bf16 v[104:107], v[140:143], v[194:197], v[104:107]
	v_mfma_f32_16x16x32_bf16 v[92:95], v[132:135], v[202:205], v[92:95]
	v_mfma_f32_16x16x32_bf16 v[88:91], v[140:143], v[202:205], v[88:91]
	v_mfma_f32_16x16x32_bf16 v[76:79], v[132:135], v[210:213], v[76:79]
	v_mfma_f32_16x16x32_bf16 v[72:75], v[140:143], v[210:213], v[72:75]
	v_mfma_f32_16x16x32_bf16 v[116:119], v[156:159], v[180:183], v[116:119]
	v_mfma_f32_16x16x32_bf16 v[112:115], v[172:175], v[180:183], v[112:115]
	v_mfma_f32_16x16x32_bf16 v[100:103], v[156:159], v[190:193], v[100:103]
	v_mfma_f32_16x16x32_bf16 v[96:99], v[172:175], v[190:193], v[96:99]
	v_mfma_f32_16x16x32_bf16 v[84:87], v[156:159], v[198:201], v[84:87]
	v_mfma_f32_16x16x32_bf16 v[80:83], v[172:175], v[198:201], v[80:83]
	v_mfma_f32_16x16x32_bf16 v[68:71], v[156:159], v[206:209], v[68:71]
	v_mfma_f32_16x16x32_bf16 v[64:67], v[172:175], v[206:209], v[64:67]
	v_mfma_f32_16x16x32_bf16 v[116:119], v[160:163], v[184:187], v[116:119]
	v_mfma_f32_16x16x32_bf16 v[112:115], v[176:179], v[184:187], v[112:115]
	v_mfma_f32_16x16x32_bf16 v[100:103], v[160:163], v[194:197], v[100:103]
	v_mfma_f32_16x16x32_bf16 v[96:99], v[176:179], v[194:197], v[96:99]
	v_mfma_f32_16x16x32_bf16 v[84:87], v[160:163], v[202:205], v[84:87]
	v_mfma_f32_16x16x32_bf16 v[80:83], v[176:179], v[202:205], v[80:83]
	v_mfma_f32_16x16x32_bf16 v[68:71], v[160:163], v[210:213], v[68:71]
	v_mfma_f32_16x16x32_bf16 v[64:67], v[176:179], v[210:213], v[64:67]
	s_setprio 0
	s_barrier
	s_add_i32 s48, s77, s57
	s_add_i32 m0, s48, 0xffffff80
	ds_read_b128 v[180:183], v171 offset:49152
	ds_read_b128 v[184:187], v171 offset:50176
	ds_read_b128 v[190:193], v171 offset:51200
	ds_read_b128 v[194:197], v171 offset:52224
	global_load_lds_dwordx4 v150, s[100:101] offset:128
	s_add_i32 m0, s48, 0x1f80
	s_add_i32 s48, s78, s57
	global_load_lds_dwordx4 v148, s[100:101] offset:128
	s_add_i32 m0, s48, 0xffffff80
	s_add_u32 s100, s100, s8
	s_addc_u32 s101, s101, s9
	global_load_lds_dwordx4 v150, s[100:101] offset:128
	s_add_i32 m0, s48, 0x1f80
	ds_read_b128 v[206:209], v171 offset:55296
	global_load_lds_dwordx4 v148, s[100:101] offset:128
	s_add_i32 m0, s65, 0xffffff80
	ds_read_b128 v[202:205], v171 offset:54272
	global_load_lds_dwordx4 v144, vcc offset:128
	s_add_i32 m0, s66, 0xffffff80
	ds_read_b128 v[198:201], v171 offset:53248
	global_load_lds_dwordx4 v146, vcc offset:128
	ds_read_b128 v[210:213], v171 offset:56320
	s_waitcnt vmcnt(8) lgkmcnt(0)
	s_setprio 1
	s_barrier
	v_mfma_f32_16x16x32_bf16 v[60:63], v[128:131], v[180:183], v[60:63]
	v_mfma_f32_16x16x32_bf16 v[56:59], v[136:139], v[180:183], v[56:59]
	v_mfma_f32_16x16x32_bf16 v[44:47], v[128:131], v[190:193], v[44:47]
	v_mfma_f32_16x16x32_bf16 v[40:43], v[136:139], v[190:193], v[40:43]
	v_mfma_f32_16x16x32_bf16 v[28:31], v[128:131], v[198:201], v[28:31]
	v_mfma_f32_16x16x32_bf16 v[24:27], v[136:139], v[198:201], v[24:27]
	v_mfma_f32_16x16x32_bf16 v[12:15], v[128:131], v[206:209], v[12:15]
	v_mfma_f32_16x16x32_bf16 v[8:11], v[136:139], v[206:209], v[8:11]
	v_mfma_f32_16x16x32_bf16 v[60:63], v[132:135], v[184:187], v[60:63]
	v_mfma_f32_16x16x32_bf16 v[56:59], v[140:143], v[184:187], v[56:59]
	v_mfma_f32_16x16x32_bf16 v[44:47], v[132:135], v[194:197], v[44:47]
	v_mfma_f32_16x16x32_bf16 v[40:43], v[140:143], v[194:197], v[40:43]
	v_mfma_f32_16x16x32_bf16 v[28:31], v[132:135], v[202:205], v[28:31]
	v_mfma_f32_16x16x32_bf16 v[24:27], v[140:143], v[202:205], v[24:27]
	v_mfma_f32_16x16x32_bf16 v[12:15], v[132:135], v[210:213], v[12:15]
	v_mfma_f32_16x16x32_bf16 v[8:11], v[140:143], v[210:213], v[8:11]
	v_mfma_f32_16x16x32_bf16 v[52:55], v[156:159], v[180:183], v[52:55]
	v_mfma_f32_16x16x32_bf16 v[48:51], v[172:175], v[180:183], v[48:51]
	v_mfma_f32_16x16x32_bf16 v[36:39], v[156:159], v[190:193], v[36:39]
	v_mfma_f32_16x16x32_bf16 v[32:35], v[172:175], v[190:193], v[32:35]
	v_mfma_f32_16x16x32_bf16 v[20:23], v[156:159], v[198:201], v[20:23]
	v_mfma_f32_16x16x32_bf16 v[16:19], v[172:175], v[198:201], v[16:19]
	v_mfma_f32_16x16x32_bf16 v[4:7], v[156:159], v[206:209], v[4:7]
	v_mfma_f32_16x16x32_bf16 v[0:3], v[172:175], v[206:209], v[0:3]
	v_mfma_f32_16x16x32_bf16 v[52:55], v[160:163], v[184:187], v[52:55]
	v_mfma_f32_16x16x32_bf16 v[48:51], v[176:179], v[184:187], v[48:51]
	v_mfma_f32_16x16x32_bf16 v[36:39], v[160:163], v[194:197], v[36:39]
	v_mfma_f32_16x16x32_bf16 v[32:35], v[176:179], v[194:197], v[32:35]
	v_mfma_f32_16x16x32_bf16 v[20:23], v[160:163], v[202:205], v[20:23]
	v_mfma_f32_16x16x32_bf16 v[16:19], v[176:179], v[202:205], v[16:19]
	v_mfma_f32_16x16x32_bf16 v[4:7], v[160:163], v[210:213], v[4:7]
	v_mfma_f32_16x16x32_bf16 v[0:3], v[176:179], v[210:213], v[0:3]
	s_setprio 0
	s_barrier
	s_add_u32 s44, s44, 0x100
	s_addc_u32 s45, s45, 0
	s_add_u32 s51, s51, 0x100
	s_addc_u32 s75, s75, 0
	s_cmp_ge_i32 s76, s67
	s_mov_b32 s48, s76
	s_cbranch_scc0 .LBB0_762

; #define PG8_STAGE(bufoff, gbase, voff) do { _Pragma("unroll") for (int _i = 0; _i < 2; ++_i) \
;         __builtin_amdgcn_global_load_lds((const unsigned*)((const char*)(gbase) + (voff)[_i]), (PG8_LAS unsigned*)(lds + (bufoff) + ldsw + _i * 8192), 16, 0, 0); } while (0)
; #define PG8_LDA(dst, b, h) do { _Pragma("unroll") for (int m = 0; m < 4; ++m) _Pragma("unroll") for (int k = 0; k < 2; ++k) dst[m][k] = *(const PG8_LAS bf16x8*)(lds + PG8_SA(b, h) + aoff + m * 2048 + k * 1024); } while (0)
; #define PG8_LDB(dst, b, h) do { _Pragma("unroll") for (int n = 0; n < 2; ++n) _Pragma("unroll") for (int k = 0; k < 2; ++k) dst[n][k] = *(const PG8_LAS bf16x8*)(lds + PG8_SB(b, h) + boff + n * 2048 + k * 1024); } while (0)
; #define PG8_WAIT_V(n) asm volatile("s_waitcnt vmcnt(" #n ")" ::: "memory")
; #define PG8_WAIT_L(n) asm volatile("s_waitcnt lgkmcnt(" #n ")" ::: "memory")
; #define PG8_BAR __builtin_amdgcn_s_barrier()
; #define PG8_SCHED __builtin_amdgcn_sched_barrier(0)
; template <class Epi, class Sched, bool ALIGN_EPI = false, bool SP2 = false>
; __device__ __forceinline__ void gemm_phase(PG8_LAS unsigned char* lds, const Gemm g, const Sched& S, const Epi& E) {
;     ...
;         const char* nA = has_next ? (const char*)g.A + (size_t)nxt.pm * tstepA : cA; const char* nB = has_next ? (const char*)g.Bt + (size_t)nxt.pn * tstep : cB;
;         for (int t = 0; t < nt; t += 2) {
;             const bool last = (t == nt - 2);
;             const char* a1 = cA + (size_t)(t + 1) * kstep;
;             const char* a2 = last ? nA : cA + (size_t)(t + 2) * kstep; const char* b2 = last ? nB : cB + (size_t)(t + 2) * kstep;
;             const char* a3 = a2 + kstep; const char* b3 = b2 + kstep;
;             if (last && has_next) S.a_ready(nxt);
;             if constexpr (SP2) {
;             PG8_LDB(B0, 0, 0); PG8_LDB(B1, 0, 1); PG8_SCHED; PG8_LDA(At, 0, 0); PG8_STAGE(PG8_SA(1, 1), a1 + hstepA, voffA);
;             PG8_WAIT_V(8); PG8_WAIT_L(0); PG8_BAR; PG8_MMA(0, 0, At, B0); PG8_MMA(0, 1, At, B1); PG8_BAR; PG8_SCHED;
;             PG8_LDA(At, 0, 1); PG8_STAGE(PG8_SB(0, 0), b2, voffB); PG8_STAGE(PG8_SB(0, 1), b2 + hstep, voffB); PG8_STAGE(PG8_SA(0, 0), a2, voffA);
;             PG8_WAIT_V(8); PG8_WAIT_L(0); PG8_BAR; PG8_MMA(1, 0, At, B0); PG8_MMA(1, 1, At, B1); PG8_BAR; PG8_SCHED;
.LBB0_898:
	ds_read_b128 v[150:153], v147
	ds_read_b128 v[154:157], v147 offset:1024
	ds_read_b128 v[158:161], v147 offset:2048
	ds_read_b128 v[162:165], v147 offset:3072
	ds_read_b128 v[166:169], v148
	ds_read_b128 v[170:173], v148 offset:1024
	ds_read_b128 v[174:177], v148 offset:2048
	ds_read_b128 v[178:181], v148 offset:3072
	s_add_i32 s58, s30, 2
	s_add_u32 s59, s10, 0xfffc0080
	s_addc_u32 s31, s11, -1
	s_cmp_eq_u32 s51, s30
	s_cselect_b32 s30, s57, s59
	s_cselect_b32 s31, s23, s31
	s_cselect_b32 s61, s25, s35
	s_cselect_b32 s60, s24, s34
	s_add_i32 m0, s29, 0xc000
	ds_read_b128 v[182:185], v149
	ds_read_b128 v[190:193], v149 offset:1024
	ds_read_b128 v[194:197], v149 offset:2048
	ds_read_b128 v[198:201], v149 offset:3072
	ds_read_b128 v[202:205], v149 offset:4096
	ds_read_b128 v[206:209], v149 offset:5120
	ds_read_b128 v[210:213], v149 offset:6144
	global_load_lds_dwordx4 v136, s[10:11]
	s_add_i32 m0, s29, 0xe000
	ds_read_b128 v[214:217], v149 offset:7168
	global_load_lds_dwordx4 v138, s[10:11]
	s_waitcnt vmcnt(8) lgkmcnt(0)
	s_setprio 1
	s_barrier
	v_mfma_f32_16x16x32_bf16 v[124:127], v[150:153], v[182:185], v[124:127]
	v_mfma_f32_16x16x32_bf16 v[116:119], v[158:161], v[182:185], v[116:119]
	v_mfma_f32_16x16x32_bf16 v[108:111], v[150:153], v[194:197], v[108:111]
	v_mfma_f32_16x16x32_bf16 v[100:103], v[158:161], v[194:197], v[100:103]
	v_mfma_f32_16x16x32_bf16 v[92:95], v[150:153], v[202:205], v[92:95]
	v_mfma_f32_16x16x32_bf16 v[84:87], v[158:161], v[202:205], v[84:87]
	v_mfma_f32_16x16x32_bf16 v[76:79], v[150:153], v[210:213], v[76:79]
	v_mfma_f32_16x16x32_bf16 v[68:71], v[158:161], v[210:213], v[68:71]
	v_mfma_f32_16x16x32_bf16 v[124:127], v[154:157], v[190:193], v[124:127]
	v_mfma_f32_16x16x32_bf16 v[116:119], v[162:165], v[190:193], v[116:119]
	v_mfma_f32_16x16x32_bf16 v[108:111], v[154:157], v[198:201], v[108:111]
	v_mfma_f32_16x16x32_bf16 v[100:103], v[162:165], v[198:201], v[100:103]
	v_mfma_f32_16x16x32_bf16 v[92:95], v[154:157], v[206:209], v[92:95]
	v_mfma_f32_16x16x32_bf16 v[84:87], v[162:165], v[206:209], v[84:87]
	v_mfma_f32_16x16x32_bf16 v[76:79], v[154:157], v[214:217], v[76:79]
	v_mfma_f32_16x16x32_bf16 v[68:71], v[162:165], v[214:217], v[68:71]
	v_mfma_f32_16x16x32_bf16 v[120:123], v[166:169], v[182:185], v[120:123]
	v_mfma_f32_16x16x32_bf16 v[112:115], v[174:177], v[182:185], v[112:115]
	v_mfma_f32_16x16x32_bf16 v[104:107], v[166:169], v[194:197], v[104:107]
	v_mfma_f32_16x16x32_bf16 v[96:99], v[174:177], v[194:197], v[96:99]
	v_mfma_f32_16x16x32_bf16 v[88:91], v[166:169], v[202:205], v[88:91]
	v_mfma_f32_16x16x32_bf16 v[80:83], v[174:177], v[202:205], v[80:83]
	v_mfma_f32_16x16x32_bf16 v[72:75], v[166:169], v[210:213], v[72:75]
	v_mfma_f32_16x16x32_bf16 v[64:67], v[174:177], v[210:213], v[64:67]
	v_mfma_f32_16x16x32_bf16 v[120:123], v[170:173], v[190:193], v[120:123]
	v_mfma_f32_16x16x32_bf16 v[112:115], v[178:181], v[190:193], v[112:115]
	v_mfma_f32_16x16x32_bf16 v[104:107], v[170:173], v[198:201], v[104:107]
	v_mfma_f32_16x16x32_bf16 v[96:99], v[178:181], v[198:201], v[96:99]
	v_mfma_f32_16x16x32_bf16 v[88:91], v[170:173], v[206:209], v[88:91]
	v_mfma_f32_16x16x32_bf16 v[80:83], v[178:181], v[206:209], v[80:83]
	v_mfma_f32_16x16x32_bf16 v[72:75], v[170:173], v[214:217], v[72:75]
	v_mfma_f32_16x16x32_bf16 v[64:67], v[178:181], v[214:217], v[64:67]
	s_setprio 0
	s_barrier
	s_add_i32 s59, s52, s38
	s_mov_b32 m0, s59
	ds_read_b128 v[182:185], v149 offset:16384
	ds_read_b128 v[190:193], v149 offset:17408
	ds_read_b128 v[194:197], v149 offset:18432
	ds_read_b128 v[198:201], v149 offset:19456
	global_load_lds_dwordx4 v134, s[60:61]
	s_add_i32 m0, s59, 0x2000
	s_mov_b64 s[100:101], s[60:61]
	s_add_i32 s59, s53, s38
	global_load_lds_dwordx4 v132, s[60:61]
	s_mov_b32 m0, s59
	s_add_u32 s60, s60, s4
	s_addc_u32 s61, s61, s5
	global_load_lds_dwordx4 v134, s[60:61]
	s_add_i32 m0, s59, 0x2000
	ds_read_b128 v[210:213], v149 offset:22528
	global_load_lds_dwordx4 v132, s[60:61]
	s_mov_b32 m0, s29
	ds_read_b128 v[206:209], v149 offset:21504
	global_load_lds_dwordx4 v128, s[30:31]
	s_mov_b32 m0, s41
	ds_read_b128 v[202:205], v149 offset:20480
	global_load_lds_dwordx4 v130, s[30:31]
	ds_read_b128 v[214:217], v149 offset:23552
	s_waitcnt vmcnt(8) lgkmcnt(0)
	s_setprio 1
	s_barrier
	v_mfma_f32_16x16x32_bf16 v[60:63], v[150:153], v[182:185], v[60:63]
	v_mfma_f32_16x16x32_bf16 v[52:55], v[158:161], v[182:185], v[52:55]
	v_mfma_f32_16x16x32_bf16 v[44:47], v[150:153], v[194:197], v[44:47]
	v_mfma_f32_16x16x32_bf16 v[36:39], v[158:161], v[194:197], v[36:39]
	v_mfma_f32_16x16x32_bf16 v[28:31], v[150:153], v[202:205], v[28:31]
	v_mfma_f32_16x16x32_bf16 v[20:23], v[158:161], v[202:205], v[20:23]
	v_mfma_f32_16x16x32_bf16 v[12:15], v[150:153], v[210:213], v[12:15]
	v_mfma_f32_16x16x32_bf16 v[4:7], v[158:161], v[210:213], v[4:7]
	v_mfma_f32_16x16x32_bf16 v[60:63], v[154:157], v[190:193], v[60:63]
	v_mfma_f32_16x16x32_bf16 v[52:55], v[162:165], v[190:193], v[52:55]
	v_mfma_f32_16x16x32_bf16 v[44:47], v[154:157], v[198:201], v[44:47]
	v_mfma_f32_16x16x32_bf16 v[36:39], v[162:165], v[198:201], v[36:39]
	v_mfma_f32_16x16x32_bf16 v[28:31], v[154:157], v[206:209], v[28:31]
	v_mfma_f32_16x16x32_bf16 v[20:23], v[162:165], v[206:209], v[20:23]
	v_mfma_f32_16x16x32_bf16 v[12:15], v[154:157], v[214:217], v[12:15]
	v_mfma_f32_16x16x32_bf16 v[4:7], v[162:165], v[214:217], v[4:7]
	v_mfma_f32_16x16x32_bf16 v[56:59], v[166:169], v[182:185], v[56:59]
	v_mfma_f32_16x16x32_bf16 v[48:51], v[174:177], v[182:185], v[48:51]
	v_mfma_f32_16x16x32_bf16 v[40:43], v[166:169], v[194:197], v[40:43]
	v_mfma_f32_16x16x32_bf16 v[32:35], v[174:177], v[194:197], v[32:35]
	v_mfma_f32_16x16x32_bf16 v[24:27], v[166:169], v[202:205], v[24:27]
	v_mfma_f32_16x16x32_bf16 v[16:19], v[174:177], v[202:205], v[16:19]
	v_mfma_f32_16x16x32_bf16 v[8:11], v[166:169], v[210:213], v[8:11]
	v_mfma_f32_16x16x32_bf16 v[0:3], v[174:177], v[210:213], v[0:3]
	v_mfma_f32_16x16x32_bf16 v[56:59], v[170:173], v[190:193], v[56:59]
	v_mfma_f32_16x16x32_bf16 v[48:51], v[178:181], v[190:193], v[48:51]
	v_mfma_f32_16x16x32_bf16 v[40:43], v[170:173], v[198:201], v[40:43]
	v_mfma_f32_16x16x32_bf16 v[32:35], v[178:181], v[198:201], v[32:35]
	v_mfma_f32_16x16x32_bf16 v[24:27], v[170:173], v[206:209], v[24:27]
	v_mfma_f32_16x16x32_bf16 v[16:19], v[178:181], v[206:209], v[16:19]
	v_mfma_f32_16x16x32_bf16 v[8:11], v[170:173], v[214:217], v[8:11]
	v_mfma_f32_16x16x32_bf16 v[0:3], v[178:181], v[214:217], v[0:3]
	s_setprio 0
	s_barrier
; #define PG8_STAGE(bufoff, gbase, voff) do { _Pragma("unroll") for (int _i = 0; _i < 2; ++_i) \
;         __builtin_amdgcn_global_load_lds((const unsigned*)((const char*)(gbase) + (voff)[_i]), (PG8_LAS unsigned*)(lds + (bufoff) + ldsw + _i * 8192), 16, 0, 0); } while (0)
; #define PG8_LDA(dst, b, h) do { _Pragma("unroll") for (int m = 0; m < 4; ++m) _Pragma("unroll") for (int k = 0; k < 2; ++k) dst[m][k] = *(const PG8_LAS bf16x8*)(lds + PG8_SA(b, h) + aoff + m * 2048 + k * 1024); } while (0)
; #define PG8_LDB(dst, b, h) do { _Pragma("unroll") for (int n = 0; n < 2; ++n) _Pragma("unroll") for (int k = 0; k < 2; ++k) dst[n][k] = *(const PG8_LAS bf16x8*)(lds + PG8_SB(b, h) + boff + n * 2048 + k * 1024); } while (0)
; #define PG8_MMA(ai, bj, At, Bt) do { __builtin_amdgcn_s_setprio(1); _Pragma("unroll") for (int m = 0; m < 4; ++m) _Pragma("unroll") for (int n = 0; n < 2; ++n) _Pragma("unroll") for (int k = 0; k < 2; ++k) \
;         acc[ai][bj][m][n] = __builtin_amdgcn_mfma_f32_16x16x32_bf16(Bt[n][k], At[m][k], acc[ai][bj][m][n], 0, 0, 0); __builtin_amdgcn_s_setprio(0); } while (0)
; #define PG8_WAIT_V(n) asm volatile("s_waitcnt vmcnt(" #n ")" ::: "memory")
; #define PG8_WAIT_L(n) asm volatile("s_waitcnt lgkmcnt(" #n ")" ::: "memory")
; #define PG8_BAR __builtin_amdgcn_s_barrier()
; #define PG8_SCHED __builtin_amdgcn_sched_barrier(0)
; template <class Epi, class Sched, bool ALIGN_EPI = false, bool SP2 = false>
; __device__ __forceinline__ void gemm_phase(PG8_LAS unsigned char* lds, const Gemm g, const Sched& S, const Epi& E) {
;     ...
;             PG8_LDB(B0, 1, 0); PG8_LDB(B1, 1, 1); PG8_SCHED; PG8_LDA(At, 1, 0); PG8_STAGE(PG8_SA(0, 1), a2 + hstepA, voffA);
;             PG8_WAIT_V(8); PG8_WAIT_L(0); PG8_BAR; PG8_MMA(0, 0, At, B0); PG8_MMA(0, 1, At, B1); PG8_BAR; PG8_SCHED;
;             PG8_LDA(At, 1, 1); PG8_STAGE(PG8_SB(1, 0), b3, voffB); PG8_STAGE(PG8_SB(1, 1), b3 + hstep, voffB); PG8_STAGE(PG8_SA(1, 0), a3, voffA);
;             PG8_WAIT_V(8); PG8_WAIT_L(0); PG8_BAR; PG8_MMA(1, 0, At, B0); PG8_MMA(1, 1, At, B1); PG8_BAR; PG8_SCHED;
	s_add_i32 s59, 0, 0x18000
	s_add_i32 s60, 0, 0x1c000
	v_add_u32_e32 v162, s59, v145
	v_add_u32_e32 v178, s60, v145
	ds_read_b128 v[150:153], v162
	ds_read_b128 v[154:157], v162 offset:1024
	ds_read_b128 v[158:161], v162 offset:2048
	ds_read_b128 v[162:165], v162 offset:3072
	ds_read_b128 v[166:169], v178
	ds_read_b128 v[170:173], v178 offset:1024
	ds_read_b128 v[174:177], v178 offset:2048
	ds_read_b128 v[178:181], v178 offset:3072
	s_mov_b64 vcc, s[30:31]
	s_add_u32 s30, s30, 0x40000
	s_addc_u32 s31, s31, 0
	s_mov_b32 m0, s42
	ds_read_b128 v[182:185], v149 offset:32768
	ds_read_b128 v[190:193], v149 offset:33792
	ds_read_b128 v[194:197], v149 offset:34816
	ds_read_b128 v[198:201], v149 offset:35840
	ds_read_b128 v[202:205], v149 offset:36864
	ds_read_b128 v[206:209], v149 offset:37888
	ds_read_b128 v[210:213], v149 offset:38912
	global_load_lds_dwordx4 v128, s[30:31]
	s_mov_b32 m0, s43
	ds_read_b128 v[214:217], v149 offset:39936
	global_load_lds_dwordx4 v130, s[30:31]
	s_waitcnt vmcnt(8) lgkmcnt(0)
	s_setprio 1
	s_barrier
	v_mfma_f32_16x16x32_bf16 v[124:127], v[150:153], v[182:185], v[124:127]
	v_mfma_f32_16x16x32_bf16 v[116:119], v[158:161], v[182:185], v[116:119]
	v_mfma_f32_16x16x32_bf16 v[108:111], v[150:153], v[194:197], v[108:111]
	v_mfma_f32_16x16x32_bf16 v[100:103], v[158:161], v[194:197], v[100:103]
	v_mfma_f32_16x16x32_bf16 v[92:95], v[150:153], v[202:205], v[92:95]
	v_mfma_f32_16x16x32_bf16 v[84:87], v[158:161], v[202:205], v[84:87]
	v_mfma_f32_16x16x32_bf16 v[76:79], v[150:153], v[210:213], v[76:79]
	v_mfma_f32_16x16x32_bf16 v[68:71], v[158:161], v[210:213], v[68:71]
	v_mfma_f32_16x16x32_bf16 v[124:127], v[154:157], v[190:193], v[124:127]
	v_mfma_f32_16x16x32_bf16 v[116:119], v[162:165], v[190:193], v[116:119]
	v_mfma_f32_16x16x32_bf16 v[108:111], v[154:157], v[198:201], v[108:111]
	v_mfma_f32_16x16x32_bf16 v[100:103], v[162:165], v[198:201], v[100:103]
	v_mfma_f32_16x16x32_bf16 v[92:95], v[154:157], v[206:209], v[92:95]
	v_mfma_f32_16x16x32_bf16 v[84:87], v[162:165], v[206:209], v[84:87]
	v_mfma_f32_16x16x32_bf16 v[76:79], v[154:157], v[214:217], v[76:79]
	v_mfma_f32_16x16x32_bf16 v[68:71], v[162:165], v[214:217], v[68:71]
	v_mfma_f32_16x16x32_bf16 v[120:123], v[166:169], v[182:185], v[120:123]
	v_mfma_f32_16x16x32_bf16 v[112:115], v[174:177], v[182:185], v[112:115]
	v_mfma_f32_16x16x32_bf16 v[104:107], v[166:169], v[194:197], v[104:107]
	v_mfma_f32_16x16x32_bf16 v[96:99], v[174:177], v[194:197], v[96:99]
	v_mfma_f32_16x16x32_bf16 v[88:91], v[166:169], v[202:205], v[88:91]
	v_mfma_f32_16x16x32_bf16 v[80:83], v[174:177], v[202:205], v[80:83]
	v_mfma_f32_16x16x32_bf16 v[72:75], v[166:169], v[210:213], v[72:75]
	v_mfma_f32_16x16x32_bf16 v[64:67], v[174:177], v[210:213], v[64:67]
	v_mfma_f32_16x16x32_bf16 v[120:123], v[170:173], v[190:193], v[120:123]
	v_mfma_f32_16x16x32_bf16 v[112:115], v[178:181], v[190:193], v[112:115]
	v_mfma_f32_16x16x32_bf16 v[104:107], v[170:173], v[198:201], v[104:107]
	v_mfma_f32_16x16x32_bf16 v[96:99], v[178:181], v[198:201], v[96:99]
	v_mfma_f32_16x16x32_bf16 v[88:91], v[170:173], v[206:209], v[88:91]
	v_mfma_f32_16x16x32_bf16 v[80:83], v[178:181], v[206:209], v[80:83]
	v_mfma_f32_16x16x32_bf16 v[72:75], v[170:173], v[214:217], v[72:75]
	v_mfma_f32_16x16x32_bf16 v[64:67], v[178:181], v[214:217], v[64:67]
	s_setprio 0
	s_barrier
	s_add_i32 s30, s59, s38
	s_add_i32 m0, s30, 0xffffff80
	ds_read_b128 v[182:185], v149 offset:49152
	ds_read_b128 v[190:193], v149 offset:50176
	ds_read_b128 v[194:197], v149 offset:51200
	ds_read_b128 v[198:201], v149 offset:52224
	global_load_lds_dwordx4 v134, s[100:101] offset:128
	s_add_i32 m0, s30, 0x1f80
	s_add_i32 s30, s60, s38
	global_load_lds_dwordx4 v132, s[100:101] offset:128
	s_add_i32 m0, s30, 0xffffff80
	s_add_u32 s100, s100, s4
	s_addc_u32 s101, s101, s5
	global_load_lds_dwordx4 v134, s[100:101] offset:128
	s_add_i32 m0, s30, 0x1f80
	ds_read_b128 v[210:213], v149 offset:55296
	global_load_lds_dwordx4 v132, s[100:101] offset:128
	s_add_i32 m0, s47, 0xffffff80
	ds_read_b128 v[206:209], v149 offset:54272
	global_load_lds_dwordx4 v128, vcc offset:128
	s_add_i32 m0, s48, 0xffffff80
	ds_read_b128 v[202:205], v149 offset:53248
	global_load_lds_dwordx4 v130, vcc offset:128
	ds_read_b128 v[214:217], v149 offset:56320
	s_waitcnt vmcnt(8) lgkmcnt(0)
	s_setprio 1
	s_barrier
	v_mfma_f32_16x16x32_bf16 v[60:63], v[150:153], v[182:185], v[60:63]
	v_mfma_f32_16x16x32_bf16 v[52:55], v[158:161], v[182:185], v[52:55]
	v_mfma_f32_16x16x32_bf16 v[44:47], v[150:153], v[194:197], v[44:47]
	v_mfma_f32_16x16x32_bf16 v[36:39], v[158:161], v[194:197], v[36:39]
	v_mfma_f32_16x16x32_bf16 v[28:31], v[150:153], v[202:205], v[28:31]
	v_mfma_f32_16x16x32_bf16 v[20:23], v[158:161], v[202:205], v[20:23]
	v_mfma_f32_16x16x32_bf16 v[12:15], v[150:153], v[210:213], v[12:15]
	v_mfma_f32_16x16x32_bf16 v[4:7], v[158:161], v[210:213], v[4:7]
	v_mfma_f32_16x16x32_bf16 v[60:63], v[154:157], v[190:193], v[60:63]
	v_mfma_f32_16x16x32_bf16 v[52:55], v[162:165], v[190:193], v[52:55]
	v_mfma_f32_16x16x32_bf16 v[44:47], v[154:157], v[198:201], v[44:47]
	v_mfma_f32_16x16x32_bf16 v[36:39], v[162:165], v[198:201], v[36:39]
	v_mfma_f32_16x16x32_bf16 v[28:31], v[154:157], v[206:209], v[28:31]
	v_mfma_f32_16x16x32_bf16 v[20:23], v[162:165], v[206:209], v[20:23]
	v_mfma_f32_16x16x32_bf16 v[12:15], v[154:157], v[214:217], v[12:15]
	v_mfma_f32_16x16x32_bf16 v[4:7], v[162:165], v[214:217], v[4:7]
	v_mfma_f32_16x16x32_bf16 v[56:59], v[166:169], v[182:185], v[56:59]
	v_mfma_f32_16x16x32_bf16 v[48:51], v[174:177], v[182:185], v[48:51]
	v_mfma_f32_16x16x32_bf16 v[40:43], v[166:169], v[194:197], v[40:43]
	v_mfma_f32_16x16x32_bf16 v[32:35], v[174:177], v[194:197], v[32:35]
	v_mfma_f32_16x16x32_bf16 v[24:27], v[166:169], v[202:205], v[24:27]
	v_mfma_f32_16x16x32_bf16 v[16:19], v[174:177], v[202:205], v[16:19]
	v_mfma_f32_16x16x32_bf16 v[8:11], v[166:169], v[210:213], v[8:11]
	v_mfma_f32_16x16x32_bf16 v[0:3], v[174:177], v[210:213], v[0:3]
	v_mfma_f32_16x16x32_bf16 v[56:59], v[170:173], v[190:193], v[56:59]
	v_mfma_f32_16x16x32_bf16 v[48:51], v[178:181], v[190:193], v[48:51]
	v_mfma_f32_16x16x32_bf16 v[40:43], v[170:173], v[198:201], v[40:43]
	v_mfma_f32_16x16x32_bf16 v[32:35], v[178:181], v[198:201], v[32:35]
	v_mfma_f32_16x16x32_bf16 v[24:27], v[170:173], v[206:209], v[24:27]
	v_mfma_f32_16x16x32_bf16 v[16:19], v[178:181], v[206:209], v[16:19]
	v_mfma_f32_16x16x32_bf16 v[8:11], v[170:173], v[214:217], v[8:11]
	v_mfma_f32_16x16x32_bf16 v[0:3], v[178:181], v[214:217], v[0:3]
	s_setprio 0
	s_barrier
	s_add_u32 s10, s10, 0x100
	s_addc_u32 s11, s11, 0
	s_add_u32 s34, s34, 0x100
	s_addc_u32 s35, s35, 0
	s_cmp_ge_i32 s58, s50
	s_mov_b32 s30, s58
	s_cbranch_scc0 .LBB0_898

; #define PG8_STAGE(bufoff, gbase, voff) do { _Pragma("unroll") for (int _i = 0; _i < 2; ++_i) \
;         __builtin_amdgcn_global_load_lds((const unsigned*)((const char*)(gbase) + (voff)[_i]), (PG8_LAS unsigned*)(lds + (bufoff) + ldsw + _i * 8192), 16, 0, 0); } while (0)
; #define PG8_LDA(dst, b, h) do { _Pragma("unroll") for (int m = 0; m < 4; ++m) _Pragma("unroll") for (int k = 0; k < 2; ++k) dst[m][k] = *(const PG8_LAS bf16x8*)(lds + PG8_SA(b, h) + aoff + m * 2048 + k * 1024); } while (0)
; #define PG8_LDB(dst, b, h) do { _Pragma("unroll") for (int n = 0; n < 2; ++n) _Pragma("unroll") for (int k = 0; k < 2; ++k) dst[n][k] = *(const PG8_LAS bf16x8*)(lds + PG8_SB(b, h) + boff + n * 2048 + k * 1024); } while (0)
; #define PG8_WAIT_V(n) asm volatile("s_waitcnt vmcnt(" #n ")" ::: "memory")
; #define PG8_WAIT_L(n) asm volatile("s_waitcnt lgkmcnt(" #n ")" ::: "memory")
; #define PG8_BAR __builtin_amdgcn_s_barrier()
; #define PG8_SCHED __builtin_amdgcn_sched_barrier(0)
; template <class Epi, class Sched, bool ALIGN_EPI = false, bool SP2 = false>
; __device__ __forceinline__ void gemm_phase(PG8_LAS unsigned char* lds, const Gemm g, const Sched& S, const Epi& E) {
;     ...
;         const char* nA = has_next ? (const char*)g.A + (size_t)nxt.pm * tstepA : cA; const char* nB = has_next ? (const char*)g.Bt + (size_t)nxt.pn * tstep : cB;
;         for (int t = 0; t < nt; t += 2) {
;             const bool last = (t == nt - 2);
;             const char* a1 = cA + (size_t)(t + 1) * kstep;
;             const char* a2 = last ? nA : cA + (size_t)(t + 2) * kstep; const char* b2 = last ? nB : cB + (size_t)(t + 2) * kstep;
;             const char* a3 = a2 + kstep; const char* b3 = b2 + kstep;
;             if (last && has_next) S.a_ready(nxt);
;             if constexpr (SP2) {
;             PG8_LDB(B0, 0, 0); PG8_LDB(B1, 0, 1); PG8_SCHED; PG8_LDA(At, 0, 0); PG8_STAGE(PG8_SA(1, 1), a1 + hstepA, voffA);
;             PG8_WAIT_V(8); PG8_WAIT_L(0); PG8_BAR; PG8_MMA(0, 0, At, B0); PG8_MMA(0, 1, At, B1); PG8_BAR; PG8_SCHED;
;             PG8_LDA(At, 0, 1); PG8_STAGE(PG8_SB(0, 0), b2, voffB); PG8_STAGE(PG8_SB(0, 1), b2 + hstep, voffB); PG8_STAGE(PG8_SA(0, 0), a2, voffA);
;             PG8_WAIT_V(8); PG8_WAIT_L(0); PG8_BAR; PG8_MMA(1, 0, At, B0); PG8_MMA(1, 1, At, B1); PG8_BAR; PG8_SCHED;
.LBB0_980:
	ds_read_b128 v[128:131], v169
	ds_read_b128 v[132:135], v169 offset:1024
	ds_read_b128 v[136:139], v169 offset:2048
	ds_read_b128 v[140:143], v169 offset:3072
	ds_read_b128 v[160:163], v170
	ds_read_b128 v[172:175], v170 offset:1024
	ds_read_b128 v[176:179], v170 offset:2048
	ds_read_b128 v[180:183], v170 offset:3072
	s_add_i32 s69, s38, 2
	s_add_u32 s70, s36, 0xfff50080
	s_addc_u32 s39, s37, -1
	s_cmp_eq_u32 s55, s38
	s_cselect_b32 s38, s8, s70
	s_cselect_b32 s39, s9, s39
	s_cselect_b32 s71, s35, s68
	s_cselect_b32 s70, s34, s67
	s_add_i32 m0, s44, 0xc000
	ds_read_b128 v[184:187], v171
	ds_read_b128 v[190:193], v171 offset:1024
	ds_read_b128 v[194:197], v171 offset:2048
	ds_read_b128 v[198:201], v171 offset:3072
	ds_read_b128 v[202:205], v171 offset:4096
	ds_read_b128 v[206:209], v171 offset:5120
	ds_read_b128 v[210:213], v171 offset:6144
	global_load_lds_dwordx4 v152, s[36:37]
	s_add_i32 m0, s44, 0xe000
	ds_read_b128 v[214:217], v171 offset:7168
	global_load_lds_dwordx4 v154, s[36:37]
	s_waitcnt vmcnt(8) lgkmcnt(0)
	s_setprio 1
	s_barrier
	v_mfma_f32_16x16x32_bf16 v[124:127], v[128:131], v[184:187], v[124:127]
	v_mfma_f32_16x16x32_bf16 v[120:123], v[136:139], v[184:187], v[120:123]
	v_mfma_f32_16x16x32_bf16 v[108:111], v[128:131], v[194:197], v[108:111]
	v_mfma_f32_16x16x32_bf16 v[104:107], v[136:139], v[194:197], v[104:107]
	v_mfma_f32_16x16x32_bf16 v[92:95], v[128:131], v[202:205], v[92:95]
	v_mfma_f32_16x16x32_bf16 v[88:91], v[136:139], v[202:205], v[88:91]
	v_mfma_f32_16x16x32_bf16 v[76:79], v[128:131], v[210:213], v[76:79]
	v_mfma_f32_16x16x32_bf16 v[72:75], v[136:139], v[210:213], v[72:75]
	v_mfma_f32_16x16x32_bf16 v[124:127], v[132:135], v[190:193], v[124:127]
	v_mfma_f32_16x16x32_bf16 v[120:123], v[140:143], v[190:193], v[120:123]
	v_mfma_f32_16x16x32_bf16 v[108:111], v[132:135], v[198:201], v[108:111]
	v_mfma_f32_16x16x32_bf16 v[104:107], v[140:143], v[198:201], v[104:107]
	v_mfma_f32_16x16x32_bf16 v[92:95], v[132:135], v[206:209], v[92:95]
	v_mfma_f32_16x16x32_bf16 v[88:91], v[140:143], v[206:209], v[88:91]
	v_mfma_f32_16x16x32_bf16 v[76:79], v[132:135], v[214:217], v[76:79]
	v_mfma_f32_16x16x32_bf16 v[72:75], v[140:143], v[214:217], v[72:75]
	v_mfma_f32_16x16x32_bf16 v[116:119], v[160:163], v[184:187], v[116:119]
	v_mfma_f32_16x16x32_bf16 v[112:115], v[176:179], v[184:187], v[112:115]
	v_mfma_f32_16x16x32_bf16 v[100:103], v[160:163], v[194:197], v[100:103]
	v_mfma_f32_16x16x32_bf16 v[96:99], v[176:179], v[194:197], v[96:99]
	v_mfma_f32_16x16x32_bf16 v[84:87], v[160:163], v[202:205], v[84:87]
	v_mfma_f32_16x16x32_bf16 v[80:83], v[176:179], v[202:205], v[80:83]
	v_mfma_f32_16x16x32_bf16 v[68:71], v[160:163], v[210:213], v[68:71]
	v_mfma_f32_16x16x32_bf16 v[64:67], v[176:179], v[210:213], v[64:67]
	v_mfma_f32_16x16x32_bf16 v[116:119], v[172:175], v[190:193], v[116:119]
	v_mfma_f32_16x16x32_bf16 v[112:115], v[180:183], v[190:193], v[112:115]
	v_mfma_f32_16x16x32_bf16 v[100:103], v[172:175], v[198:201], v[100:103]
	v_mfma_f32_16x16x32_bf16 v[96:99], v[180:183], v[198:201], v[96:99]
	v_mfma_f32_16x16x32_bf16 v[84:87], v[172:175], v[206:209], v[84:87]
	v_mfma_f32_16x16x32_bf16 v[80:83], v[180:183], v[206:209], v[80:83]
	v_mfma_f32_16x16x32_bf16 v[68:71], v[172:175], v[214:217], v[68:71]
	v_mfma_f32_16x16x32_bf16 v[64:67], v[180:183], v[214:217], v[64:67]
	s_setprio 0
	s_barrier
	s_add_i32 s72, s56, s42
	s_mov_b32 m0, s72
	ds_read_b128 v[184:187], v171 offset:16384
	ds_read_b128 v[190:193], v171 offset:17408
	ds_read_b128 v[194:197], v171 offset:18432
	ds_read_b128 v[198:201], v171 offset:19456
	global_load_lds_dwordx4 v150, s[70:71]
	s_add_i32 m0, s72, 0x2000
	s_mov_b64 s[100:101], s[70:71]
	s_add_i32 s72, s57, s42
	global_load_lds_dwordx4 v148, s[70:71]
	s_mov_b32 m0, s72
	s_add_u32 s70, s70, s4
	s_addc_u32 s71, s71, s5
	global_load_lds_dwordx4 v150, s[70:71]
	s_add_i32 m0, s72, 0x2000
	ds_read_b128 v[210:213], v171 offset:22528
	global_load_lds_dwordx4 v148, s[70:71]
	s_mov_b32 m0, s44
	ds_read_b128 v[206:209], v171 offset:21504
	global_load_lds_dwordx4 v144, s[38:39]
	s_mov_b32 m0, s45
	ds_read_b128 v[202:205], v171 offset:20480
	global_load_lds_dwordx4 v146, s[38:39]
	ds_read_b128 v[214:217], v171 offset:23552
	s_waitcnt vmcnt(8) lgkmcnt(0)
	s_setprio 1
	s_barrier
	v_mfma_f32_16x16x32_bf16 v[60:63], v[128:131], v[184:187], v[60:63]
	v_mfma_f32_16x16x32_bf16 v[56:59], v[136:139], v[184:187], v[56:59]
	v_mfma_f32_16x16x32_bf16 v[44:47], v[128:131], v[194:197], v[44:47]
	v_mfma_f32_16x16x32_bf16 v[40:43], v[136:139], v[194:197], v[40:43]
	v_mfma_f32_16x16x32_bf16 v[28:31], v[128:131], v[202:205], v[28:31]
	v_mfma_f32_16x16x32_bf16 v[24:27], v[136:139], v[202:205], v[24:27]
	v_mfma_f32_16x16x32_bf16 v[12:15], v[128:131], v[210:213], v[12:15]
	v_mfma_f32_16x16x32_bf16 v[8:11], v[136:139], v[210:213], v[8:11]
	v_mfma_f32_16x16x32_bf16 v[60:63], v[132:135], v[190:193], v[60:63]
	v_mfma_f32_16x16x32_bf16 v[56:59], v[140:143], v[190:193], v[56:59]
	v_mfma_f32_16x16x32_bf16 v[44:47], v[132:135], v[198:201], v[44:47]
	v_mfma_f32_16x16x32_bf16 v[40:43], v[140:143], v[198:201], v[40:43]
	v_mfma_f32_16x16x32_bf16 v[28:31], v[132:135], v[206:209], v[28:31]
	v_mfma_f32_16x16x32_bf16 v[24:27], v[140:143], v[206:209], v[24:27]
	v_mfma_f32_16x16x32_bf16 v[12:15], v[132:135], v[214:217], v[12:15]
	v_mfma_f32_16x16x32_bf16 v[8:11], v[140:143], v[214:217], v[8:11]
	v_mfma_f32_16x16x32_bf16 v[52:55], v[160:163], v[184:187], v[52:55]
	v_mfma_f32_16x16x32_bf16 v[48:51], v[176:179], v[184:187], v[48:51]
	v_mfma_f32_16x16x32_bf16 v[36:39], v[160:163], v[194:197], v[36:39]
	v_mfma_f32_16x16x32_bf16 v[32:35], v[176:179], v[194:197], v[32:35]
	v_mfma_f32_16x16x32_bf16 v[20:23], v[160:163], v[202:205], v[20:23]
	v_mfma_f32_16x16x32_bf16 v[16:19], v[176:179], v[202:205], v[16:19]
	v_mfma_f32_16x16x32_bf16 v[4:7], v[160:163], v[210:213], v[4:7]
	v_mfma_f32_16x16x32_bf16 v[0:3], v[176:179], v[210:213], v[0:3]
	v_mfma_f32_16x16x32_bf16 v[52:55], v[172:175], v[190:193], v[52:55]
	v_mfma_f32_16x16x32_bf16 v[48:51], v[180:183], v[190:193], v[48:51]
	v_mfma_f32_16x16x32_bf16 v[36:39], v[172:175], v[198:201], v[36:39]
	v_mfma_f32_16x16x32_bf16 v[32:35], v[180:183], v[198:201], v[32:35]
	v_mfma_f32_16x16x32_bf16 v[20:23], v[172:175], v[206:209], v[20:23]
	v_mfma_f32_16x16x32_bf16 v[16:19], v[180:183], v[206:209], v[16:19]
	v_mfma_f32_16x16x32_bf16 v[4:7], v[172:175], v[214:217], v[4:7]
	v_mfma_f32_16x16x32_bf16 v[0:3], v[180:183], v[214:217], v[0:3]
	s_setprio 0
	s_barrier
; #define PG8_STAGE(bufoff, gbase, voff) do { _Pragma("unroll") for (int _i = 0; _i < 2; ++_i) \
;         __builtin_amdgcn_global_load_lds((const unsigned*)((const char*)(gbase) + (voff)[_i]), (PG8_LAS unsigned*)(lds + (bufoff) + ldsw + _i * 8192), 16, 0, 0); } while (0)
; #define PG8_LDA(dst, b, h) do { _Pragma("unroll") for (int m = 0; m < 4; ++m) _Pragma("unroll") for (int k = 0; k < 2; ++k) dst[m][k] = *(const PG8_LAS bf16x8*)(lds + PG8_SA(b, h) + aoff + m * 2048 + k * 1024); } while (0)
; #define PG8_LDB(dst, b, h) do { _Pragma("unroll") for (int n = 0; n < 2; ++n) _Pragma("unroll") for (int k = 0; k < 2; ++k) dst[n][k] = *(const PG8_LAS bf16x8*)(lds + PG8_SB(b, h) + boff + n * 2048 + k * 1024); } while (0)
; #define PG8_MMA(ai, bj, At, Bt) do { __builtin_amdgcn_s_setprio(1); _Pragma("unroll") for (int m = 0; m < 4; ++m) _Pragma("unroll") for (int n = 0; n < 2; ++n) _Pragma("unroll") for (int k = 0; k < 2; ++k) \
;         acc[ai][bj][m][n] = __builtin_amdgcn_mfma_f32_16x16x32_bf16(Bt[n][k], At[m][k], acc[ai][bj][m][n], 0, 0, 0); __builtin_amdgcn_s_setprio(0); } while (0)
; #define PG8_WAIT_V(n) asm volatile("s_waitcnt vmcnt(" #n ")" ::: "memory")
; #define PG8_WAIT_L(n) asm volatile("s_waitcnt lgkmcnt(" #n ")" ::: "memory")
; #define PG8_BAR __builtin_amdgcn_s_barrier()
; #define PG8_SCHED __builtin_amdgcn_sched_barrier(0)
; template <class Epi, class Sched, bool ALIGN_EPI = false, bool SP2 = false>
; __device__ __forceinline__ void gemm_phase(PG8_LAS unsigned char* lds, const Gemm g, const Sched& S, const Epi& E) {
;     ...
;             PG8_LDB(B0, 1, 0); PG8_LDB(B1, 1, 1); PG8_SCHED; PG8_LDA(At, 1, 0); PG8_STAGE(PG8_SA(0, 1), a2 + hstepA, voffA);
;             PG8_WAIT_V(8); PG8_WAIT_L(0); PG8_BAR; PG8_MMA(0, 0, At, B0); PG8_MMA(0, 1, At, B1); PG8_BAR; PG8_SCHED;
;             PG8_LDA(At, 1, 1); PG8_STAGE(PG8_SB(1, 0), b3, voffB); PG8_STAGE(PG8_SB(1, 1), b3 + hstep, voffB); PG8_STAGE(PG8_SA(1, 0), a3, voffA);
;             PG8_WAIT_V(8); PG8_WAIT_L(0); PG8_BAR; PG8_MMA(1, 0, At, B0); PG8_MMA(1, 1, At, B1); PG8_BAR; PG8_SCHED;
	s_add_i32 s70, 0, 0x18000
	s_add_i32 s71, 0, 0x1c000
	v_add_u32_e32 v140, s70, v167
	v_add_u32_e32 v180, s71, v167
	ds_read_b128 v[128:131], v140
	ds_read_b128 v[132:135], v140 offset:1024
	ds_read_b128 v[136:139], v140 offset:2048
	ds_read_b128 v[140:143], v140 offset:3072
	ds_read_b128 v[160:163], v180
	ds_read_b128 v[172:175], v180 offset:1024
	ds_read_b128 v[176:179], v180 offset:2048
	ds_read_b128 v[180:183], v180 offset:3072
	s_mov_b64 vcc, s[38:39]
	s_add_u32 s38, s38, 0xb0000
	s_addc_u32 s39, s39, 0
	s_mov_b32 m0, s47
	ds_read_b128 v[184:187], v171 offset:32768
	ds_read_b128 v[190:193], v171 offset:33792
	ds_read_b128 v[194:197], v171 offset:34816
	ds_read_b128 v[198:201], v171 offset:35840
	ds_read_b128 v[202:205], v171 offset:36864
	ds_read_b128 v[206:209], v171 offset:37888
	ds_read_b128 v[210:213], v171 offset:38912
	global_load_lds_dwordx4 v144, s[38:39]
	s_mov_b32 m0, s48
	ds_read_b128 v[214:217], v171 offset:39936
	global_load_lds_dwordx4 v146, s[38:39]
	s_waitcnt vmcnt(8) lgkmcnt(0)
	s_setprio 1
	s_barrier
	v_mfma_f32_16x16x32_bf16 v[124:127], v[128:131], v[184:187], v[124:127]
	v_mfma_f32_16x16x32_bf16 v[120:123], v[136:139], v[184:187], v[120:123]
	v_mfma_f32_16x16x32_bf16 v[108:111], v[128:131], v[194:197], v[108:111]
	v_mfma_f32_16x16x32_bf16 v[104:107], v[136:139], v[194:197], v[104:107]
	v_mfma_f32_16x16x32_bf16 v[92:95], v[128:131], v[202:205], v[92:95]
	v_mfma_f32_16x16x32_bf16 v[88:91], v[136:139], v[202:205], v[88:91]
	v_mfma_f32_16x16x32_bf16 v[76:79], v[128:131], v[210:213], v[76:79]
	v_mfma_f32_16x16x32_bf16 v[72:75], v[136:139], v[210:213], v[72:75]
	v_mfma_f32_16x16x32_bf16 v[124:127], v[132:135], v[190:193], v[124:127]
	v_mfma_f32_16x16x32_bf16 v[120:123], v[140:143], v[190:193], v[120:123]
	v_mfma_f32_16x16x32_bf16 v[108:111], v[132:135], v[198:201], v[108:111]
	v_mfma_f32_16x16x32_bf16 v[104:107], v[140:143], v[198:201], v[104:107]
	v_mfma_f32_16x16x32_bf16 v[92:95], v[132:135], v[206:209], v[92:95]
	v_mfma_f32_16x16x32_bf16 v[88:91], v[140:143], v[206:209], v[88:91]
	v_mfma_f32_16x16x32_bf16 v[76:79], v[132:135], v[214:217], v[76:79]
	v_mfma_f32_16x16x32_bf16 v[72:75], v[140:143], v[214:217], v[72:75]
	v_mfma_f32_16x16x32_bf16 v[116:119], v[160:163], v[184:187], v[116:119]
	v_mfma_f32_16x16x32_bf16 v[112:115], v[176:179], v[184:187], v[112:115]
	v_mfma_f32_16x16x32_bf16 v[100:103], v[160:163], v[194:197], v[100:103]
	v_mfma_f32_16x16x32_bf16 v[96:99], v[176:179], v[194:197], v[96:99]
	v_mfma_f32_16x16x32_bf16 v[84:87], v[160:163], v[202:205], v[84:87]
	v_mfma_f32_16x16x32_bf16 v[80:83], v[176:179], v[202:205], v[80:83]
	v_mfma_f32_16x16x32_bf16 v[68:71], v[160:163], v[210:213], v[68:71]
	v_mfma_f32_16x16x32_bf16 v[64:67], v[176:179], v[210:213], v[64:67]
	v_mfma_f32_16x16x32_bf16 v[116:119], v[172:175], v[190:193], v[116:119]
	v_mfma_f32_16x16x32_bf16 v[112:115], v[180:183], v[190:193], v[112:115]
	v_mfma_f32_16x16x32_bf16 v[100:103], v[172:175], v[198:201], v[100:103]
	v_mfma_f32_16x16x32_bf16 v[96:99], v[180:183], v[198:201], v[96:99]
	v_mfma_f32_16x16x32_bf16 v[84:87], v[172:175], v[206:209], v[84:87]
	v_mfma_f32_16x16x32_bf16 v[80:83], v[180:183], v[206:209], v[80:83]
	v_mfma_f32_16x16x32_bf16 v[68:71], v[172:175], v[214:217], v[68:71]
	v_mfma_f32_16x16x32_bf16 v[64:67], v[180:183], v[214:217], v[64:67]
	s_setprio 0
	s_barrier
	s_add_i32 s38, s70, s42
	s_add_i32 m0, s38, 0xffffff80
	ds_read_b128 v[184:187], v171 offset:49152
	ds_read_b128 v[190:193], v171 offset:50176
	ds_read_b128 v[194:197], v171 offset:51200
	ds_read_b128 v[198:201], v171 offset:52224
	global_load_lds_dwordx4 v150, s[100:101] offset:128
	s_add_i32 m0, s38, 0x1f80
	s_add_i32 s38, s71, s42
	global_load_lds_dwordx4 v148, s[100:101] offset:128
	s_add_i32 m0, s38, 0xffffff80
	s_add_u32 s100, s100, s4
	s_addc_u32 s101, s101, s5
	global_load_lds_dwordx4 v150, s[100:101] offset:128
	s_add_i32 m0, s38, 0x1f80
	ds_read_b128 v[210:213], v171 offset:55296
	global_load_lds_dwordx4 v148, s[100:101] offset:128
	s_add_i32 m0, s51, 0xffffff80
	ds_read_b128 v[206:209], v171 offset:54272
	global_load_lds_dwordx4 v144, vcc offset:128
	s_add_i32 m0, s52, 0xffffff80
	ds_read_b128 v[202:205], v171 offset:53248
	global_load_lds_dwordx4 v146, vcc offset:128
	ds_read_b128 v[214:217], v171 offset:56320
	s_waitcnt vmcnt(8) lgkmcnt(0)
	s_setprio 1
	s_barrier
	v_mfma_f32_16x16x32_bf16 v[60:63], v[128:131], v[184:187], v[60:63]
	v_mfma_f32_16x16x32_bf16 v[56:59], v[136:139], v[184:187], v[56:59]
	v_mfma_f32_16x16x32_bf16 v[44:47], v[128:131], v[194:197], v[44:47]
	v_mfma_f32_16x16x32_bf16 v[40:43], v[136:139], v[194:197], v[40:43]
	v_mfma_f32_16x16x32_bf16 v[28:31], v[128:131], v[202:205], v[28:31]
	v_mfma_f32_16x16x32_bf16 v[24:27], v[136:139], v[202:205], v[24:27]
	v_mfma_f32_16x16x32_bf16 v[12:15], v[128:131], v[210:213], v[12:15]
	v_mfma_f32_16x16x32_bf16 v[8:11], v[136:139], v[210:213], v[8:11]
	v_mfma_f32_16x16x32_bf16 v[60:63], v[132:135], v[190:193], v[60:63]
	v_mfma_f32_16x16x32_bf16 v[56:59], v[140:143], v[190:193], v[56:59]
	v_mfma_f32_16x16x32_bf16 v[44:47], v[132:135], v[198:201], v[44:47]
	v_mfma_f32_16x16x32_bf16 v[40:43], v[140:143], v[198:201], v[40:43]
	v_mfma_f32_16x16x32_bf16 v[28:31], v[132:135], v[206:209], v[28:31]
	v_mfma_f32_16x16x32_bf16 v[24:27], v[140:143], v[206:209], v[24:27]
	v_mfma_f32_16x16x32_bf16 v[12:15], v[132:135], v[214:217], v[12:15]
	v_mfma_f32_16x16x32_bf16 v[8:11], v[140:143], v[214:217], v[8:11]
	v_mfma_f32_16x16x32_bf16 v[52:55], v[160:163], v[184:187], v[52:55]
	v_mfma_f32_16x16x32_bf16 v[48:51], v[176:179], v[184:187], v[48:51]
	v_mfma_f32_16x16x32_bf16 v[36:39], v[160:163], v[194:197], v[36:39]
	v_mfma_f32_16x16x32_bf16 v[32:35], v[176:179], v[194:197], v[32:35]
	v_mfma_f32_16x16x32_bf16 v[20:23], v[160:163], v[202:205], v[20:23]
	v_mfma_f32_16x16x32_bf16 v[16:19], v[176:179], v[202:205], v[16:19]
	v_mfma_f32_16x16x32_bf16 v[4:7], v[160:163], v[210:213], v[4:7]
	v_mfma_f32_16x16x32_bf16 v[0:3], v[176:179], v[210:213], v[0:3]
	v_mfma_f32_16x16x32_bf16 v[52:55], v[172:175], v[190:193], v[52:55]
	v_mfma_f32_16x16x32_bf16 v[48:51], v[180:183], v[190:193], v[48:51]
	v_mfma_f32_16x16x32_bf16 v[36:39], v[172:175], v[198:201], v[36:39]
	v_mfma_f32_16x16x32_bf16 v[32:35], v[180:183], v[198:201], v[32:35]
	v_mfma_f32_16x16x32_bf16 v[20:23], v[172:175], v[206:209], v[20:23]
	v_mfma_f32_16x16x32_bf16 v[16:19], v[180:183], v[206:209], v[16:19]
	v_mfma_f32_16x16x32_bf16 v[4:7], v[172:175], v[214:217], v[4:7]
	v_mfma_f32_16x16x32_bf16 v[0:3], v[180:183], v[214:217], v[0:3]
	s_setprio 0
	s_barrier
	s_add_u32 s36, s36, 0x100
	s_addc_u32 s37, s37, 0
	s_add_u32 s67, s67, 0x100
	s_addc_u32 s68, s68, 0
	s_cmp_ge_i32 s69, s54
	s_mov_b32 s38, s69
	s_cbranch_scc0 .LBB0_980

; #define PG8_STAGE(bufoff, gbase, voff) do { _Pragma("unroll") for (int _i = 0; _i < 2; ++_i) \
;         __builtin_amdgcn_global_load_lds((const unsigned*)((const char*)(gbase) + (voff)[_i]), (PG8_LAS unsigned*)(lds + (bufoff) + ldsw + _i * 8192), 16, 0, 0); } while (0)
; #define PG8_LDA(dst, b, h) do { _Pragma("unroll") for (int m = 0; m < 4; ++m) _Pragma("unroll") for (int k = 0; k < 2; ++k) dst[m][k] = *(const PG8_LAS bf16x8*)(lds + PG8_SA(b, h) + aoff + m * 2048 + k * 1024); } while (0)
; #define PG8_LDB(dst, b, h) do { _Pragma("unroll") for (int n = 0; n < 2; ++n) _Pragma("unroll") for (int k = 0; k < 2; ++k) dst[n][k] = *(const PG8_LAS bf16x8*)(lds + PG8_SB(b, h) + boff + n * 2048 + k * 1024); } while (0)
; #define PG8_WAIT_V(n) asm volatile("s_waitcnt vmcnt(" #n ")" ::: "memory")
; #define PG8_WAIT_L(n) asm volatile("s_waitcnt lgkmcnt(" #n ")" ::: "memory")
; #define PG8_BAR __builtin_amdgcn_s_barrier()
; #define PG8_SCHED __builtin_amdgcn_sched_barrier(0)
; template <class Epi, class Sched, bool ALIGN_EPI = false, bool SP2 = false>
; __device__ __forceinline__ void gemm_phase(PG8_LAS unsigned char* lds, const Gemm g, const Sched& S, const Epi& E) {
;     ...
;         const char* nA = has_next ? (const char*)g.A + (size_t)nxt.pm * tstepA : cA; const char* nB = has_next ? (const char*)g.Bt + (size_t)nxt.pn * tstep : cB;
;         for (int t = 0; t < nt; t += 2) {
;             const bool last = (t == nt - 2);
;             const char* a1 = cA + (size_t)(t + 1) * kstep;
;             const char* a2 = last ? nA : cA + (size_t)(t + 2) * kstep; const char* b2 = last ? nB : cB + (size_t)(t + 2) * kstep;
;             const char* a3 = a2 + kstep; const char* b3 = b2 + kstep;
;             if (last && has_next) S.a_ready(nxt);
;             if constexpr (SP2) {
;             PG8_LDB(B0, 0, 0); PG8_LDB(B1, 0, 1); PG8_SCHED; PG8_LDA(At, 0, 0); PG8_STAGE(PG8_SA(1, 1), a1 + hstepA, voffA);
;             PG8_WAIT_V(8); PG8_WAIT_L(0); PG8_BAR; PG8_MMA(0, 0, At, B0); PG8_MMA(0, 1, At, B1); PG8_BAR; PG8_SCHED;
;             PG8_LDA(At, 0, 1); PG8_STAGE(PG8_SB(0, 0), b2, voffB); PG8_STAGE(PG8_SB(0, 1), b2 + hstep, voffB); PG8_STAGE(PG8_SA(0, 0), a2, voffA);
;             PG8_WAIT_V(8); PG8_WAIT_L(0); PG8_BAR; PG8_MMA(1, 0, At, B0); PG8_MMA(1, 1, At, B1); PG8_BAR; PG8_SCHED;
.LBB0_1236:
	ds_read_b128 v[150:153], v147
	ds_read_b128 v[154:157], v147 offset:1024
	ds_read_b128 v[158:161], v147 offset:2048
	ds_read_b128 v[162:165], v147 offset:3072
	ds_read_b128 v[166:169], v148
	ds_read_b128 v[170:173], v148 offset:1024
	ds_read_b128 v[174:177], v148 offset:2048
	ds_read_b128 v[178:181], v148 offset:3072
	s_add_i32 s68, s40, 2
	s_add_u32 s69, s8, 0xfffc0080
	s_addc_u32 s41, s9, -1
	s_cmp_eq_u32 s59, s40
	s_cselect_b32 s40, s67, s69
	s_cselect_b32 s41, s35, s41
	s_cselect_b32 s71, s37, s43
	s_cselect_b32 s70, s36, s42
	s_add_i32 m0, s31, 0xc000
	ds_read_b128 v[182:185], v149
	ds_read_b128 v[190:193], v149 offset:1024
	ds_read_b128 v[194:197], v149 offset:2048
	ds_read_b128 v[198:201], v149 offset:3072
	ds_read_b128 v[202:205], v149 offset:4096
	ds_read_b128 v[206:209], v149 offset:5120
	ds_read_b128 v[210:213], v149 offset:6144
	global_load_lds_dwordx4 v136, s[8:9]
	s_add_i32 m0, s31, 0xe000
	ds_read_b128 v[214:217], v149 offset:7168
	global_load_lds_dwordx4 v138, s[8:9]
	s_waitcnt vmcnt(8) lgkmcnt(0)
	s_setprio 1
	s_barrier
	v_mfma_f32_16x16x32_bf16 v[120:123], v[150:153], v[182:185], v[120:123]
	v_mfma_f32_16x16x32_bf16 v[124:127], v[158:161], v[182:185], v[124:127]
	v_mfma_f32_16x16x32_bf16 v[108:111], v[150:153], v[194:197], v[108:111]
	v_mfma_f32_16x16x32_bf16 v[104:107], v[158:161], v[194:197], v[104:107]
	v_mfma_f32_16x16x32_bf16 v[92:95], v[150:153], v[202:205], v[92:95]
	v_mfma_f32_16x16x32_bf16 v[88:91], v[158:161], v[202:205], v[88:91]
	v_mfma_f32_16x16x32_bf16 v[76:79], v[150:153], v[210:213], v[76:79]
	v_mfma_f32_16x16x32_bf16 v[72:75], v[158:161], v[210:213], v[72:75]
	v_mfma_f32_16x16x32_bf16 v[120:123], v[154:157], v[190:193], v[120:123]
	v_mfma_f32_16x16x32_bf16 v[124:127], v[162:165], v[190:193], v[124:127]
	v_mfma_f32_16x16x32_bf16 v[108:111], v[154:157], v[198:201], v[108:111]
	v_mfma_f32_16x16x32_bf16 v[104:107], v[162:165], v[198:201], v[104:107]
	v_mfma_f32_16x16x32_bf16 v[92:95], v[154:157], v[206:209], v[92:95]
	v_mfma_f32_16x16x32_bf16 v[88:91], v[162:165], v[206:209], v[88:91]
	v_mfma_f32_16x16x32_bf16 v[76:79], v[154:157], v[214:217], v[76:79]
	v_mfma_f32_16x16x32_bf16 v[72:75], v[162:165], v[214:217], v[72:75]
	v_mfma_f32_16x16x32_bf16 v[116:119], v[166:169], v[182:185], v[116:119]
	v_mfma_f32_16x16x32_bf16 v[112:115], v[174:177], v[182:185], v[112:115]
	v_mfma_f32_16x16x32_bf16 v[100:103], v[166:169], v[194:197], v[100:103]
	v_mfma_f32_16x16x32_bf16 v[96:99], v[174:177], v[194:197], v[96:99]
	v_mfma_f32_16x16x32_bf16 v[84:87], v[166:169], v[202:205], v[84:87]
	v_mfma_f32_16x16x32_bf16 v[80:83], v[174:177], v[202:205], v[80:83]
	v_mfma_f32_16x16x32_bf16 v[68:71], v[166:169], v[210:213], v[68:71]
	v_mfma_f32_16x16x32_bf16 v[64:67], v[174:177], v[210:213], v[64:67]
	v_mfma_f32_16x16x32_bf16 v[116:119], v[170:173], v[190:193], v[116:119]
	v_mfma_f32_16x16x32_bf16 v[112:115], v[178:181], v[190:193], v[112:115]
	v_mfma_f32_16x16x32_bf16 v[100:103], v[170:173], v[198:201], v[100:103]
	v_mfma_f32_16x16x32_bf16 v[96:99], v[178:181], v[198:201], v[96:99]
	v_mfma_f32_16x16x32_bf16 v[84:87], v[170:173], v[206:209], v[84:87]
	v_mfma_f32_16x16x32_bf16 v[80:83], v[178:181], v[206:209], v[80:83]
	v_mfma_f32_16x16x32_bf16 v[68:71], v[170:173], v[214:217], v[68:71]
	v_mfma_f32_16x16x32_bf16 v[64:67], v[178:181], v[214:217], v[64:67]
	s_setprio 0
	s_barrier
	s_add_i32 s69, s60, s47
	s_mov_b32 m0, s69
	ds_read_b128 v[182:185], v149 offset:16384
	ds_read_b128 v[190:193], v149 offset:17408
	ds_read_b128 v[194:197], v149 offset:18432
	ds_read_b128 v[198:201], v149 offset:19456
	global_load_lds_dwordx4 v134, s[70:71]
	s_add_i32 m0, s69, 0x2000
	s_mov_b64 s[100:101], s[70:71]
	s_add_i32 s69, s61, s47
	global_load_lds_dwordx4 v132, s[70:71]
	s_mov_b32 m0, s69
	s_add_u32 s70, s70, s4
	s_addc_u32 s71, s71, s5
	global_load_lds_dwordx4 v134, s[70:71]
	s_add_i32 m0, s69, 0x2000
	ds_read_b128 v[210:213], v149 offset:22528
	global_load_lds_dwordx4 v132, s[70:71]
	s_mov_b32 m0, s31
	ds_read_b128 v[206:209], v149 offset:21504
	global_load_lds_dwordx4 v128, s[40:41]
	s_mov_b32 m0, s50
	ds_read_b128 v[202:205], v149 offset:20480
	global_load_lds_dwordx4 v130, s[40:41]
	ds_read_b128 v[214:217], v149 offset:23552
	s_waitcnt vmcnt(8) lgkmcnt(0)
	s_setprio 1
	s_barrier
	v_mfma_f32_16x16x32_bf16 v[60:63], v[150:153], v[182:185], v[60:63]
	v_mfma_f32_16x16x32_bf16 v[56:59], v[158:161], v[182:185], v[56:59]
	v_mfma_f32_16x16x32_bf16 v[44:47], v[150:153], v[194:197], v[44:47]
	v_mfma_f32_16x16x32_bf16 v[40:43], v[158:161], v[194:197], v[40:43]
	v_mfma_f32_16x16x32_bf16 v[28:31], v[150:153], v[202:205], v[28:31]
	v_mfma_f32_16x16x32_bf16 v[24:27], v[158:161], v[202:205], v[24:27]
	v_mfma_f32_16x16x32_bf16 v[12:15], v[150:153], v[210:213], v[12:15]
	v_mfma_f32_16x16x32_bf16 v[8:11], v[158:161], v[210:213], v[8:11]
	v_mfma_f32_16x16x32_bf16 v[60:63], v[154:157], v[190:193], v[60:63]
	v_mfma_f32_16x16x32_bf16 v[56:59], v[162:165], v[190:193], v[56:59]
	v_mfma_f32_16x16x32_bf16 v[44:47], v[154:157], v[198:201], v[44:47]
	v_mfma_f32_16x16x32_bf16 v[40:43], v[162:165], v[198:201], v[40:43]
	v_mfma_f32_16x16x32_bf16 v[28:31], v[154:157], v[206:209], v[28:31]
	v_mfma_f32_16x16x32_bf16 v[24:27], v[162:165], v[206:209], v[24:27]
	v_mfma_f32_16x16x32_bf16 v[12:15], v[154:157], v[214:217], v[12:15]
	v_mfma_f32_16x16x32_bf16 v[8:11], v[162:165], v[214:217], v[8:11]
	v_mfma_f32_16x16x32_bf16 v[52:55], v[166:169], v[182:185], v[52:55]
	v_mfma_f32_16x16x32_bf16 v[48:51], v[174:177], v[182:185], v[48:51]
	v_mfma_f32_16x16x32_bf16 v[36:39], v[166:169], v[194:197], v[36:39]
	v_mfma_f32_16x16x32_bf16 v[32:35], v[174:177], v[194:197], v[32:35]
	v_mfma_f32_16x16x32_bf16 v[20:23], v[166:169], v[202:205], v[20:23]
	v_mfma_f32_16x16x32_bf16 v[16:19], v[174:177], v[202:205], v[16:19]
	v_mfma_f32_16x16x32_bf16 v[4:7], v[166:169], v[210:213], v[4:7]
	v_mfma_f32_16x16x32_bf16 v[0:3], v[174:177], v[210:213], v[0:3]
	v_mfma_f32_16x16x32_bf16 v[52:55], v[170:173], v[190:193], v[52:55]
	v_mfma_f32_16x16x32_bf16 v[48:51], v[178:181], v[190:193], v[48:51]
	v_mfma_f32_16x16x32_bf16 v[36:39], v[170:173], v[198:201], v[36:39]
	v_mfma_f32_16x16x32_bf16 v[32:35], v[178:181], v[198:201], v[32:35]
	v_mfma_f32_16x16x32_bf16 v[20:23], v[170:173], v[206:209], v[20:23]
	v_mfma_f32_16x16x32_bf16 v[16:19], v[178:181], v[206:209], v[16:19]
	v_mfma_f32_16x16x32_bf16 v[4:7], v[170:173], v[214:217], v[4:7]
	v_mfma_f32_16x16x32_bf16 v[0:3], v[178:181], v[214:217], v[0:3]
	s_setprio 0
	s_barrier
; #define PG8_STAGE(bufoff, gbase, voff) do { _Pragma("unroll") for (int _i = 0; _i < 2; ++_i) \
;         __builtin_amdgcn_global_load_lds((const unsigned*)((const char*)(gbase) + (voff)[_i]), (PG8_LAS unsigned*)(lds + (bufoff) + ldsw + _i * 8192), 16, 0, 0); } while (0)
; #define PG8_LDA(dst, b, h) do { _Pragma("unroll") for (int m = 0; m < 4; ++m) _Pragma("unroll") for (int k = 0; k < 2; ++k) dst[m][k] = *(const PG8_LAS bf16x8*)(lds + PG8_SA(b, h) + aoff + m * 2048 + k * 1024); } while (0)
; #define PG8_LDB(dst, b, h) do { _Pragma("unroll") for (int n = 0; n < 2; ++n) _Pragma("unroll") for (int k = 0; k < 2; ++k) dst[n][k] = *(const PG8_LAS bf16x8*)(lds + PG8_SB(b, h) + boff + n * 2048 + k * 1024); } while (0)
; #define PG8_MMA(ai, bj, At, Bt) do { __builtin_amdgcn_s_setprio(1); _Pragma("unroll") for (int m = 0; m < 4; ++m) _Pragma("unroll") for (int n = 0; n < 2; ++n) _Pragma("unroll") for (int k = 0; k < 2; ++k) \
;         acc[ai][bj][m][n] = __builtin_amdgcn_mfma_f32_16x16x32_bf16(Bt[n][k], At[m][k], acc[ai][bj][m][n], 0, 0, 0); __builtin_amdgcn_s_setprio(0); } while (0)
; #define PG8_WAIT_V(n) asm volatile("s_waitcnt vmcnt(" #n ")" ::: "memory")
; #define PG8_WAIT_L(n) asm volatile("s_waitcnt lgkmcnt(" #n ")" ::: "memory")
; #define PG8_BAR __builtin_amdgcn_s_barrier()
; #define PG8_SCHED __builtin_amdgcn_sched_barrier(0)
; template <class Epi, class Sched, bool ALIGN_EPI = false, bool SP2 = false>
; __device__ __forceinline__ void gemm_phase(PG8_LAS unsigned char* lds, const Gemm g, const Sched& S, const Epi& E) {
;     ...
;             PG8_LDB(B0, 1, 0); PG8_LDB(B1, 1, 1); PG8_SCHED; PG8_LDA(At, 1, 0); PG8_STAGE(PG8_SA(0, 1), a2 + hstepA, voffA);
;             PG8_WAIT_V(8); PG8_WAIT_L(0); PG8_BAR; PG8_MMA(0, 0, At, B0); PG8_MMA(0, 1, At, B1); PG8_BAR; PG8_SCHED;
;             PG8_LDA(At, 1, 1); PG8_STAGE(PG8_SB(1, 0), b3, voffB); PG8_STAGE(PG8_SB(1, 1), b3 + hstep, voffB); PG8_STAGE(PG8_SA(1, 0), a3, voffA);
;             PG8_WAIT_V(8); PG8_WAIT_L(0); PG8_BAR; PG8_MMA(1, 0, At, B0); PG8_MMA(1, 1, At, B1); PG8_BAR; PG8_SCHED;
	s_add_i32 s69, 0, 0x18000
	s_add_i32 s70, 0, 0x1c000
	v_add_u32_e32 v162, s69, v145
	v_add_u32_e32 v178, s70, v145
	ds_read_b128 v[150:153], v162
	ds_read_b128 v[154:157], v162 offset:1024
	ds_read_b128 v[158:161], v162 offset:2048
	ds_read_b128 v[162:165], v162 offset:3072
	ds_read_b128 v[166:169], v178
	ds_read_b128 v[170:173], v178 offset:1024
	ds_read_b128 v[174:177], v178 offset:2048
	ds_read_b128 v[178:181], v178 offset:3072
	s_mov_b64 vcc, s[40:41]
	s_add_u32 s40, s40, 0x40000
	s_addc_u32 s41, s41, 0
	s_mov_b32 m0, s51
	ds_read_b128 v[182:185], v149 offset:32768
	ds_read_b128 v[190:193], v149 offset:33792
	ds_read_b128 v[194:197], v149 offset:34816
	ds_read_b128 v[198:201], v149 offset:35840
	ds_read_b128 v[202:205], v149 offset:36864
	ds_read_b128 v[206:209], v149 offset:37888
	ds_read_b128 v[210:213], v149 offset:38912
	global_load_lds_dwordx4 v128, s[40:41]
	s_mov_b32 m0, s52
	ds_read_b128 v[214:217], v149 offset:39936
	global_load_lds_dwordx4 v130, s[40:41]
	s_waitcnt vmcnt(8) lgkmcnt(0)
	s_setprio 1
	s_barrier
	v_mfma_f32_16x16x32_bf16 v[120:123], v[150:153], v[182:185], v[120:123]
	v_mfma_f32_16x16x32_bf16 v[124:127], v[158:161], v[182:185], v[124:127]
	v_mfma_f32_16x16x32_bf16 v[108:111], v[150:153], v[194:197], v[108:111]
	v_mfma_f32_16x16x32_bf16 v[104:107], v[158:161], v[194:197], v[104:107]
	v_mfma_f32_16x16x32_bf16 v[92:95], v[150:153], v[202:205], v[92:95]
	v_mfma_f32_16x16x32_bf16 v[88:91], v[158:161], v[202:205], v[88:91]
	v_mfma_f32_16x16x32_bf16 v[76:79], v[150:153], v[210:213], v[76:79]
	v_mfma_f32_16x16x32_bf16 v[72:75], v[158:161], v[210:213], v[72:75]
	v_mfma_f32_16x16x32_bf16 v[120:123], v[154:157], v[190:193], v[120:123]
	v_mfma_f32_16x16x32_bf16 v[124:127], v[162:165], v[190:193], v[124:127]
	v_mfma_f32_16x16x32_bf16 v[108:111], v[154:157], v[198:201], v[108:111]
	v_mfma_f32_16x16x32_bf16 v[104:107], v[162:165], v[198:201], v[104:107]
	v_mfma_f32_16x16x32_bf16 v[92:95], v[154:157], v[206:209], v[92:95]
	v_mfma_f32_16x16x32_bf16 v[88:91], v[162:165], v[206:209], v[88:91]
	v_mfma_f32_16x16x32_bf16 v[76:79], v[154:157], v[214:217], v[76:79]
	v_mfma_f32_16x16x32_bf16 v[72:75], v[162:165], v[214:217], v[72:75]
	v_mfma_f32_16x16x32_bf16 v[116:119], v[166:169], v[182:185], v[116:119]
	v_mfma_f32_16x16x32_bf16 v[112:115], v[174:177], v[182:185], v[112:115]
	v_mfma_f32_16x16x32_bf16 v[100:103], v[166:169], v[194:197], v[100:103]
	v_mfma_f32_16x16x32_bf16 v[96:99], v[174:177], v[194:197], v[96:99]
	v_mfma_f32_16x16x32_bf16 v[84:87], v[166:169], v[202:205], v[84:87]
	v_mfma_f32_16x16x32_bf16 v[80:83], v[174:177], v[202:205], v[80:83]
	v_mfma_f32_16x16x32_bf16 v[68:71], v[166:169], v[210:213], v[68:71]
	v_mfma_f32_16x16x32_bf16 v[64:67], v[174:177], v[210:213], v[64:67]
	v_mfma_f32_16x16x32_bf16 v[116:119], v[170:173], v[190:193], v[116:119]
	v_mfma_f32_16x16x32_bf16 v[112:115], v[178:181], v[190:193], v[112:115]
	v_mfma_f32_16x16x32_bf16 v[100:103], v[170:173], v[198:201], v[100:103]
	v_mfma_f32_16x16x32_bf16 v[96:99], v[178:181], v[198:201], v[96:99]
	v_mfma_f32_16x16x32_bf16 v[84:87], v[170:173], v[206:209], v[84:87]
	v_mfma_f32_16x16x32_bf16 v[80:83], v[178:181], v[206:209], v[80:83]
	v_mfma_f32_16x16x32_bf16 v[68:71], v[170:173], v[214:217], v[68:71]
	v_mfma_f32_16x16x32_bf16 v[64:67], v[178:181], v[214:217], v[64:67]
	s_setprio 0
	s_barrier
	s_add_i32 s40, s69, s47
	s_add_i32 m0, s40, 0xffffff80
	ds_read_b128 v[182:185], v149 offset:49152
	ds_read_b128 v[190:193], v149 offset:50176
	ds_read_b128 v[194:197], v149 offset:51200
	ds_read_b128 v[198:201], v149 offset:52224
	global_load_lds_dwordx4 v134, s[100:101] offset:128
	s_add_i32 m0, s40, 0x1f80
	s_add_i32 s40, s70, s47
	global_load_lds_dwordx4 v132, s[100:101] offset:128
	s_add_i32 m0, s40, 0xffffff80
	s_add_u32 s100, s100, s4
	s_addc_u32 s101, s101, s5
	global_load_lds_dwordx4 v134, s[100:101] offset:128
	s_add_i32 m0, s40, 0x1f80
	ds_read_b128 v[210:213], v149 offset:55296
	global_load_lds_dwordx4 v132, s[100:101] offset:128
	s_add_i32 m0, s55, 0xffffff80
	ds_read_b128 v[206:209], v149 offset:54272
	global_load_lds_dwordx4 v128, vcc offset:128
	s_add_i32 m0, s56, 0xffffff80
	ds_read_b128 v[202:205], v149 offset:53248
	global_load_lds_dwordx4 v130, vcc offset:128
	ds_read_b128 v[214:217], v149 offset:56320
	s_waitcnt vmcnt(8) lgkmcnt(0)
	s_setprio 1
	s_barrier
	v_mfma_f32_16x16x32_bf16 v[60:63], v[150:153], v[182:185], v[60:63]
	v_mfma_f32_16x16x32_bf16 v[56:59], v[158:161], v[182:185], v[56:59]
	v_mfma_f32_16x16x32_bf16 v[44:47], v[150:153], v[194:197], v[44:47]
	v_mfma_f32_16x16x32_bf16 v[40:43], v[158:161], v[194:197], v[40:43]
	v_mfma_f32_16x16x32_bf16 v[28:31], v[150:153], v[202:205], v[28:31]
	v_mfma_f32_16x16x32_bf16 v[24:27], v[158:161], v[202:205], v[24:27]
	v_mfma_f32_16x16x32_bf16 v[12:15], v[150:153], v[210:213], v[12:15]
	v_mfma_f32_16x16x32_bf16 v[8:11], v[158:161], v[210:213], v[8:11]
	v_mfma_f32_16x16x32_bf16 v[60:63], v[154:157], v[190:193], v[60:63]
	v_mfma_f32_16x16x32_bf16 v[56:59], v[162:165], v[190:193], v[56:59]
	v_mfma_f32_16x16x32_bf16 v[44:47], v[154:157], v[198:201], v[44:47]
	v_mfma_f32_16x16x32_bf16 v[40:43], v[162:165], v[198:201], v[40:43]
	v_mfma_f32_16x16x32_bf16 v[28:31], v[154:157], v[206:209], v[28:31]
	v_mfma_f32_16x16x32_bf16 v[24:27], v[162:165], v[206:209], v[24:27]
	v_mfma_f32_16x16x32_bf16 v[12:15], v[154:157], v[214:217], v[12:15]
	v_mfma_f32_16x16x32_bf16 v[8:11], v[162:165], v[214:217], v[8:11]
	v_mfma_f32_16x16x32_bf16 v[52:55], v[166:169], v[182:185], v[52:55]
	v_mfma_f32_16x16x32_bf16 v[48:51], v[174:177], v[182:185], v[48:51]
	v_mfma_f32_16x16x32_bf16 v[36:39], v[166:169], v[194:197], v[36:39]
	v_mfma_f32_16x16x32_bf16 v[32:35], v[174:177], v[194:197], v[32:35]
	v_mfma_f32_16x16x32_bf16 v[20:23], v[166:169], v[202:205], v[20:23]
	v_mfma_f32_16x16x32_bf16 v[16:19], v[174:177], v[202:205], v[16:19]
	v_mfma_f32_16x16x32_bf16 v[4:7], v[166:169], v[210:213], v[4:7]
	v_mfma_f32_16x16x32_bf16 v[0:3], v[174:177], v[210:213], v[0:3]
	v_mfma_f32_16x16x32_bf16 v[52:55], v[170:173], v[190:193], v[52:55]
	v_mfma_f32_16x16x32_bf16 v[48:51], v[178:181], v[190:193], v[48:51]
	v_mfma_f32_16x16x32_bf16 v[36:39], v[170:173], v[198:201], v[36:39]
	v_mfma_f32_16x16x32_bf16 v[32:35], v[178:181], v[198:201], v[32:35]
	v_mfma_f32_16x16x32_bf16 v[20:23], v[170:173], v[206:209], v[20:23]
	v_mfma_f32_16x16x32_bf16 v[16:19], v[178:181], v[206:209], v[16:19]
	v_mfma_f32_16x16x32_bf16 v[4:7], v[170:173], v[214:217], v[4:7]
	v_mfma_f32_16x16x32_bf16 v[0:3], v[178:181], v[214:217], v[0:3]
	s_setprio 0
	s_barrier
	s_add_u32 s8, s8, 0x100
	s_addc_u32 s9, s9, 0
	s_add_u32 s42, s42, 0x100
	s_addc_u32 s43, s43, 0
	s_cmp_ge_i32 s68, s58
	s_mov_b32 s40, s68
	s_cbranch_scc0 .LBB0_1236

; #define PG8_STAGE(bufoff, gbase, voff) do { _Pragma("unroll") for (int _i = 0; _i < 2; ++_i) \
;         __builtin_amdgcn_global_load_lds((const unsigned*)((const char*)(gbase) + (voff)[_i]), (PG8_LAS unsigned*)(lds + (bufoff) + ldsw + _i * 8192), 16, 0, 0); } while (0)
; #define PG8_LDA(dst, b, h) do { _Pragma("unroll") for (int m = 0; m < 4; ++m) _Pragma("unroll") for (int k = 0; k < 2; ++k) dst[m][k] = *(const PG8_LAS bf16x8*)(lds + PG8_SA(b, h) + aoff + m * 2048 + k * 1024); } while (0)
; #define PG8_LDB(dst, b, h) do { _Pragma("unroll") for (int n = 0; n < 2; ++n) _Pragma("unroll") for (int k = 0; k < 2; ++k) dst[n][k] = *(const PG8_LAS bf16x8*)(lds + PG8_SB(b, h) + boff + n * 2048 + k * 1024); } while (0)
; #define PG8_WAIT_V(n) asm volatile("s_waitcnt vmcnt(" #n ")" ::: "memory")
; #define PG8_WAIT_L(n) asm volatile("s_waitcnt lgkmcnt(" #n ")" ::: "memory")
; #define PG8_BAR __builtin_amdgcn_s_barrier()
; #define PG8_SCHED __builtin_amdgcn_sched_barrier(0)
; template <class Epi, class Sched, bool ALIGN_EPI = false, bool SP2 = false>
; __device__ __forceinline__ void gemm_phase(PG8_LAS unsigned char* lds, const Gemm g, const Sched& S, const Epi& E) {
;     ...
;         const char* nA = has_next ? (const char*)g.A + (size_t)nxt.pm * tstepA : cA; const char* nB = has_next ? (const char*)g.Bt + (size_t)nxt.pn * tstep : cB;
;         for (int t = 0; t < nt; t += 2) {
;             const bool last = (t == nt - 2);
;             const char* a1 = cA + (size_t)(t + 1) * kstep;
;             const char* a2 = last ? nA : cA + (size_t)(t + 2) * kstep; const char* b2 = last ? nB : cB + (size_t)(t + 2) * kstep;
;             const char* a3 = a2 + kstep; const char* b3 = b2 + kstep;
;             if (last && has_next) S.a_ready(nxt);
;             if constexpr (SP2) {
;             PG8_LDB(B0, 0, 0); PG8_LDB(B1, 0, 1); PG8_SCHED; PG8_LDA(At, 0, 0); PG8_STAGE(PG8_SA(1, 1), a1 + hstepA, voffA);
;             PG8_WAIT_V(8); PG8_WAIT_L(0); PG8_BAR; PG8_MMA(0, 0, At, B0); PG8_MMA(0, 1, At, B1); PG8_BAR; PG8_SCHED;
;             PG8_LDA(At, 0, 1); PG8_STAGE(PG8_SB(0, 0), b2, voffB); PG8_STAGE(PG8_SB(0, 1), b2 + hstep, voffB); PG8_STAGE(PG8_SA(0, 0), a2, voffA);
;             PG8_WAIT_V(8); PG8_WAIT_L(0); PG8_BAR; PG8_MMA(1, 0, At, B0); PG8_MMA(1, 1, At, B1); PG8_BAR; PG8_SCHED;
.LBB0_1480:
	ds_read_b128 v[162:165], v159
	ds_read_b128 v[166:169], v159 offset:1024
	ds_read_b128 v[170:173], v159 offset:2048
	ds_read_b128 v[174:177], v159 offset:3072
	ds_read_b128 v[178:181], v160
	ds_read_b128 v[182:185], v160 offset:1024
	ds_read_b128 v[190:193], v160 offset:2048
	ds_read_b128 v[194:197], v160 offset:3072
	s_add_i32 s63, s36, 2
	s_add_u32 s64, s10, 0xfffe0080
	s_addc_u32 s37, s11, -1
	s_cmp_eq_u32 s56, s36
	s_cselect_b32 s36, s62, s64
	s_cselect_b32 s37, s29, s37
	s_cselect_b32 s65, s31, s39
	s_cselect_b32 s64, s30, s38
	s_add_i32 m0, s27, 0xc000
	ds_read_b128 v[198:201], v161
	ds_read_b128 v[202:205], v161 offset:1024
	ds_read_b128 v[206:209], v161 offset:2048
	ds_read_b128 v[210:213], v161 offset:3072
	ds_read_b128 v[214:217], v161 offset:4096
	ds_read_b128 v[218:221], v161 offset:5120
	ds_read_b128 v[222:225], v161 offset:6144
	global_load_lds_dwordx4 v138, s[10:11]
	s_add_i32 m0, s27, 0xe000
	ds_read_b128 v[226:229], v161 offset:7168
	global_load_lds_dwordx4 v140, s[10:11]
	s_waitcnt vmcnt(8) lgkmcnt(0)
	s_setprio 1
	s_barrier
	v_mfma_f32_16x16x32_bf16 v[124:127], v[162:165], v[198:201], v[124:127]
	v_mfma_f32_16x16x32_bf16 v[120:123], v[170:173], v[198:201], v[120:123]
	v_mfma_f32_16x16x32_bf16 v[108:111], v[162:165], v[206:209], v[108:111]
	v_mfma_f32_16x16x32_bf16 v[104:107], v[170:173], v[206:209], v[104:107]
	v_mfma_f32_16x16x32_bf16 v[92:95], v[162:165], v[214:217], v[92:95]
	v_mfma_f32_16x16x32_bf16 v[88:91], v[170:173], v[214:217], v[88:91]
	v_mfma_f32_16x16x32_bf16 v[76:79], v[162:165], v[222:225], v[76:79]
	v_mfma_f32_16x16x32_bf16 v[72:75], v[170:173], v[222:225], v[72:75]
	v_mfma_f32_16x16x32_bf16 v[124:127], v[166:169], v[202:205], v[124:127]
	v_mfma_f32_16x16x32_bf16 v[120:123], v[174:177], v[202:205], v[120:123]
	v_mfma_f32_16x16x32_bf16 v[108:111], v[166:169], v[210:213], v[108:111]
	v_mfma_f32_16x16x32_bf16 v[104:107], v[174:177], v[210:213], v[104:107]
	v_mfma_f32_16x16x32_bf16 v[92:95], v[166:169], v[218:221], v[92:95]
	v_mfma_f32_16x16x32_bf16 v[88:91], v[174:177], v[218:221], v[88:91]
	v_mfma_f32_16x16x32_bf16 v[76:79], v[166:169], v[226:229], v[76:79]
	v_mfma_f32_16x16x32_bf16 v[72:75], v[174:177], v[226:229], v[72:75]
	v_mfma_f32_16x16x32_bf16 v[116:119], v[178:181], v[198:201], v[116:119]
	v_mfma_f32_16x16x32_bf16 v[112:115], v[190:193], v[198:201], v[112:115]
	v_mfma_f32_16x16x32_bf16 v[100:103], v[178:181], v[206:209], v[100:103]
	v_mfma_f32_16x16x32_bf16 v[96:99], v[190:193], v[206:209], v[96:99]
	v_mfma_f32_16x16x32_bf16 v[84:87], v[178:181], v[214:217], v[84:87]
	v_mfma_f32_16x16x32_bf16 v[80:83], v[190:193], v[214:217], v[80:83]
	v_mfma_f32_16x16x32_bf16 v[68:71], v[178:181], v[222:225], v[68:71]
	v_mfma_f32_16x16x32_bf16 v[64:67], v[190:193], v[222:225], v[64:67]
	v_mfma_f32_16x16x32_bf16 v[116:119], v[182:185], v[202:205], v[116:119]
	v_mfma_f32_16x16x32_bf16 v[112:115], v[194:197], v[202:205], v[112:115]
	v_mfma_f32_16x16x32_bf16 v[100:103], v[182:185], v[210:213], v[100:103]
	v_mfma_f32_16x16x32_bf16 v[96:99], v[194:197], v[210:213], v[96:99]
	v_mfma_f32_16x16x32_bf16 v[84:87], v[182:185], v[218:221], v[84:87]
	v_mfma_f32_16x16x32_bf16 v[80:83], v[194:197], v[218:221], v[80:83]
	v_mfma_f32_16x16x32_bf16 v[68:71], v[182:185], v[226:229], v[68:71]
	v_mfma_f32_16x16x32_bf16 v[64:67], v[194:197], v[226:229], v[64:67]
	s_setprio 0
	s_barrier
	s_add_i32 s66, s57, s47
	s_mov_b32 m0, s66
	ds_read_b128 v[198:201], v161 offset:16384
	ds_read_b128 v[202:205], v161 offset:17408
	ds_read_b128 v[206:209], v161 offset:18432
	ds_read_b128 v[210:213], v161 offset:19456
	global_load_lds_dwordx4 v136, s[64:65]
	s_add_i32 m0, s66, 0x2000
	s_mov_b64 s[100:101], s[64:65]
	s_add_i32 s66, s58, s47
	global_load_lds_dwordx4 v134, s[64:65]
	s_mov_b32 m0, s66
	s_add_u32 s64, s64, s16
	s_addc_u32 s65, s65, s17
	global_load_lds_dwordx4 v136, s[64:65]
	s_add_i32 m0, s66, 0x2000
	ds_read_b128 v[222:225], v161 offset:22528
	global_load_lds_dwordx4 v134, s[64:65]
	s_mov_b32 m0, s27
	ds_read_b128 v[218:221], v161 offset:21504
	global_load_lds_dwordx4 v130, s[36:37]
	s_mov_b32 m0, s48
	ds_read_b128 v[214:217], v161 offset:20480
	global_load_lds_dwordx4 v132, s[36:37]
	ds_read_b128 v[226:229], v161 offset:23552
	s_waitcnt vmcnt(8) lgkmcnt(0)
	s_setprio 1
	s_barrier
	v_mfma_f32_16x16x32_bf16 v[60:63], v[162:165], v[198:201], v[60:63]
	v_mfma_f32_16x16x32_bf16 v[56:59], v[170:173], v[198:201], v[56:59]
	v_mfma_f32_16x16x32_bf16 v[44:47], v[162:165], v[206:209], v[44:47]
	v_mfma_f32_16x16x32_bf16 v[40:43], v[170:173], v[206:209], v[40:43]
	v_mfma_f32_16x16x32_bf16 v[28:31], v[162:165], v[214:217], v[28:31]
	v_mfma_f32_16x16x32_bf16 v[24:27], v[170:173], v[214:217], v[24:27]
	v_mfma_f32_16x16x32_bf16 v[12:15], v[162:165], v[222:225], v[12:15]
	v_mfma_f32_16x16x32_bf16 v[8:11], v[170:173], v[222:225], v[8:11]
	v_mfma_f32_16x16x32_bf16 v[60:63], v[166:169], v[202:205], v[60:63]
	v_mfma_f32_16x16x32_bf16 v[56:59], v[174:177], v[202:205], v[56:59]
	v_mfma_f32_16x16x32_bf16 v[44:47], v[166:169], v[210:213], v[44:47]
	v_mfma_f32_16x16x32_bf16 v[40:43], v[174:177], v[210:213], v[40:43]
	v_mfma_f32_16x16x32_bf16 v[28:31], v[166:169], v[218:221], v[28:31]
	v_mfma_f32_16x16x32_bf16 v[24:27], v[174:177], v[218:221], v[24:27]
	v_mfma_f32_16x16x32_bf16 v[12:15], v[166:169], v[226:229], v[12:15]
	v_mfma_f32_16x16x32_bf16 v[8:11], v[174:177], v[226:229], v[8:11]
	v_mfma_f32_16x16x32_bf16 v[52:55], v[178:181], v[198:201], v[52:55]
	v_mfma_f32_16x16x32_bf16 v[48:51], v[190:193], v[198:201], v[48:51]
	v_mfma_f32_16x16x32_bf16 v[36:39], v[178:181], v[206:209], v[36:39]
	v_mfma_f32_16x16x32_bf16 v[32:35], v[190:193], v[206:209], v[32:35]
	v_mfma_f32_16x16x32_bf16 v[20:23], v[178:181], v[214:217], v[20:23]
	v_mfma_f32_16x16x32_bf16 v[16:19], v[190:193], v[214:217], v[16:19]
	v_mfma_f32_16x16x32_bf16 v[4:7], v[178:181], v[222:225], v[4:7]
	v_mfma_f32_16x16x32_bf16 v[0:3], v[190:193], v[222:225], v[0:3]
	v_mfma_f32_16x16x32_bf16 v[52:55], v[182:185], v[202:205], v[52:55]
	v_mfma_f32_16x16x32_bf16 v[48:51], v[194:197], v[202:205], v[48:51]
	v_mfma_f32_16x16x32_bf16 v[36:39], v[182:185], v[210:213], v[36:39]
	v_mfma_f32_16x16x32_bf16 v[32:35], v[194:197], v[210:213], v[32:35]
	v_mfma_f32_16x16x32_bf16 v[20:23], v[182:185], v[218:221], v[20:23]
	v_mfma_f32_16x16x32_bf16 v[16:19], v[194:197], v[218:221], v[16:19]
	v_mfma_f32_16x16x32_bf16 v[4:7], v[182:185], v[226:229], v[4:7]
	v_mfma_f32_16x16x32_bf16 v[0:3], v[194:197], v[226:229], v[0:3]
	s_setprio 0
	s_barrier
; #define PG8_STAGE(bufoff, gbase, voff) do { _Pragma("unroll") for (int _i = 0; _i < 2; ++_i) \
;         __builtin_amdgcn_global_load_lds((const unsigned*)((const char*)(gbase) + (voff)[_i]), (PG8_LAS unsigned*)(lds + (bufoff) + ldsw + _i * 8192), 16, 0, 0); } while (0)
; #define PG8_LDA(dst, b, h) do { _Pragma("unroll") for (int m = 0; m < 4; ++m) _Pragma("unroll") for (int k = 0; k < 2; ++k) dst[m][k] = *(const PG8_LAS bf16x8*)(lds + PG8_SA(b, h) + aoff + m * 2048 + k * 1024); } while (0)
; #define PG8_LDB(dst, b, h) do { _Pragma("unroll") for (int n = 0; n < 2; ++n) _Pragma("unroll") for (int k = 0; k < 2; ++k) dst[n][k] = *(const PG8_LAS bf16x8*)(lds + PG8_SB(b, h) + boff + n * 2048 + k * 1024); } while (0)
; #define PG8_MMA(ai, bj, At, Bt) do { __builtin_amdgcn_s_setprio(1); _Pragma("unroll") for (int m = 0; m < 4; ++m) _Pragma("unroll") for (int n = 0; n < 2; ++n) _Pragma("unroll") for (int k = 0; k < 2; ++k) \
;         acc[ai][bj][m][n] = __builtin_amdgcn_mfma_f32_16x16x32_bf16(Bt[n][k], At[m][k], acc[ai][bj][m][n], 0, 0, 0); __builtin_amdgcn_s_setprio(0); } while (0)
; #define PG8_WAIT_V(n) asm volatile("s_waitcnt vmcnt(" #n ")" ::: "memory")
; #define PG8_WAIT_L(n) asm volatile("s_waitcnt lgkmcnt(" #n ")" ::: "memory")
; #define PG8_BAR __builtin_amdgcn_s_barrier()
; #define PG8_SCHED __builtin_amdgcn_sched_barrier(0)
; template <class Epi, class Sched, bool ALIGN_EPI = false, bool SP2 = false>
; __device__ __forceinline__ void gemm_phase(PG8_LAS unsigned char* lds, const Gemm g, const Sched& S, const Epi& E) {
;     ...
;             PG8_LDB(B0, 1, 0); PG8_LDB(B1, 1, 1); PG8_SCHED; PG8_LDA(At, 1, 0); PG8_STAGE(PG8_SA(0, 1), a2 + hstepA, voffA);
;             PG8_WAIT_V(8); PG8_WAIT_L(0); PG8_BAR; PG8_MMA(0, 0, At, B0); PG8_MMA(0, 1, At, B1); PG8_BAR; PG8_SCHED;
;             PG8_LDA(At, 1, 1); PG8_STAGE(PG8_SB(1, 0), b3, voffB); PG8_STAGE(PG8_SB(1, 1), b3 + hstep, voffB); PG8_STAGE(PG8_SA(1, 0), a3, voffA);
;             PG8_WAIT_V(8); PG8_WAIT_L(0); PG8_BAR; PG8_MMA(1, 0, At, B0); PG8_MMA(1, 1, At, B1); PG8_BAR; PG8_SCHED;
	s_add_i32 s64, 0, 0x18000
	s_add_i32 s65, 0, 0x1c000
	v_add_u32_e32 v174, s64, v157
	v_add_u32_e32 v194, s65, v157
	ds_read_b128 v[162:165], v174
	ds_read_b128 v[166:169], v174 offset:1024
	ds_read_b128 v[170:173], v174 offset:2048
	ds_read_b128 v[174:177], v174 offset:3072
	ds_read_b128 v[178:181], v194
	ds_read_b128 v[182:185], v194 offset:1024
	ds_read_b128 v[190:193], v194 offset:2048
	ds_read_b128 v[194:197], v194 offset:3072
	s_mov_b64 vcc, s[36:37]
	s_add_u32 s36, s36, 0x20000
	s_addc_u32 s37, s37, 0
	s_mov_b32 m0, s49
	ds_read_b128 v[198:201], v161 offset:32768
	ds_read_b128 v[202:205], v161 offset:33792
	ds_read_b128 v[206:209], v161 offset:34816
	ds_read_b128 v[210:213], v161 offset:35840
	ds_read_b128 v[214:217], v161 offset:36864
	ds_read_b128 v[218:221], v161 offset:37888
	ds_read_b128 v[222:225], v161 offset:38912
	global_load_lds_dwordx4 v130, s[36:37]
	s_mov_b32 m0, s50
	ds_read_b128 v[226:229], v161 offset:39936
	global_load_lds_dwordx4 v132, s[36:37]
	s_waitcnt vmcnt(8) lgkmcnt(0)
	s_setprio 1
	s_barrier
	v_mfma_f32_16x16x32_bf16 v[124:127], v[162:165], v[198:201], v[124:127]
	v_mfma_f32_16x16x32_bf16 v[120:123], v[170:173], v[198:201], v[120:123]
	v_mfma_f32_16x16x32_bf16 v[108:111], v[162:165], v[206:209], v[108:111]
	v_mfma_f32_16x16x32_bf16 v[104:107], v[170:173], v[206:209], v[104:107]
	v_mfma_f32_16x16x32_bf16 v[92:95], v[162:165], v[214:217], v[92:95]
	v_mfma_f32_16x16x32_bf16 v[88:91], v[170:173], v[214:217], v[88:91]
	v_mfma_f32_16x16x32_bf16 v[76:79], v[162:165], v[222:225], v[76:79]
	v_mfma_f32_16x16x32_bf16 v[72:75], v[170:173], v[222:225], v[72:75]
	v_mfma_f32_16x16x32_bf16 v[124:127], v[166:169], v[202:205], v[124:127]
	v_mfma_f32_16x16x32_bf16 v[120:123], v[174:177], v[202:205], v[120:123]
	v_mfma_f32_16x16x32_bf16 v[108:111], v[166:169], v[210:213], v[108:111]
	v_mfma_f32_16x16x32_bf16 v[104:107], v[174:177], v[210:213], v[104:107]
	v_mfma_f32_16x16x32_bf16 v[92:95], v[166:169], v[218:221], v[92:95]
	v_mfma_f32_16x16x32_bf16 v[88:91], v[174:177], v[218:221], v[88:91]
	v_mfma_f32_16x16x32_bf16 v[76:79], v[166:169], v[226:229], v[76:79]
	v_mfma_f32_16x16x32_bf16 v[72:75], v[174:177], v[226:229], v[72:75]
	v_mfma_f32_16x16x32_bf16 v[116:119], v[178:181], v[198:201], v[116:119]
	v_mfma_f32_16x16x32_bf16 v[112:115], v[190:193], v[198:201], v[112:115]
	v_mfma_f32_16x16x32_bf16 v[100:103], v[178:181], v[206:209], v[100:103]
	v_mfma_f32_16x16x32_bf16 v[96:99], v[190:193], v[206:209], v[96:99]
	v_mfma_f32_16x16x32_bf16 v[84:87], v[178:181], v[214:217], v[84:87]
	v_mfma_f32_16x16x32_bf16 v[80:83], v[190:193], v[214:217], v[80:83]
	v_mfma_f32_16x16x32_bf16 v[68:71], v[178:181], v[222:225], v[68:71]
	v_mfma_f32_16x16x32_bf16 v[64:67], v[190:193], v[222:225], v[64:67]
	v_mfma_f32_16x16x32_bf16 v[116:119], v[182:185], v[202:205], v[116:119]
	v_mfma_f32_16x16x32_bf16 v[112:115], v[194:197], v[202:205], v[112:115]
	v_mfma_f32_16x16x32_bf16 v[100:103], v[182:185], v[210:213], v[100:103]
	v_mfma_f32_16x16x32_bf16 v[96:99], v[194:197], v[210:213], v[96:99]
	v_mfma_f32_16x16x32_bf16 v[84:87], v[182:185], v[218:221], v[84:87]
	v_mfma_f32_16x16x32_bf16 v[80:83], v[194:197], v[218:221], v[80:83]
	v_mfma_f32_16x16x32_bf16 v[68:71], v[182:185], v[226:229], v[68:71]
	v_mfma_f32_16x16x32_bf16 v[64:67], v[194:197], v[226:229], v[64:67]
	s_setprio 0
	s_barrier
	s_add_i32 s36, s64, s47
	s_add_i32 m0, s36, 0xffffff80
	ds_read_b128 v[198:201], v161 offset:49152
	ds_read_b128 v[202:205], v161 offset:50176
	ds_read_b128 v[206:209], v161 offset:51200
	ds_read_b128 v[210:213], v161 offset:52224
	global_load_lds_dwordx4 v136, s[100:101] offset:128
	s_add_i32 m0, s36, 0x1f80
	s_add_i32 s36, s65, s47
	global_load_lds_dwordx4 v134, s[100:101] offset:128
	s_add_i32 m0, s36, 0xffffff80
	s_add_u32 s100, s100, s16
	s_addc_u32 s101, s101, s17
	global_load_lds_dwordx4 v136, s[100:101] offset:128
	s_add_i32 m0, s36, 0x1f80
	ds_read_b128 v[222:225], v161 offset:55296
	global_load_lds_dwordx4 v134, s[100:101] offset:128
	s_add_i32 m0, s51, 0xffffff80
	ds_read_b128 v[218:221], v161 offset:54272
	global_load_lds_dwordx4 v130, vcc offset:128
	s_add_i32 m0, s52, 0xffffff80
	ds_read_b128 v[214:217], v161 offset:53248
	global_load_lds_dwordx4 v132, vcc offset:128
	ds_read_b128 v[226:229], v161 offset:56320
	s_waitcnt vmcnt(8) lgkmcnt(0)
	s_setprio 1
	s_barrier
	v_mfma_f32_16x16x32_bf16 v[60:63], v[162:165], v[198:201], v[60:63]
	v_mfma_f32_16x16x32_bf16 v[56:59], v[170:173], v[198:201], v[56:59]
	v_mfma_f32_16x16x32_bf16 v[44:47], v[162:165], v[206:209], v[44:47]
	v_mfma_f32_16x16x32_bf16 v[40:43], v[170:173], v[206:209], v[40:43]
	v_mfma_f32_16x16x32_bf16 v[28:31], v[162:165], v[214:217], v[28:31]
	v_mfma_f32_16x16x32_bf16 v[24:27], v[170:173], v[214:217], v[24:27]
	v_mfma_f32_16x16x32_bf16 v[12:15], v[162:165], v[222:225], v[12:15]
	v_mfma_f32_16x16x32_bf16 v[8:11], v[170:173], v[222:225], v[8:11]
	v_mfma_f32_16x16x32_bf16 v[60:63], v[166:169], v[202:205], v[60:63]
	v_mfma_f32_16x16x32_bf16 v[56:59], v[174:177], v[202:205], v[56:59]
	v_mfma_f32_16x16x32_bf16 v[44:47], v[166:169], v[210:213], v[44:47]
	v_mfma_f32_16x16x32_bf16 v[40:43], v[174:177], v[210:213], v[40:43]
	v_mfma_f32_16x16x32_bf16 v[28:31], v[166:169], v[218:221], v[28:31]
	v_mfma_f32_16x16x32_bf16 v[24:27], v[174:177], v[218:221], v[24:27]
	v_mfma_f32_16x16x32_bf16 v[12:15], v[166:169], v[226:229], v[12:15]
	v_mfma_f32_16x16x32_bf16 v[8:11], v[174:177], v[226:229], v[8:11]
	v_mfma_f32_16x16x32_bf16 v[52:55], v[178:181], v[198:201], v[52:55]
	v_mfma_f32_16x16x32_bf16 v[48:51], v[190:193], v[198:201], v[48:51]
	v_mfma_f32_16x16x32_bf16 v[36:39], v[178:181], v[206:209], v[36:39]
	v_mfma_f32_16x16x32_bf16 v[32:35], v[190:193], v[206:209], v[32:35]
	v_mfma_f32_16x16x32_bf16 v[20:23], v[178:181], v[214:217], v[20:23]
	v_mfma_f32_16x16x32_bf16 v[16:19], v[190:193], v[214:217], v[16:19]
	v_mfma_f32_16x16x32_bf16 v[4:7], v[178:181], v[222:225], v[4:7]
	v_mfma_f32_16x16x32_bf16 v[0:3], v[190:193], v[222:225], v[0:3]
	v_mfma_f32_16x16x32_bf16 v[52:55], v[182:185], v[202:205], v[52:55]
	v_mfma_f32_16x16x32_bf16 v[48:51], v[194:197], v[202:205], v[48:51]
	v_mfma_f32_16x16x32_bf16 v[36:39], v[182:185], v[210:213], v[36:39]
	v_mfma_f32_16x16x32_bf16 v[32:35], v[194:197], v[210:213], v[32:35]
	v_mfma_f32_16x16x32_bf16 v[20:23], v[182:185], v[218:221], v[20:23]
	v_mfma_f32_16x16x32_bf16 v[16:19], v[194:197], v[218:221], v[16:19]
	v_mfma_f32_16x16x32_bf16 v[4:7], v[182:185], v[226:229], v[4:7]
	v_mfma_f32_16x16x32_bf16 v[0:3], v[194:197], v[226:229], v[0:3]
	s_setprio 0
	s_barrier
	s_add_u32 s10, s10, 0x100
	s_addc_u32 s11, s11, 0
	s_add_u32 s38, s38, 0x100
	s_addc_u32 s39, s39, 0
	s_cmp_ge_i32 s63, s53
	s_mov_b32 s36, s63
	s_cbranch_scc0 .LBB0_1480

; #define PG8_STAGE(bufoff, gbase, voff) do { _Pragma("unroll") for (int _i = 0; _i < 2; ++_i) \
;         __builtin_amdgcn_global_load_lds((const unsigned*)((const char*)(gbase) + (voff)[_i]), (PG8_LAS unsigned*)(lds + (bufoff) + ldsw + _i * 8192), 16, 0, 0); } while (0)
; #define PG8_LDA(dst, b, h) do { _Pragma("unroll") for (int m = 0; m < 4; ++m) _Pragma("unroll") for (int k = 0; k < 2; ++k) dst[m][k] = *(const PG8_LAS bf16x8*)(lds + PG8_SA(b, h) + aoff + m * 2048 + k * 1024); } while (0)
; #define PG8_LDB(dst, b, h) do { _Pragma("unroll") for (int n = 0; n < 2; ++n) _Pragma("unroll") for (int k = 0; k < 2; ++k) dst[n][k] = *(const PG8_LAS bf16x8*)(lds + PG8_SB(b, h) + boff + n * 2048 + k * 1024); } while (0)
; #define PG8_WAIT_V(n) asm volatile("s_waitcnt vmcnt(" #n ")" ::: "memory")
; #define PG8_WAIT_L(n) asm volatile("s_waitcnt lgkmcnt(" #n ")" ::: "memory")
; #define PG8_BAR __builtin_amdgcn_s_barrier()
; #define PG8_SCHED __builtin_amdgcn_sched_barrier(0)
; template <class Epi, class Sched, bool ALIGN_EPI = false, bool SP2 = false>
; __device__ __forceinline__ void gemm_phase(PG8_LAS unsigned char* lds, const Gemm g, const Sched& S, const Epi& E) {
;     ...
;         const char* nA = has_next ? (const char*)g.A + (size_t)nxt.pm * tstepA : cA; const char* nB = has_next ? (const char*)g.Bt + (size_t)nxt.pn * tstep : cB;
;         for (int t = 0; t < nt; t += 2) {
;             const bool last = (t == nt - 2);
;             const char* a1 = cA + (size_t)(t + 1) * kstep;
;             const char* a2 = last ? nA : cA + (size_t)(t + 2) * kstep; const char* b2 = last ? nB : cB + (size_t)(t + 2) * kstep;
;             const char* a3 = a2 + kstep; const char* b3 = b2 + kstep;
;             if (last && has_next) S.a_ready(nxt);
;             if constexpr (SP2) {
;             PG8_LDB(B0, 0, 0); PG8_LDB(B1, 0, 1); PG8_SCHED; PG8_LDA(At, 0, 0); PG8_STAGE(PG8_SA(1, 1), a1 + hstepA, voffA);
;             PG8_WAIT_V(8); PG8_WAIT_L(0); PG8_BAR; PG8_MMA(0, 0, At, B0); PG8_MMA(0, 1, At, B1); PG8_BAR; PG8_SCHED;
;             PG8_LDA(At, 0, 1); PG8_STAGE(PG8_SB(0, 0), b2, voffB); PG8_STAGE(PG8_SB(0, 1), b2 + hstep, voffB); PG8_STAGE(PG8_SA(0, 0), a2, voffA);
;             PG8_WAIT_V(8); PG8_WAIT_L(0); PG8_BAR; PG8_MMA(1, 0, At, B0); PG8_MMA(1, 1, At, B1); PG8_BAR; PG8_SCHED;
.LBB0_1501:
	ds_read_b128 v[68:71], v196
	ds_read_b128 v[72:75], v196 offset:1024
	ds_read_b128 v[76:79], v196 offset:2048
	ds_read_b128 v[80:83], v196 offset:3072
	ds_read_b128 v[84:87], v197
	ds_read_b128 v[88:91], v197 offset:1024
	ds_read_b128 v[182:185], v197 offset:2048
	ds_read_b128 v[202:205], v197 offset:3072
	s_add_i32 s38, s14, 2
	s_add_u32 s39, s4, 0xffff0080
	s_addc_u32 s15, s5, -1
	s_cmp_eq_u32 s58, s14
	s_cselect_b32 s14, s35, s39
	s_cselect_b32 s15, s27, s15
	s_cselect_b32 s73, s29, s37
	s_cselect_b32 s72, s28, s36
	s_add_i32 m0, s47, 0xc000
	ds_read_b128 v[206:209], v198
	ds_read_b128 v[210:213], v198 offset:1024
	ds_read_b128 v[214:217], v198 offset:2048
	ds_read_b128 v[218:221], v198 offset:3072
	ds_read_b128 v[222:225], v198 offset:4096
	ds_read_b128 v[226:229], v198 offset:5120
	ds_read_b128 v[230:233], v198 offset:6144
	global_load_lds_dwordx4 v174, s[4:5]
	s_add_i32 m0, s47, 0xe000
	ds_read_b128 v[234:237], v198 offset:7168
	global_load_lds_dwordx4 v176, s[4:5]
	s_waitcnt vmcnt(8) lgkmcnt(0)
	s_setprio 1
	s_barrier
	v_mfma_f32_16x16x32_bf16 v[152:155], v[68:71], v[206:209], v[152:155]
	v_mfma_f32_16x16x32_bf16 v[148:151], v[76:79], v[206:209], v[148:151]
	v_mfma_f32_16x16x32_bf16 v[136:139], v[68:71], v[214:217], v[136:139]
	v_mfma_f32_16x16x32_bf16 v[132:135], v[76:79], v[214:217], v[132:135]
	v_mfma_f32_16x16x32_bf16 v[120:123], v[68:71], v[222:225], v[120:123]
	v_mfma_f32_16x16x32_bf16 v[116:119], v[76:79], v[222:225], v[116:119]
	v_mfma_f32_16x16x32_bf16 v[104:107], v[68:71], v[230:233], v[104:107]
	v_mfma_f32_16x16x32_bf16 v[100:103], v[76:79], v[230:233], v[100:103]
	v_mfma_f32_16x16x32_bf16 v[152:155], v[72:75], v[210:213], v[152:155]
	v_mfma_f32_16x16x32_bf16 v[148:151], v[80:83], v[210:213], v[148:151]
	v_mfma_f32_16x16x32_bf16 v[136:139], v[72:75], v[218:221], v[136:139]
	v_mfma_f32_16x16x32_bf16 v[132:135], v[80:83], v[218:221], v[132:135]
	v_mfma_f32_16x16x32_bf16 v[120:123], v[72:75], v[226:229], v[120:123]
	v_mfma_f32_16x16x32_bf16 v[116:119], v[80:83], v[226:229], v[116:119]
	v_mfma_f32_16x16x32_bf16 v[104:107], v[72:75], v[234:237], v[104:107]
	v_mfma_f32_16x16x32_bf16 v[100:103], v[80:83], v[234:237], v[100:103]
	v_mfma_f32_16x16x32_bf16 v[144:147], v[84:87], v[206:209], v[144:147]
	v_mfma_f32_16x16x32_bf16 v[140:143], v[182:185], v[206:209], v[140:143]
	v_mfma_f32_16x16x32_bf16 v[128:131], v[84:87], v[214:217], v[128:131]
	v_mfma_f32_16x16x32_bf16 v[124:127], v[182:185], v[214:217], v[124:127]
	v_mfma_f32_16x16x32_bf16 v[112:115], v[84:87], v[222:225], v[112:115]
	v_mfma_f32_16x16x32_bf16 v[108:111], v[182:185], v[222:225], v[108:111]
	v_mfma_f32_16x16x32_bf16 v[96:99], v[84:87], v[230:233], v[96:99]
	v_mfma_f32_16x16x32_bf16 v[92:95], v[182:185], v[230:233], v[92:95]
	v_mfma_f32_16x16x32_bf16 v[144:147], v[88:91], v[210:213], v[144:147]
	v_mfma_f32_16x16x32_bf16 v[140:143], v[202:205], v[210:213], v[140:143]
	v_mfma_f32_16x16x32_bf16 v[128:131], v[88:91], v[218:221], v[128:131]
	v_mfma_f32_16x16x32_bf16 v[124:127], v[202:205], v[218:221], v[124:127]
	v_mfma_f32_16x16x32_bf16 v[112:115], v[88:91], v[226:229], v[112:115]
	v_mfma_f32_16x16x32_bf16 v[108:111], v[202:205], v[226:229], v[108:111]
	v_mfma_f32_16x16x32_bf16 v[96:99], v[88:91], v[234:237], v[96:99]
	v_mfma_f32_16x16x32_bf16 v[92:95], v[202:205], v[234:237], v[92:95]
	s_setprio 0
	s_barrier
	s_add_i32 s39, s61, s45
	s_mov_b32 m0, s39
	ds_read_b128 v[206:209], v198 offset:16384
	ds_read_b128 v[210:213], v198 offset:17408
	ds_read_b128 v[214:217], v198 offset:18432
	ds_read_b128 v[218:221], v198 offset:19456
	global_load_lds_dwordx4 v156, s[72:73]
	s_add_i32 m0, s39, 0x2000
	s_mov_b64 s[100:101], s[72:73]
	s_add_i32 s39, s62, s45
	global_load_lds_dwordx4 v158, s[72:73]
	s_mov_b32 m0, s39
	s_add_u32 s72, s72, s16
	s_addc_u32 s73, s73, s17
	global_load_lds_dwordx4 v156, s[72:73]
	s_add_i32 m0, s39, 0x2000
	ds_read_b128 v[230:233], v198 offset:22528
	global_load_lds_dwordx4 v158, s[72:73]
	s_mov_b32 m0, s47
	ds_read_b128 v[226:229], v198 offset:21504
	global_load_lds_dwordx4 v160, s[14:15]
	s_mov_b32 m0, s48
	ds_read_b128 v[222:225], v198 offset:20480
	global_load_lds_dwordx4 v162, s[14:15]
	ds_read_b128 v[234:237], v198 offset:23552
	s_waitcnt vmcnt(8) lgkmcnt(0)
	s_setprio 1
	s_barrier
	v_mfma_f32_16x16x32_bf16 v[64:67], v[68:71], v[206:209], v[64:67]
	v_mfma_f32_16x16x32_bf16 v[60:63], v[76:79], v[206:209], v[60:63]
	v_mfma_f32_16x16x32_bf16 v[48:51], v[68:71], v[214:217], v[48:51]
	v_mfma_f32_16x16x32_bf16 v[44:47], v[76:79], v[214:217], v[44:47]
	v_mfma_f32_16x16x32_bf16 v[32:35], v[68:71], v[222:225], v[32:35]
	v_mfma_f32_16x16x32_bf16 v[28:31], v[76:79], v[222:225], v[28:31]
	v_mfma_f32_16x16x32_bf16 v[16:19], v[68:71], v[230:233], v[16:19]
	v_mfma_f32_16x16x32_bf16 v[12:15], v[76:79], v[230:233], v[12:15]
	v_mfma_f32_16x16x32_bf16 v[64:67], v[72:75], v[210:213], v[64:67]
	v_mfma_f32_16x16x32_bf16 v[60:63], v[80:83], v[210:213], v[60:63]
	v_mfma_f32_16x16x32_bf16 v[48:51], v[72:75], v[218:221], v[48:51]
	v_mfma_f32_16x16x32_bf16 v[44:47], v[80:83], v[218:221], v[44:47]
	v_mfma_f32_16x16x32_bf16 v[32:35], v[72:75], v[226:229], v[32:35]
	v_mfma_f32_16x16x32_bf16 v[28:31], v[80:83], v[226:229], v[28:31]
	v_mfma_f32_16x16x32_bf16 v[16:19], v[72:75], v[234:237], v[16:19]
	v_mfma_f32_16x16x32_bf16 v[12:15], v[80:83], v[234:237], v[12:15]
	v_mfma_f32_16x16x32_bf16 v[56:59], v[84:87], v[206:209], v[56:59]
	v_mfma_f32_16x16x32_bf16 v[52:55], v[182:185], v[206:209], v[52:55]
	v_mfma_f32_16x16x32_bf16 v[40:43], v[84:87], v[214:217], v[40:43]
	v_mfma_f32_16x16x32_bf16 v[36:39], v[182:185], v[214:217], v[36:39]
	v_mfma_f32_16x16x32_bf16 v[24:27], v[84:87], v[222:225], v[24:27]
	v_mfma_f32_16x16x32_bf16 v[20:23], v[182:185], v[222:225], v[20:23]
	v_mfma_f32_16x16x32_bf16 v[8:11], v[84:87], v[230:233], v[8:11]
	v_mfma_f32_16x16x32_bf16 v[4:7], v[182:185], v[230:233], v[4:7]
	v_mfma_f32_16x16x32_bf16 v[56:59], v[88:91], v[210:213], v[56:59]
	v_mfma_f32_16x16x32_bf16 v[52:55], v[202:205], v[210:213], v[52:55]
	v_mfma_f32_16x16x32_bf16 v[40:43], v[88:91], v[218:221], v[40:43]
	v_mfma_f32_16x16x32_bf16 v[36:39], v[202:205], v[218:221], v[36:39]
	v_mfma_f32_16x16x32_bf16 v[24:27], v[88:91], v[226:229], v[24:27]
	v_mfma_f32_16x16x32_bf16 v[20:23], v[202:205], v[226:229], v[20:23]
	v_mfma_f32_16x16x32_bf16 v[8:11], v[88:91], v[234:237], v[8:11]
	v_mfma_f32_16x16x32_bf16 v[4:7], v[202:205], v[234:237], v[4:7]
	s_setprio 0
	s_barrier
; #define PG8_STAGE(bufoff, gbase, voff) do { _Pragma("unroll") for (int _i = 0; _i < 2; ++_i) \
;         __builtin_amdgcn_global_load_lds((const unsigned*)((const char*)(gbase) + (voff)[_i]), (PG8_LAS unsigned*)(lds + (bufoff) + ldsw + _i * 8192), 16, 0, 0); } while (0)
; #define PG8_LDA(dst, b, h) do { _Pragma("unroll") for (int m = 0; m < 4; ++m) _Pragma("unroll") for (int k = 0; k < 2; ++k) dst[m][k] = *(const PG8_LAS bf16x8*)(lds + PG8_SA(b, h) + aoff + m * 2048 + k * 1024); } while (0)
; #define PG8_LDB(dst, b, h) do { _Pragma("unroll") for (int n = 0; n < 2; ++n) _Pragma("unroll") for (int k = 0; k < 2; ++k) dst[n][k] = *(const PG8_LAS bf16x8*)(lds + PG8_SB(b, h) + boff + n * 2048 + k * 1024); } while (0)
; #define PG8_MMA(ai, bj, At, Bt) do { __builtin_amdgcn_s_setprio(1); _Pragma("unroll") for (int m = 0; m < 4; ++m) _Pragma("unroll") for (int n = 0; n < 2; ++n) _Pragma("unroll") for (int k = 0; k < 2; ++k) \
;         acc[ai][bj][m][n] = __builtin_amdgcn_mfma_f32_16x16x32_bf16(Bt[n][k], At[m][k], acc[ai][bj][m][n], 0, 0, 0); __builtin_amdgcn_s_setprio(0); } while (0)
; #define PG8_WAIT_V(n) asm volatile("s_waitcnt vmcnt(" #n ")" ::: "memory")
; #define PG8_WAIT_L(n) asm volatile("s_waitcnt lgkmcnt(" #n ")" ::: "memory")
; #define PG8_BAR __builtin_amdgcn_s_barrier()
; #define PG8_SCHED __builtin_amdgcn_sched_barrier(0)
; template <class Epi, class Sched, bool ALIGN_EPI = false, bool SP2 = false>
; __device__ __forceinline__ void gemm_phase(PG8_LAS unsigned char* lds, const Gemm g, const Sched& S, const Epi& E) {
;     ...
;             PG8_LDB(B0, 1, 0); PG8_LDB(B1, 1, 1); PG8_SCHED; PG8_LDA(At, 1, 0); PG8_STAGE(PG8_SA(0, 1), a2 + hstepA, voffA);
;             PG8_WAIT_V(8); PG8_WAIT_L(0); PG8_BAR; PG8_MMA(0, 0, At, B0); PG8_MMA(0, 1, At, B1); PG8_BAR; PG8_SCHED;
;             PG8_LDA(At, 1, 1); PG8_STAGE(PG8_SB(1, 0), b3, voffB); PG8_STAGE(PG8_SB(1, 1), b3 + hstep, voffB); PG8_STAGE(PG8_SA(1, 0), a3, voffA);
;             PG8_WAIT_V(8); PG8_WAIT_L(0); PG8_BAR; PG8_MMA(1, 0, At, B0); PG8_MMA(1, 1, At, B1); PG8_BAR; PG8_SCHED;
	s_add_i32 s39, 0, 0x18000
	s_add_i32 s71, 0, 0x1c000
	v_add_u32_e32 v80, s39, v191
	v_add_u32_e32 v164, s71, v191
	ds_read_b128 v[68:71], v80
	ds_read_b128 v[72:75], v80 offset:1024
	ds_read_b128 v[76:79], v80 offset:2048
	ds_read_b128 v[80:83], v80 offset:3072
	ds_read_b128 v[84:87], v164
	ds_read_b128 v[88:91], v164 offset:1024
	ds_read_b128 v[182:185], v164 offset:2048
	ds_read_b128 v[202:205], v164 offset:3072
	s_mov_b64 vcc, s[14:15]
	s_add_u32 s14, s14, 0x10000
	s_addc_u32 s15, s15, 0
	s_mov_b32 m0, s49
	ds_read_b128 v[206:209], v198 offset:32768
	ds_read_b128 v[210:213], v198 offset:33792
	ds_read_b128 v[214:217], v198 offset:34816
	ds_read_b128 v[218:221], v198 offset:35840
	ds_read_b128 v[222:225], v198 offset:36864
	ds_read_b128 v[226:229], v198 offset:37888
	ds_read_b128 v[230:233], v198 offset:38912
	global_load_lds_dwordx4 v160, s[14:15]
	s_mov_b32 m0, s50
	ds_read_b128 v[234:237], v198 offset:39936
	global_load_lds_dwordx4 v162, s[14:15]
	s_waitcnt vmcnt(8) lgkmcnt(0)
	s_setprio 1
	s_barrier
	v_mfma_f32_16x16x32_bf16 v[152:155], v[68:71], v[206:209], v[152:155]
	v_mfma_f32_16x16x32_bf16 v[148:151], v[76:79], v[206:209], v[148:151]
	v_mfma_f32_16x16x32_bf16 v[136:139], v[68:71], v[214:217], v[136:139]
	v_mfma_f32_16x16x32_bf16 v[132:135], v[76:79], v[214:217], v[132:135]
	v_mfma_f32_16x16x32_bf16 v[120:123], v[68:71], v[222:225], v[120:123]
	v_mfma_f32_16x16x32_bf16 v[116:119], v[76:79], v[222:225], v[116:119]
	v_mfma_f32_16x16x32_bf16 v[104:107], v[68:71], v[230:233], v[104:107]
	v_mfma_f32_16x16x32_bf16 v[100:103], v[76:79], v[230:233], v[100:103]
	v_mfma_f32_16x16x32_bf16 v[152:155], v[72:75], v[210:213], v[152:155]
	v_mfma_f32_16x16x32_bf16 v[148:151], v[80:83], v[210:213], v[148:151]
	v_mfma_f32_16x16x32_bf16 v[136:139], v[72:75], v[218:221], v[136:139]
	v_mfma_f32_16x16x32_bf16 v[132:135], v[80:83], v[218:221], v[132:135]
	v_mfma_f32_16x16x32_bf16 v[120:123], v[72:75], v[226:229], v[120:123]
	v_mfma_f32_16x16x32_bf16 v[116:119], v[80:83], v[226:229], v[116:119]
	v_mfma_f32_16x16x32_bf16 v[104:107], v[72:75], v[234:237], v[104:107]
	v_mfma_f32_16x16x32_bf16 v[100:103], v[80:83], v[234:237], v[100:103]
	v_mfma_f32_16x16x32_bf16 v[144:147], v[84:87], v[206:209], v[144:147]
	v_mfma_f32_16x16x32_bf16 v[140:143], v[182:185], v[206:209], v[140:143]
	v_mfma_f32_16x16x32_bf16 v[128:131], v[84:87], v[214:217], v[128:131]
	v_mfma_f32_16x16x32_bf16 v[124:127], v[182:185], v[214:217], v[124:127]
	v_mfma_f32_16x16x32_bf16 v[112:115], v[84:87], v[222:225], v[112:115]
	v_mfma_f32_16x16x32_bf16 v[108:111], v[182:185], v[222:225], v[108:111]
	v_mfma_f32_16x16x32_bf16 v[96:99], v[84:87], v[230:233], v[96:99]
	v_mfma_f32_16x16x32_bf16 v[92:95], v[182:185], v[230:233], v[92:95]
	v_mfma_f32_16x16x32_bf16 v[144:147], v[88:91], v[210:213], v[144:147]
	v_mfma_f32_16x16x32_bf16 v[140:143], v[202:205], v[210:213], v[140:143]
	v_mfma_f32_16x16x32_bf16 v[128:131], v[88:91], v[218:221], v[128:131]
	v_mfma_f32_16x16x32_bf16 v[124:127], v[202:205], v[218:221], v[124:127]
	v_mfma_f32_16x16x32_bf16 v[112:115], v[88:91], v[226:229], v[112:115]
	v_mfma_f32_16x16x32_bf16 v[108:111], v[202:205], v[226:229], v[108:111]
	v_mfma_f32_16x16x32_bf16 v[96:99], v[88:91], v[234:237], v[96:99]
	v_mfma_f32_16x16x32_bf16 v[92:95], v[202:205], v[234:237], v[92:95]
	s_setprio 0
	s_barrier
	s_add_i32 s14, s39, s45
	s_add_i32 m0, s14, 0xffffff80
	ds_read_b128 v[206:209], v198 offset:49152
	ds_read_b128 v[210:213], v198 offset:50176
	ds_read_b128 v[214:217], v198 offset:51200
	ds_read_b128 v[218:221], v198 offset:52224
	global_load_lds_dwordx4 v156, s[100:101] offset:128
	s_add_i32 m0, s14, 0x1f80
	s_add_i32 s14, s71, s45
	global_load_lds_dwordx4 v158, s[100:101] offset:128
	s_add_i32 m0, s14, 0xffffff80
	ds_read_b128 v[234:237], v198 offset:56320
	global_load_lds_dwordx4 v156, s[72:73] offset:128
	s_add_i32 m0, s14, 0x1f80
	ds_read_b128 v[230:233], v198 offset:55296
	global_load_lds_dwordx4 v158, s[72:73] offset:128
	s_add_i32 m0, s56, 0xffffff80
	ds_read_b128 v[226:229], v198 offset:54272
	global_load_lds_dwordx4 v160, vcc offset:128
	s_add_i32 m0, s57, 0xffffff80
	ds_read_b128 v[222:225], v198 offset:53248
	global_load_lds_dwordx4 v162, vcc offset:128
	s_waitcnt vmcnt(8) lgkmcnt(0)
	s_setprio 1
	s_barrier
	v_mfma_f32_16x16x32_bf16 v[64:67], v[68:71], v[206:209], v[64:67]
	v_mfma_f32_16x16x32_bf16 v[60:63], v[76:79], v[206:209], v[60:63]
	v_mfma_f32_16x16x32_bf16 v[48:51], v[68:71], v[214:217], v[48:51]
	v_mfma_f32_16x16x32_bf16 v[44:47], v[76:79], v[214:217], v[44:47]
	v_mfma_f32_16x16x32_bf16 v[32:35], v[68:71], v[222:225], v[32:35]
	v_mfma_f32_16x16x32_bf16 v[28:31], v[76:79], v[222:225], v[28:31]
	v_mfma_f32_16x16x32_bf16 v[16:19], v[68:71], v[230:233], v[16:19]
	v_mfma_f32_16x16x32_bf16 v[12:15], v[76:79], v[230:233], v[12:15]
	v_mfma_f32_16x16x32_bf16 v[64:67], v[72:75], v[210:213], v[64:67]
	v_mfma_f32_16x16x32_bf16 v[60:63], v[80:83], v[210:213], v[60:63]
	v_mfma_f32_16x16x32_bf16 v[48:51], v[72:75], v[218:221], v[48:51]
	v_mfma_f32_16x16x32_bf16 v[44:47], v[80:83], v[218:221], v[44:47]
	v_mfma_f32_16x16x32_bf16 v[32:35], v[72:75], v[226:229], v[32:35]
	v_mfma_f32_16x16x32_bf16 v[28:31], v[80:83], v[226:229], v[28:31]
	v_mfma_f32_16x16x32_bf16 v[16:19], v[72:75], v[234:237], v[16:19]
	v_mfma_f32_16x16x32_bf16 v[12:15], v[80:83], v[234:237], v[12:15]
	v_mfma_f32_16x16x32_bf16 v[56:59], v[84:87], v[206:209], v[56:59]
	v_mfma_f32_16x16x32_bf16 v[52:55], v[182:185], v[206:209], v[52:55]
	v_mfma_f32_16x16x32_bf16 v[40:43], v[84:87], v[214:217], v[40:43]
	v_mfma_f32_16x16x32_bf16 v[36:39], v[182:185], v[214:217], v[36:39]
	v_mfma_f32_16x16x32_bf16 v[24:27], v[84:87], v[222:225], v[24:27]
	v_mfma_f32_16x16x32_bf16 v[20:23], v[182:185], v[222:225], v[20:23]
	v_mfma_f32_16x16x32_bf16 v[8:11], v[84:87], v[230:233], v[8:11]
	v_mfma_f32_16x16x32_bf16 v[4:7], v[182:185], v[230:233], v[4:7]
	v_mfma_f32_16x16x32_bf16 v[56:59], v[88:91], v[210:213], v[56:59]
	v_mfma_f32_16x16x32_bf16 v[52:55], v[202:205], v[210:213], v[52:55]
	v_mfma_f32_16x16x32_bf16 v[40:43], v[88:91], v[218:221], v[40:43]
	v_mfma_f32_16x16x32_bf16 v[36:39], v[202:205], v[218:221], v[36:39]
	v_mfma_f32_16x16x32_bf16 v[24:27], v[88:91], v[226:229], v[24:27]
	v_mfma_f32_16x16x32_bf16 v[20:23], v[202:205], v[226:229], v[20:23]
	v_mfma_f32_16x16x32_bf16 v[8:11], v[88:91], v[234:237], v[8:11]
	v_mfma_f32_16x16x32_bf16 v[4:7], v[202:205], v[234:237], v[4:7]
	s_setprio 0
	s_barrier
	s_add_u32 s4, s4, 0x100
	s_addc_u32 s5, s5, 0
	s_add_u32 s36, s36, 0x100
	s_addc_u32 s37, s37, 0
	s_cmp_ge_i32 s38, s54
	s_mov_b32 s14, s38
	s_cbranch_scc0 .LBB0_1501

; #define PG8_STAGE(bufoff, gbase, voff) do { _Pragma("unroll") for (int _i = 0; _i < 2; ++_i) \
;         __builtin_amdgcn_global_load_lds((const unsigned*)((const char*)(gbase) + (voff)[_i]), (PG8_LAS unsigned*)(lds + (bufoff) + ldsw + _i * 8192), 16, 0, 0); } while (0)
; #define PG8_LDA(dst, b, h) do { _Pragma("unroll") for (int m = 0; m < 4; ++m) _Pragma("unroll") for (int k = 0; k < 2; ++k) dst[m][k] = *(const PG8_LAS bf16x8*)(lds + PG8_SA(b, h) + aoff + m * 2048 + k * 1024); } while (0)
; #define PG8_LDB(dst, b, h) do { _Pragma("unroll") for (int n = 0; n < 2; ++n) _Pragma("unroll") for (int k = 0; k < 2; ++k) dst[n][k] = *(const PG8_LAS bf16x8*)(lds + PG8_SB(b, h) + boff + n * 2048 + k * 1024); } while (0)
; #define PG8_WAIT_V(n) asm volatile("s_waitcnt vmcnt(" #n ")" ::: "memory")
; #define PG8_WAIT_L(n) asm volatile("s_waitcnt lgkmcnt(" #n ")" ::: "memory")
; #define PG8_BAR __builtin_amdgcn_s_barrier()
; #define PG8_SCHED __builtin_amdgcn_sched_barrier(0)
; template <class Epi, class Sched, bool ALIGN_EPI = false, bool SP2 = false>
; __device__ __forceinline__ void gemm_phase(PG8_LAS unsigned char* lds, const Gemm g, const Sched& S, const Epi& E) {
;     ...
;         const char* nA = has_next ? (const char*)g.A + (size_t)nxt.pm * tstepA : cA; const char* nB = has_next ? (const char*)g.Bt + (size_t)nxt.pn * tstep : cB;
;         for (int t = 0; t < nt; t += 2) {
;             const bool last = (t == nt - 2);
;             const char* a1 = cA + (size_t)(t + 1) * kstep;
;             const char* a2 = last ? nA : cA + (size_t)(t + 2) * kstep; const char* b2 = last ? nB : cB + (size_t)(t + 2) * kstep;
;             const char* a3 = a2 + kstep; const char* b3 = b2 + kstep;
;             if (last && has_next) S.a_ready(nxt);
;             if constexpr (SP2) {
;             PG8_LDB(B0, 0, 0); PG8_LDB(B1, 0, 1); PG8_SCHED; PG8_LDA(At, 0, 0); PG8_STAGE(PG8_SA(1, 1), a1 + hstepA, voffA);
;             PG8_WAIT_V(8); PG8_WAIT_L(0); PG8_BAR; PG8_MMA(0, 0, At, B0); PG8_MMA(0, 1, At, B1); PG8_BAR; PG8_SCHED;
;             PG8_LDA(At, 0, 1); PG8_STAGE(PG8_SB(0, 0), b2, voffB); PG8_STAGE(PG8_SB(0, 1), b2 + hstep, voffB); PG8_STAGE(PG8_SA(0, 0), a2, voffA);
;             PG8_WAIT_V(8); PG8_WAIT_L(0); PG8_BAR; PG8_MMA(1, 0, At, B0); PG8_MMA(1, 1, At, B1); PG8_BAR; PG8_SCHED;
.LBB0_1679:
	ds_read_b128 v[120:123], v169
	ds_read_b128 v[128:131], v169 offset:1024
	ds_read_b128 v[136:139], v169 offset:2048
	ds_read_b128 v[140:143], v169 offset:3072
	ds_read_b128 v[160:163], v170
	ds_read_b128 v[172:175], v170 offset:1024
	ds_read_b128 v[176:179], v170 offset:2048
	ds_read_b128 v[180:183], v170 offset:3072
	s_add_i32 s90, s68, 2
	s_add_u32 s91, s8, 0xfffc0080
	s_addc_u32 s69, s9, -1
	s_cmp_eq_u32 s84, s68
	s_cselect_b32 s68, s89, s91
	s_cselect_b32 s69, s61, s69
	s_cselect_b32 s93, s63, s71
	s_cselect_b32 s92, s62, s70
	s_add_i32 m0, s67, 0xc000
	ds_read_b128 v[184:187], v171
	ds_read_b128 v[190:193], v171 offset:1024
	ds_read_b128 v[194:197], v171 offset:2048
	ds_read_b128 v[198:201], v171 offset:3072
	ds_read_b128 v[202:205], v171 offset:4096
	ds_read_b128 v[206:209], v171 offset:5120
	ds_read_b128 v[210:213], v171 offset:6144
	global_load_lds_dwordx4 v152, s[8:9]
	s_add_i32 m0, s67, 0xe000
	ds_read_b128 v[214:217], v171 offset:7168
	global_load_lds_dwordx4 v154, s[8:9]
	s_waitcnt vmcnt(8) lgkmcnt(0)
	s_setprio 1
	s_barrier
	v_mfma_f32_16x16x32_bf16 v[132:135], v[120:123], v[184:187], v[132:135]
	v_mfma_f32_16x16x32_bf16 v[124:127], v[136:139], v[184:187], v[124:127]
	v_mfma_f32_16x16x32_bf16 v[108:111], v[120:123], v[194:197], v[108:111]
	v_mfma_f32_16x16x32_bf16 v[104:107], v[136:139], v[194:197], v[104:107]
	v_mfma_f32_16x16x32_bf16 v[92:95], v[120:123], v[202:205], v[92:95]
	v_mfma_f32_16x16x32_bf16 v[88:91], v[136:139], v[202:205], v[88:91]
	v_mfma_f32_16x16x32_bf16 v[76:79], v[120:123], v[210:213], v[76:79]
	v_mfma_f32_16x16x32_bf16 v[72:75], v[136:139], v[210:213], v[72:75]
	v_mfma_f32_16x16x32_bf16 v[132:135], v[128:131], v[190:193], v[132:135]
	v_mfma_f32_16x16x32_bf16 v[124:127], v[140:143], v[190:193], v[124:127]
	v_mfma_f32_16x16x32_bf16 v[108:111], v[128:131], v[198:201], v[108:111]
	v_mfma_f32_16x16x32_bf16 v[104:107], v[140:143], v[198:201], v[104:107]
	v_mfma_f32_16x16x32_bf16 v[92:95], v[128:131], v[206:209], v[92:95]
	v_mfma_f32_16x16x32_bf16 v[88:91], v[140:143], v[206:209], v[88:91]
	v_mfma_f32_16x16x32_bf16 v[76:79], v[128:131], v[214:217], v[76:79]
	v_mfma_f32_16x16x32_bf16 v[72:75], v[140:143], v[214:217], v[72:75]
	v_mfma_f32_16x16x32_bf16 v[116:119], v[160:163], v[184:187], v[116:119]
	v_mfma_f32_16x16x32_bf16 v[112:115], v[176:179], v[184:187], v[112:115]
	v_mfma_f32_16x16x32_bf16 v[100:103], v[160:163], v[194:197], v[100:103]
	v_mfma_f32_16x16x32_bf16 v[96:99], v[176:179], v[194:197], v[96:99]
	v_mfma_f32_16x16x32_bf16 v[84:87], v[160:163], v[202:205], v[84:87]
	v_mfma_f32_16x16x32_bf16 v[80:83], v[176:179], v[202:205], v[80:83]
	v_mfma_f32_16x16x32_bf16 v[68:71], v[160:163], v[210:213], v[68:71]
	v_mfma_f32_16x16x32_bf16 v[64:67], v[176:179], v[210:213], v[64:67]
	v_mfma_f32_16x16x32_bf16 v[116:119], v[172:175], v[190:193], v[116:119]
	v_mfma_f32_16x16x32_bf16 v[112:115], v[180:183], v[190:193], v[112:115]
	v_mfma_f32_16x16x32_bf16 v[100:103], v[172:175], v[198:201], v[100:103]
	v_mfma_f32_16x16x32_bf16 v[96:99], v[180:183], v[198:201], v[96:99]
	v_mfma_f32_16x16x32_bf16 v[84:87], v[172:175], v[206:209], v[84:87]
	v_mfma_f32_16x16x32_bf16 v[80:83], v[180:183], v[206:209], v[80:83]
	v_mfma_f32_16x16x32_bf16 v[68:71], v[172:175], v[214:217], v[68:71]
	v_mfma_f32_16x16x32_bf16 v[64:67], v[180:183], v[214:217], v[64:67]
	s_setprio 0
	s_barrier
	s_add_i32 s91, s85, s73
	s_mov_b32 m0, s91
	ds_read_b128 v[184:187], v171 offset:16384
	ds_read_b128 v[190:193], v171 offset:17408
	ds_read_b128 v[194:197], v171 offset:18432
	ds_read_b128 v[198:201], v171 offset:19456
	global_load_lds_dwordx4 v150, s[92:93]
	s_add_i32 m0, s91, 0x2000
	s_mov_b64 s[100:101], s[92:93]
	s_add_i32 s91, s86, s73
	global_load_lds_dwordx4 v148, s[92:93]
	s_mov_b32 m0, s91
	s_add_u32 s92, s92, s10
	s_addc_u32 s93, s93, s11
	global_load_lds_dwordx4 v150, s[92:93]
	s_add_i32 m0, s91, 0x2000
	ds_read_b128 v[210:213], v171 offset:22528
	global_load_lds_dwordx4 v148, s[92:93]
	s_mov_b32 m0, s67
	ds_read_b128 v[206:209], v171 offset:21504
	global_load_lds_dwordx4 v144, s[68:69]
	s_mov_b32 m0, s75
	ds_read_b128 v[202:205], v171 offset:20480
	global_load_lds_dwordx4 v146, s[68:69]
	ds_read_b128 v[214:217], v171 offset:23552
	s_waitcnt vmcnt(8) lgkmcnt(0)
	s_setprio 1
	s_barrier
	v_mfma_f32_16x16x32_bf16 v[60:63], v[120:123], v[184:187], v[60:63]
	v_mfma_f32_16x16x32_bf16 v[56:59], v[136:139], v[184:187], v[56:59]
	v_mfma_f32_16x16x32_bf16 v[44:47], v[120:123], v[194:197], v[44:47]
	v_mfma_f32_16x16x32_bf16 v[40:43], v[136:139], v[194:197], v[40:43]
	v_mfma_f32_16x16x32_bf16 v[28:31], v[120:123], v[202:205], v[28:31]
	v_mfma_f32_16x16x32_bf16 v[24:27], v[136:139], v[202:205], v[24:27]
	v_mfma_f32_16x16x32_bf16 v[12:15], v[120:123], v[210:213], v[12:15]
	v_mfma_f32_16x16x32_bf16 v[8:11], v[136:139], v[210:213], v[8:11]
	v_mfma_f32_16x16x32_bf16 v[60:63], v[128:131], v[190:193], v[60:63]
	v_mfma_f32_16x16x32_bf16 v[56:59], v[140:143], v[190:193], v[56:59]
	v_mfma_f32_16x16x32_bf16 v[44:47], v[128:131], v[198:201], v[44:47]
	v_mfma_f32_16x16x32_bf16 v[40:43], v[140:143], v[198:201], v[40:43]
	v_mfma_f32_16x16x32_bf16 v[28:31], v[128:131], v[206:209], v[28:31]
	v_mfma_f32_16x16x32_bf16 v[24:27], v[140:143], v[206:209], v[24:27]
	v_mfma_f32_16x16x32_bf16 v[12:15], v[128:131], v[214:217], v[12:15]
	v_mfma_f32_16x16x32_bf16 v[8:11], v[140:143], v[214:217], v[8:11]
	v_mfma_f32_16x16x32_bf16 v[52:55], v[160:163], v[184:187], v[52:55]
	v_mfma_f32_16x16x32_bf16 v[48:51], v[176:179], v[184:187], v[48:51]
	v_mfma_f32_16x16x32_bf16 v[36:39], v[160:163], v[194:197], v[36:39]
	v_mfma_f32_16x16x32_bf16 v[32:35], v[176:179], v[194:197], v[32:35]
	v_mfma_f32_16x16x32_bf16 v[20:23], v[160:163], v[202:205], v[20:23]
	v_mfma_f32_16x16x32_bf16 v[16:19], v[176:179], v[202:205], v[16:19]
	v_mfma_f32_16x16x32_bf16 v[4:7], v[160:163], v[210:213], v[4:7]
	v_mfma_f32_16x16x32_bf16 v[0:3], v[176:179], v[210:213], v[0:3]
	v_mfma_f32_16x16x32_bf16 v[52:55], v[172:175], v[190:193], v[52:55]
	v_mfma_f32_16x16x32_bf16 v[48:51], v[180:183], v[190:193], v[48:51]
	v_mfma_f32_16x16x32_bf16 v[36:39], v[172:175], v[198:201], v[36:39]
	v_mfma_f32_16x16x32_bf16 v[32:35], v[180:183], v[198:201], v[32:35]
	v_mfma_f32_16x16x32_bf16 v[20:23], v[172:175], v[206:209], v[20:23]
	v_mfma_f32_16x16x32_bf16 v[16:19], v[180:183], v[206:209], v[16:19]
	v_mfma_f32_16x16x32_bf16 v[4:7], v[172:175], v[214:217], v[4:7]
	v_mfma_f32_16x16x32_bf16 v[0:3], v[180:183], v[214:217], v[0:3]
	s_setprio 0
	s_barrier
; #define PG8_STAGE(bufoff, gbase, voff) do { _Pragma("unroll") for (int _i = 0; _i < 2; ++_i) \
;         __builtin_amdgcn_global_load_lds((const unsigned*)((const char*)(gbase) + (voff)[_i]), (PG8_LAS unsigned*)(lds + (bufoff) + ldsw + _i * 8192), 16, 0, 0); } while (0)
; #define PG8_LDA(dst, b, h) do { _Pragma("unroll") for (int m = 0; m < 4; ++m) _Pragma("unroll") for (int k = 0; k < 2; ++k) dst[m][k] = *(const PG8_LAS bf16x8*)(lds + PG8_SA(b, h) + aoff + m * 2048 + k * 1024); } while (0)
; #define PG8_LDB(dst, b, h) do { _Pragma("unroll") for (int n = 0; n < 2; ++n) _Pragma("unroll") for (int k = 0; k < 2; ++k) dst[n][k] = *(const PG8_LAS bf16x8*)(lds + PG8_SB(b, h) + boff + n * 2048 + k * 1024); } while (0)
; #define PG8_MMA(ai, bj, At, Bt) do { __builtin_amdgcn_s_setprio(1); _Pragma("unroll") for (int m = 0; m < 4; ++m) _Pragma("unroll") for (int n = 0; n < 2; ++n) _Pragma("unroll") for (int k = 0; k < 2; ++k) \
;         acc[ai][bj][m][n] = __builtin_amdgcn_mfma_f32_16x16x32_bf16(Bt[n][k], At[m][k], acc[ai][bj][m][n], 0, 0, 0); __builtin_amdgcn_s_setprio(0); } while (0)
; #define PG8_WAIT_V(n) asm volatile("s_waitcnt vmcnt(" #n ")" ::: "memory")
; #define PG8_WAIT_L(n) asm volatile("s_waitcnt lgkmcnt(" #n ")" ::: "memory")
; #define PG8_BAR __builtin_amdgcn_s_barrier()
; #define PG8_SCHED __builtin_amdgcn_sched_barrier(0)
; template <class Epi, class Sched, bool ALIGN_EPI = false, bool SP2 = false>
; __device__ __forceinline__ void gemm_phase(PG8_LAS unsigned char* lds, const Gemm g, const Sched& S, const Epi& E) {
;     ...
;             PG8_LDB(B0, 1, 0); PG8_LDB(B1, 1, 1); PG8_SCHED; PG8_LDA(At, 1, 0); PG8_STAGE(PG8_SA(0, 1), a2 + hstepA, voffA);
;             PG8_WAIT_V(8); PG8_WAIT_L(0); PG8_BAR; PG8_MMA(0, 0, At, B0); PG8_MMA(0, 1, At, B1); PG8_BAR; PG8_SCHED;
;             PG8_LDA(At, 1, 1); PG8_STAGE(PG8_SB(1, 0), b3, voffB); PG8_STAGE(PG8_SB(1, 1), b3 + hstep, voffB); PG8_STAGE(PG8_SA(1, 0), a3, voffA);
;             PG8_WAIT_V(8); PG8_WAIT_L(0); PG8_BAR; PG8_MMA(1, 0, At, B0); PG8_MMA(1, 1, At, B1); PG8_BAR; PG8_SCHED;
	s_add_i32 s91, 0, 0x18000
	s_add_i32 s92, 0, 0x1c000
	v_add_u32_e32 v140, s91, v167
	v_add_u32_e32 v180, s92, v167
	ds_read_b128 v[120:123], v140
	ds_read_b128 v[128:131], v140 offset:1024
	ds_read_b128 v[136:139], v140 offset:2048
	ds_read_b128 v[140:143], v140 offset:3072
	ds_read_b128 v[160:163], v180
	ds_read_b128 v[172:175], v180 offset:1024
	ds_read_b128 v[176:179], v180 offset:2048
	ds_read_b128 v[180:183], v180 offset:3072
	s_mov_b64 vcc, s[68:69]
	s_add_u32 s68, s68, 0x40000
	s_addc_u32 s69, s69, 0
	s_mov_b32 m0, s76
	ds_read_b128 v[184:187], v171 offset:32768
	ds_read_b128 v[190:193], v171 offset:33792
	ds_read_b128 v[194:197], v171 offset:34816
	ds_read_b128 v[198:201], v171 offset:35840
	ds_read_b128 v[202:205], v171 offset:36864
	ds_read_b128 v[206:209], v171 offset:37888
	ds_read_b128 v[210:213], v171 offset:38912
	global_load_lds_dwordx4 v144, s[68:69]
	s_mov_b32 m0, s77
	ds_read_b128 v[214:217], v171 offset:39936
	global_load_lds_dwordx4 v146, s[68:69]
	s_waitcnt vmcnt(8) lgkmcnt(0)
	s_setprio 1
	s_barrier
	v_mfma_f32_16x16x32_bf16 v[132:135], v[120:123], v[184:187], v[132:135]
	v_mfma_f32_16x16x32_bf16 v[124:127], v[136:139], v[184:187], v[124:127]
	v_mfma_f32_16x16x32_bf16 v[108:111], v[120:123], v[194:197], v[108:111]
	v_mfma_f32_16x16x32_bf16 v[104:107], v[136:139], v[194:197], v[104:107]
	v_mfma_f32_16x16x32_bf16 v[92:95], v[120:123], v[202:205], v[92:95]
	v_mfma_f32_16x16x32_bf16 v[88:91], v[136:139], v[202:205], v[88:91]
	v_mfma_f32_16x16x32_bf16 v[76:79], v[120:123], v[210:213], v[76:79]
	v_mfma_f32_16x16x32_bf16 v[72:75], v[136:139], v[210:213], v[72:75]
	v_mfma_f32_16x16x32_bf16 v[132:135], v[128:131], v[190:193], v[132:135]
	v_mfma_f32_16x16x32_bf16 v[124:127], v[140:143], v[190:193], v[124:127]
	v_mfma_f32_16x16x32_bf16 v[108:111], v[128:131], v[198:201], v[108:111]
	v_mfma_f32_16x16x32_bf16 v[104:107], v[140:143], v[198:201], v[104:107]
	v_mfma_f32_16x16x32_bf16 v[92:95], v[128:131], v[206:209], v[92:95]
	v_mfma_f32_16x16x32_bf16 v[88:91], v[140:143], v[206:209], v[88:91]
	v_mfma_f32_16x16x32_bf16 v[76:79], v[128:131], v[214:217], v[76:79]
	v_mfma_f32_16x16x32_bf16 v[72:75], v[140:143], v[214:217], v[72:75]
	v_mfma_f32_16x16x32_bf16 v[116:119], v[160:163], v[184:187], v[116:119]
	v_mfma_f32_16x16x32_bf16 v[112:115], v[176:179], v[184:187], v[112:115]
	v_mfma_f32_16x16x32_bf16 v[100:103], v[160:163], v[194:197], v[100:103]
	v_mfma_f32_16x16x32_bf16 v[96:99], v[176:179], v[194:197], v[96:99]
	v_mfma_f32_16x16x32_bf16 v[84:87], v[160:163], v[202:205], v[84:87]
	v_mfma_f32_16x16x32_bf16 v[80:83], v[176:179], v[202:205], v[80:83]
	v_mfma_f32_16x16x32_bf16 v[68:71], v[160:163], v[210:213], v[68:71]
	v_mfma_f32_16x16x32_bf16 v[64:67], v[176:179], v[210:213], v[64:67]
	v_mfma_f32_16x16x32_bf16 v[116:119], v[172:175], v[190:193], v[116:119]
	v_mfma_f32_16x16x32_bf16 v[112:115], v[180:183], v[190:193], v[112:115]
	v_mfma_f32_16x16x32_bf16 v[100:103], v[172:175], v[198:201], v[100:103]
	v_mfma_f32_16x16x32_bf16 v[96:99], v[180:183], v[198:201], v[96:99]
	v_mfma_f32_16x16x32_bf16 v[84:87], v[172:175], v[206:209], v[84:87]
	v_mfma_f32_16x16x32_bf16 v[80:83], v[180:183], v[206:209], v[80:83]
	v_mfma_f32_16x16x32_bf16 v[68:71], v[172:175], v[214:217], v[68:71]
	v_mfma_f32_16x16x32_bf16 v[64:67], v[180:183], v[214:217], v[64:67]
	s_setprio 0
	s_barrier
	s_add_i32 s68, s91, s73
	s_add_i32 m0, s68, 0xffffff80
	ds_read_b128 v[184:187], v171 offset:49152
	ds_read_b128 v[190:193], v171 offset:50176
	ds_read_b128 v[194:197], v171 offset:51200
	ds_read_b128 v[198:201], v171 offset:52224
	global_load_lds_dwordx4 v150, s[100:101] offset:128
	s_add_i32 m0, s68, 0x1f80
	s_add_i32 s68, s92, s73
	global_load_lds_dwordx4 v148, s[100:101] offset:128
	s_add_i32 m0, s68, 0xffffff80
	s_add_u32 s100, s100, s10
	s_addc_u32 s101, s101, s11
	global_load_lds_dwordx4 v150, s[100:101] offset:128
	s_add_i32 m0, s68, 0x1f80
	ds_read_b128 v[210:213], v171 offset:55296
	global_load_lds_dwordx4 v148, s[100:101] offset:128
	s_add_i32 m0, s80, 0xffffff80
	ds_read_b128 v[206:209], v171 offset:54272
	global_load_lds_dwordx4 v144, vcc offset:128
	s_add_i32 m0, s81, 0xffffff80
	ds_read_b128 v[202:205], v171 offset:53248
	global_load_lds_dwordx4 v146, vcc offset:128
	ds_read_b128 v[214:217], v171 offset:56320
	s_waitcnt vmcnt(8) lgkmcnt(0)
	s_setprio 1
	s_barrier
	v_mfma_f32_16x16x32_bf16 v[60:63], v[120:123], v[184:187], v[60:63]
	v_mfma_f32_16x16x32_bf16 v[56:59], v[136:139], v[184:187], v[56:59]
	v_mfma_f32_16x16x32_bf16 v[44:47], v[120:123], v[194:197], v[44:47]
	v_mfma_f32_16x16x32_bf16 v[40:43], v[136:139], v[194:197], v[40:43]
	v_mfma_f32_16x16x32_bf16 v[28:31], v[120:123], v[202:205], v[28:31]
	v_mfma_f32_16x16x32_bf16 v[24:27], v[136:139], v[202:205], v[24:27]
	v_mfma_f32_16x16x32_bf16 v[12:15], v[120:123], v[210:213], v[12:15]
	v_mfma_f32_16x16x32_bf16 v[8:11], v[136:139], v[210:213], v[8:11]
	v_mfma_f32_16x16x32_bf16 v[60:63], v[128:131], v[190:193], v[60:63]
	v_mfma_f32_16x16x32_bf16 v[56:59], v[140:143], v[190:193], v[56:59]
	v_mfma_f32_16x16x32_bf16 v[44:47], v[128:131], v[198:201], v[44:47]
	v_mfma_f32_16x16x32_bf16 v[40:43], v[140:143], v[198:201], v[40:43]
	v_mfma_f32_16x16x32_bf16 v[28:31], v[128:131], v[206:209], v[28:31]
	v_mfma_f32_16x16x32_bf16 v[24:27], v[140:143], v[206:209], v[24:27]
	v_mfma_f32_16x16x32_bf16 v[12:15], v[128:131], v[214:217], v[12:15]
	v_mfma_f32_16x16x32_bf16 v[8:11], v[140:143], v[214:217], v[8:11]
	v_mfma_f32_16x16x32_bf16 v[52:55], v[160:163], v[184:187], v[52:55]
	v_mfma_f32_16x16x32_bf16 v[48:51], v[176:179], v[184:187], v[48:51]
	v_mfma_f32_16x16x32_bf16 v[36:39], v[160:163], v[194:197], v[36:39]
	v_mfma_f32_16x16x32_bf16 v[32:35], v[176:179], v[194:197], v[32:35]
	v_mfma_f32_16x16x32_bf16 v[20:23], v[160:163], v[202:205], v[20:23]
	v_mfma_f32_16x16x32_bf16 v[16:19], v[176:179], v[202:205], v[16:19]
	v_mfma_f32_16x16x32_bf16 v[4:7], v[160:163], v[210:213], v[4:7]
	v_mfma_f32_16x16x32_bf16 v[0:3], v[176:179], v[210:213], v[0:3]
	v_mfma_f32_16x16x32_bf16 v[52:55], v[172:175], v[190:193], v[52:55]
	v_mfma_f32_16x16x32_bf16 v[48:51], v[180:183], v[190:193], v[48:51]
	v_mfma_f32_16x16x32_bf16 v[36:39], v[172:175], v[198:201], v[36:39]
	v_mfma_f32_16x16x32_bf16 v[32:35], v[180:183], v[198:201], v[32:35]
	v_mfma_f32_16x16x32_bf16 v[20:23], v[172:175], v[206:209], v[20:23]
	v_mfma_f32_16x16x32_bf16 v[16:19], v[180:183], v[206:209], v[16:19]
	v_mfma_f32_16x16x32_bf16 v[4:7], v[172:175], v[214:217], v[4:7]
	v_mfma_f32_16x16x32_bf16 v[0:3], v[180:183], v[214:217], v[0:3]
	s_setprio 0
	s_barrier
	s_add_u32 s8, s8, 0x100
	s_addc_u32 s9, s9, 0
	s_add_u32 s70, s70, 0x100
	s_addc_u32 s71, s71, 0
	s_cmp_ge_i32 s90, s83
	s_mov_b32 s68, s90
	s_cbranch_scc0 .LBB0_1679

; #define PG8_STAGE(bufoff, gbase, voff) do { _Pragma("unroll") for (int _i = 0; _i < 2; ++_i) \
;         __builtin_amdgcn_global_load_lds((const unsigned*)((const char*)(gbase) + (voff)[_i]), (PG8_LAS unsigned*)(lds + (bufoff) + ldsw + _i * 8192), 16, 0, 0); } while (0)
; #define PG8_LDA(dst, b, h) do { _Pragma("unroll") for (int m = 0; m < 4; ++m) _Pragma("unroll") for (int k = 0; k < 2; ++k) dst[m][k] = *(const PG8_LAS bf16x8*)(lds + PG8_SA(b, h) + aoff + m * 2048 + k * 1024); } while (0)
; #define PG8_LDB(dst, b, h) do { _Pragma("unroll") for (int n = 0; n < 2; ++n) _Pragma("unroll") for (int k = 0; k < 2; ++k) dst[n][k] = *(const PG8_LAS bf16x8*)(lds + PG8_SB(b, h) + boff + n * 2048 + k * 1024); } while (0)
; #define PG8_MMA(ai, bj, At, Bt) do { __builtin_amdgcn_s_setprio(1); _Pragma("unroll") for (int m = 0; m < 4; ++m) _Pragma("unroll") for (int n = 0; n < 2; ++n) _Pragma("unroll") for (int k = 0; k < 2; ++k) \
;         acc[ai][bj][m][n] = __builtin_amdgcn_mfma_f32_16x16x32_bf16(Bt[n][k], At[m][k], acc[ai][bj][m][n], 0, 0, 0); __builtin_amdgcn_s_setprio(0); } while (0)
; #define PG8_WAIT_V(n) asm volatile("s_waitcnt vmcnt(" #n ")" ::: "memory")
; #define PG8_WAIT_L(n) asm volatile("s_waitcnt lgkmcnt(" #n ")" ::: "memory")
; #define PG8_BAR __builtin_amdgcn_s_barrier()
; #define PG8_SCHED __builtin_amdgcn_sched_barrier(0)
; template <class Epi, class Sched, bool ALIGN_EPI = false, bool SP2 = false>
; __device__ __forceinline__ void gemm_phase(PG8_LAS unsigned char* lds, const Gemm g, const Sched& S, const Epi& E) {
;     ...
;             PG8_LDB(B0, 0, 0); PG8_LDB(B1, 0, 1); PG8_SCHED; PG8_LDA(At, 0, 0); PG8_STAGE(PG8_SA(1, 1), a1 + hstepA, voffA);
;             PG8_WAIT_V(8); PG8_WAIT_L(0); PG8_BAR; PG8_MMA(0, 0, At, B0); PG8_MMA(0, 1, At, B1); PG8_BAR; PG8_SCHED;
;             PG8_LDA(At, 0, 1); PG8_STAGE(PG8_SB(0, 0), b2, voffB); PG8_STAGE(PG8_SB(0, 1), b2 + hstep, voffB); PG8_STAGE(PG8_SA(0, 0), a2, voffA);
;             PG8_WAIT_V(8); PG8_WAIT_L(0); PG8_BAR; PG8_MMA(1, 0, At, B0); PG8_MMA(1, 1, At, B1); PG8_BAR; PG8_SCHED;
.LBB0_1815:
	ds_read_b128 v[150:153], v147
	ds_read_b128 v[154:157], v147 offset:1024
	ds_read_b128 v[158:161], v147 offset:2048
	ds_read_b128 v[162:165], v147 offset:3072
	ds_read_b128 v[166:169], v148
	ds_read_b128 v[170:173], v148 offset:1024
	ds_read_b128 v[174:177], v148 offset:2048
	ds_read_b128 v[178:181], v148 offset:3072
	s_add_i32 s57, s30, 2
	s_add_u32 s58, s10, 0xfffc0080
	s_addc_u32 s31, s11, -1
	s_cmp_eq_u32 s50, s30
	s_cselect_b32 s30, s56, s58
	s_cselect_b32 s31, s23, s31
	s_cselect_b32 s59, s25, s35
	s_cselect_b32 s58, s24, s34
	s_add_i32 m0, s29, 0xc000
	ds_read_b128 v[182:185], v149
	ds_read_b128 v[190:193], v149 offset:1024
	ds_read_b128 v[194:197], v149 offset:2048
	ds_read_b128 v[198:201], v149 offset:3072
	ds_read_b128 v[202:205], v149 offset:4096
	ds_read_b128 v[206:209], v149 offset:5120
	ds_read_b128 v[210:213], v149 offset:6144
	global_load_lds_dwordx4 v136, s[10:11]
	s_add_i32 m0, s29, 0xe000
	ds_read_b128 v[214:217], v149 offset:7168
	global_load_lds_dwordx4 v138, s[10:11]
	s_waitcnt vmcnt(8) lgkmcnt(0)
	s_setprio 1
	s_barrier
	v_mfma_f32_16x16x32_bf16 v[124:127], v[150:153], v[182:185], v[124:127]
	v_mfma_f32_16x16x32_bf16 v[116:119], v[158:161], v[182:185], v[116:119]
	v_mfma_f32_16x16x32_bf16 v[108:111], v[150:153], v[194:197], v[108:111]
	v_mfma_f32_16x16x32_bf16 v[100:103], v[158:161], v[194:197], v[100:103]
	v_mfma_f32_16x16x32_bf16 v[92:95], v[150:153], v[202:205], v[92:95]
	v_mfma_f32_16x16x32_bf16 v[84:87], v[158:161], v[202:205], v[84:87]
	v_mfma_f32_16x16x32_bf16 v[76:79], v[150:153], v[210:213], v[76:79]
	v_mfma_f32_16x16x32_bf16 v[68:71], v[158:161], v[210:213], v[68:71]
	v_mfma_f32_16x16x32_bf16 v[124:127], v[154:157], v[190:193], v[124:127]
	v_mfma_f32_16x16x32_bf16 v[116:119], v[162:165], v[190:193], v[116:119]
	v_mfma_f32_16x16x32_bf16 v[108:111], v[154:157], v[198:201], v[108:111]
	v_mfma_f32_16x16x32_bf16 v[100:103], v[162:165], v[198:201], v[100:103]
	v_mfma_f32_16x16x32_bf16 v[92:95], v[154:157], v[206:209], v[92:95]
	v_mfma_f32_16x16x32_bf16 v[84:87], v[162:165], v[206:209], v[84:87]
	v_mfma_f32_16x16x32_bf16 v[76:79], v[154:157], v[214:217], v[76:79]
	v_mfma_f32_16x16x32_bf16 v[68:71], v[162:165], v[214:217], v[68:71]
	v_mfma_f32_16x16x32_bf16 v[120:123], v[166:169], v[182:185], v[120:123]
	v_mfma_f32_16x16x32_bf16 v[112:115], v[174:177], v[182:185], v[112:115]
	v_mfma_f32_16x16x32_bf16 v[104:107], v[166:169], v[194:197], v[104:107]
	v_mfma_f32_16x16x32_bf16 v[96:99], v[174:177], v[194:197], v[96:99]
	v_mfma_f32_16x16x32_bf16 v[88:91], v[166:169], v[202:205], v[88:91]
	v_mfma_f32_16x16x32_bf16 v[80:83], v[174:177], v[202:205], v[80:83]
	v_mfma_f32_16x16x32_bf16 v[72:75], v[166:169], v[210:213], v[72:75]
	v_mfma_f32_16x16x32_bf16 v[64:67], v[174:177], v[210:213], v[64:67]
	v_mfma_f32_16x16x32_bf16 v[120:123], v[170:173], v[190:193], v[120:123]
	v_mfma_f32_16x16x32_bf16 v[112:115], v[178:181], v[190:193], v[112:115]
	v_mfma_f32_16x16x32_bf16 v[104:107], v[170:173], v[198:201], v[104:107]
	v_mfma_f32_16x16x32_bf16 v[96:99], v[178:181], v[198:201], v[96:99]
	v_mfma_f32_16x16x32_bf16 v[88:91], v[170:173], v[206:209], v[88:91]
	v_mfma_f32_16x16x32_bf16 v[80:83], v[178:181], v[206:209], v[80:83]
	v_mfma_f32_16x16x32_bf16 v[72:75], v[170:173], v[214:217], v[72:75]
	v_mfma_f32_16x16x32_bf16 v[64:67], v[178:181], v[214:217], v[64:67]
	s_setprio 0
	s_barrier
	s_add_i32 s60, s51, s38
	s_mov_b32 m0, s60
	ds_read_b128 v[182:185], v149 offset:16384
	ds_read_b128 v[190:193], v149 offset:17408
	ds_read_b128 v[194:197], v149 offset:18432
	ds_read_b128 v[198:201], v149 offset:19456
	global_load_lds_dwordx4 v134, s[58:59]
	s_add_i32 m0, s60, 0x2000
	s_mov_b64 s[100:101], s[58:59]
	s_add_i32 s60, s52, s38
	global_load_lds_dwordx4 v132, s[58:59]
	s_mov_b32 m0, s60
	s_add_u32 s58, s58, s4
	s_addc_u32 s59, s59, s5
	global_load_lds_dwordx4 v134, s[58:59]
	s_add_i32 m0, s60, 0x2000
	ds_read_b128 v[210:213], v149 offset:22528
	global_load_lds_dwordx4 v132, s[58:59]
	s_mov_b32 m0, s29
	ds_read_b128 v[206:209], v149 offset:21504
	global_load_lds_dwordx4 v128, s[30:31]
	s_mov_b32 m0, s41
	ds_read_b128 v[202:205], v149 offset:20480
	global_load_lds_dwordx4 v130, s[30:31]
	ds_read_b128 v[214:217], v149 offset:23552
	s_waitcnt vmcnt(8) lgkmcnt(0)
	s_setprio 1
	s_barrier
	v_mfma_f32_16x16x32_bf16 v[60:63], v[150:153], v[182:185], v[60:63]
	v_mfma_f32_16x16x32_bf16 v[52:55], v[158:161], v[182:185], v[52:55]
	v_mfma_f32_16x16x32_bf16 v[44:47], v[150:153], v[194:197], v[44:47]
	v_mfma_f32_16x16x32_bf16 v[36:39], v[158:161], v[194:197], v[36:39]
	v_mfma_f32_16x16x32_bf16 v[28:31], v[150:153], v[202:205], v[28:31]
	v_mfma_f32_16x16x32_bf16 v[20:23], v[158:161], v[202:205], v[20:23]
	v_mfma_f32_16x16x32_bf16 v[12:15], v[150:153], v[210:213], v[12:15]
	v_mfma_f32_16x16x32_bf16 v[4:7], v[158:161], v[210:213], v[4:7]
	v_mfma_f32_16x16x32_bf16 v[60:63], v[154:157], v[190:193], v[60:63]
	v_mfma_f32_16x16x32_bf16 v[52:55], v[162:165], v[190:193], v[52:55]
	v_mfma_f32_16x16x32_bf16 v[44:47], v[154:157], v[198:201], v[44:47]
	v_mfma_f32_16x16x32_bf16 v[36:39], v[162:165], v[198:201], v[36:39]
	v_mfma_f32_16x16x32_bf16 v[28:31], v[154:157], v[206:209], v[28:31]
	v_mfma_f32_16x16x32_bf16 v[20:23], v[162:165], v[206:209], v[20:23]
	v_mfma_f32_16x16x32_bf16 v[12:15], v[154:157], v[214:217], v[12:15]
	v_mfma_f32_16x16x32_bf16 v[4:7], v[162:165], v[214:217], v[4:7]
	v_mfma_f32_16x16x32_bf16 v[56:59], v[166:169], v[182:185], v[56:59]
	v_mfma_f32_16x16x32_bf16 v[48:51], v[174:177], v[182:185], v[48:51]
	v_mfma_f32_16x16x32_bf16 v[40:43], v[166:169], v[194:197], v[40:43]
	v_mfma_f32_16x16x32_bf16 v[32:35], v[174:177], v[194:197], v[32:35]
	v_mfma_f32_16x16x32_bf16 v[24:27], v[166:169], v[202:205], v[24:27]
	v_mfma_f32_16x16x32_bf16 v[16:19], v[174:177], v[202:205], v[16:19]
	v_mfma_f32_16x16x32_bf16 v[8:11], v[166:169], v[210:213], v[8:11]
	v_mfma_f32_16x16x32_bf16 v[0:3], v[174:177], v[210:213], v[0:3]
	v_mfma_f32_16x16x32_bf16 v[56:59], v[170:173], v[190:193], v[56:59]
	v_mfma_f32_16x16x32_bf16 v[48:51], v[178:181], v[190:193], v[48:51]
	v_mfma_f32_16x16x32_bf16 v[40:43], v[170:173], v[198:201], v[40:43]
	v_mfma_f32_16x16x32_bf16 v[32:35], v[178:181], v[198:201], v[32:35]
	v_mfma_f32_16x16x32_bf16 v[24:27], v[170:173], v[206:209], v[24:27]
	v_mfma_f32_16x16x32_bf16 v[16:19], v[178:181], v[206:209], v[16:19]
	v_mfma_f32_16x16x32_bf16 v[8:11], v[170:173], v[214:217], v[8:11]
	v_mfma_f32_16x16x32_bf16 v[0:3], v[178:181], v[214:217], v[0:3]
	s_setprio 0
	s_barrier
; #define PG8_STAGE(bufoff, gbase, voff) do { _Pragma("unroll") for (int _i = 0; _i < 2; ++_i) \
;         __builtin_amdgcn_global_load_lds((const unsigned*)((const char*)(gbase) + (voff)[_i]), (PG8_LAS unsigned*)(lds + (bufoff) + ldsw + _i * 8192), 16, 0, 0); } while (0)
; #define PG8_LDA(dst, b, h) do { _Pragma("unroll") for (int m = 0; m < 4; ++m) _Pragma("unroll") for (int k = 0; k < 2; ++k) dst[m][k] = *(const PG8_LAS bf16x8*)(lds + PG8_SA(b, h) + aoff + m * 2048 + k * 1024); } while (0)
; #define PG8_LDB(dst, b, h) do { _Pragma("unroll") for (int n = 0; n < 2; ++n) _Pragma("unroll") for (int k = 0; k < 2; ++k) dst[n][k] = *(const PG8_LAS bf16x8*)(lds + PG8_SB(b, h) + boff + n * 2048 + k * 1024); } while (0)
; #define PG8_MMA(ai, bj, At, Bt) do { __builtin_amdgcn_s_setprio(1); _Pragma("unroll") for (int m = 0; m < 4; ++m) _Pragma("unroll") for (int n = 0; n < 2; ++n) _Pragma("unroll") for (int k = 0; k < 2; ++k) \
;         acc[ai][bj][m][n] = __builtin_amdgcn_mfma_f32_16x16x32_bf16(Bt[n][k], At[m][k], acc[ai][bj][m][n], 0, 0, 0); __builtin_amdgcn_s_setprio(0); } while (0)
; #define PG8_WAIT_V(n) asm volatile("s_waitcnt vmcnt(" #n ")" ::: "memory")
; #define PG8_WAIT_L(n) asm volatile("s_waitcnt lgkmcnt(" #n ")" ::: "memory")
; #define PG8_BAR __builtin_amdgcn_s_barrier()
; template <class Epi, class Sched, bool ALIGN_EPI = false, bool SP2 = false>
; __device__ __forceinline__ void gemm_phase(PG8_LAS unsigned char* lds, const Gemm g, const Sched& S, const Epi& E) {
;     ...
;         for (int t = 0; t < nt; t += 2) {
;             const bool last = (t == nt - 2);
;             const char* a1 = cA + (size_t)(t + 1) * kstep;
;             const char* a2 = last ? nA : cA + (size_t)(t + 2) * kstep; const char* b2 = last ? nB : cB + (size_t)(t + 2) * kstep;
;             const char* a3 = a2 + kstep; const char* b3 = b2 + kstep;
;     ...
;             PG8_LDB(B0, 1, 0); PG8_LDB(B1, 1, 1); PG8_SCHED; PG8_LDA(At, 1, 0); PG8_STAGE(PG8_SA(0, 1), a2 + hstepA, voffA);
;             PG8_WAIT_V(8); PG8_WAIT_L(0); PG8_BAR; PG8_MMA(0, 0, At, B0); PG8_MMA(0, 1, At, B1); PG8_BAR; PG8_SCHED;
;             PG8_LDA(At, 1, 1); PG8_STAGE(PG8_SB(1, 0), b3, voffB); PG8_STAGE(PG8_SB(1, 1), b3 + hstep, voffB); PG8_STAGE(PG8_SA(1, 0), a3, voffA);
;             PG8_WAIT_V(8); PG8_WAIT_L(0); PG8_BAR; PG8_MMA(1, 0, At, B0); PG8_MMA(1, 1, At, B1); PG8_BAR; PG8_SCHED;
	s_add_i32 s58, 0, 0x18000
	s_add_i32 s59, 0, 0x1c000
	v_add_u32_e32 v162, s58, v145
	v_add_u32_e32 v178, s59, v145
	ds_read_b128 v[150:153], v162
	ds_read_b128 v[154:157], v162 offset:1024
	ds_read_b128 v[158:161], v162 offset:2048
	ds_read_b128 v[162:165], v162 offset:3072
	ds_read_b128 v[166:169], v178
	ds_read_b128 v[170:173], v178 offset:1024
	ds_read_b128 v[174:177], v178 offset:2048
	ds_read_b128 v[178:181], v178 offset:3072
	s_mov_b64 vcc, s[30:31]
	s_add_u32 s30, s30, 0x40000
	s_addc_u32 s31, s31, 0
	s_mov_b32 m0, s42
	ds_read_b128 v[182:185], v149 offset:32768
	ds_read_b128 v[190:193], v149 offset:33792
	ds_read_b128 v[194:197], v149 offset:34816
	ds_read_b128 v[198:201], v149 offset:35840
	ds_read_b128 v[202:205], v149 offset:36864
	ds_read_b128 v[206:209], v149 offset:37888
	ds_read_b128 v[210:213], v149 offset:38912
	global_load_lds_dwordx4 v128, s[30:31]
	s_mov_b32 m0, s43
	ds_read_b128 v[214:217], v149 offset:39936
	global_load_lds_dwordx4 v130, s[30:31]
	s_waitcnt vmcnt(8) lgkmcnt(0)
	s_setprio 1
	s_barrier
	v_mfma_f32_16x16x32_bf16 v[124:127], v[150:153], v[182:185], v[124:127]
	v_mfma_f32_16x16x32_bf16 v[116:119], v[158:161], v[182:185], v[116:119]
	v_mfma_f32_16x16x32_bf16 v[108:111], v[150:153], v[194:197], v[108:111]
	v_mfma_f32_16x16x32_bf16 v[100:103], v[158:161], v[194:197], v[100:103]
	v_mfma_f32_16x16x32_bf16 v[92:95], v[150:153], v[202:205], v[92:95]
	v_mfma_f32_16x16x32_bf16 v[84:87], v[158:161], v[202:205], v[84:87]
	v_mfma_f32_16x16x32_bf16 v[76:79], v[150:153], v[210:213], v[76:79]
	v_mfma_f32_16x16x32_bf16 v[68:71], v[158:161], v[210:213], v[68:71]
	v_mfma_f32_16x16x32_bf16 v[124:127], v[154:157], v[190:193], v[124:127]
	v_mfma_f32_16x16x32_bf16 v[116:119], v[162:165], v[190:193], v[116:119]
	v_mfma_f32_16x16x32_bf16 v[108:111], v[154:157], v[198:201], v[108:111]
	v_mfma_f32_16x16x32_bf16 v[100:103], v[162:165], v[198:201], v[100:103]
	v_mfma_f32_16x16x32_bf16 v[92:95], v[154:157], v[206:209], v[92:95]
	v_mfma_f32_16x16x32_bf16 v[84:87], v[162:165], v[206:209], v[84:87]
	v_mfma_f32_16x16x32_bf16 v[76:79], v[154:157], v[214:217], v[76:79]
	v_mfma_f32_16x16x32_bf16 v[68:71], v[162:165], v[214:217], v[68:71]
	v_mfma_f32_16x16x32_bf16 v[120:123], v[166:169], v[182:185], v[120:123]
	v_mfma_f32_16x16x32_bf16 v[112:115], v[174:177], v[182:185], v[112:115]
	v_mfma_f32_16x16x32_bf16 v[104:107], v[166:169], v[194:197], v[104:107]
	v_mfma_f32_16x16x32_bf16 v[96:99], v[174:177], v[194:197], v[96:99]
	v_mfma_f32_16x16x32_bf16 v[88:91], v[166:169], v[202:205], v[88:91]
	v_mfma_f32_16x16x32_bf16 v[80:83], v[174:177], v[202:205], v[80:83]
	v_mfma_f32_16x16x32_bf16 v[72:75], v[166:169], v[210:213], v[72:75]
	v_mfma_f32_16x16x32_bf16 v[64:67], v[174:177], v[210:213], v[64:67]
	v_mfma_f32_16x16x32_bf16 v[120:123], v[170:173], v[190:193], v[120:123]
	v_mfma_f32_16x16x32_bf16 v[112:115], v[178:181], v[190:193], v[112:115]
	v_mfma_f32_16x16x32_bf16 v[104:107], v[170:173], v[198:201], v[104:107]
	v_mfma_f32_16x16x32_bf16 v[96:99], v[178:181], v[198:201], v[96:99]
	v_mfma_f32_16x16x32_bf16 v[88:91], v[170:173], v[206:209], v[88:91]
	v_mfma_f32_16x16x32_bf16 v[80:83], v[178:181], v[206:209], v[80:83]
	v_mfma_f32_16x16x32_bf16 v[72:75], v[170:173], v[214:217], v[72:75]
	v_mfma_f32_16x16x32_bf16 v[64:67], v[178:181], v[214:217], v[64:67]
	s_setprio 0
	s_barrier
	s_add_i32 s30, s58, s38
	s_add_i32 m0, s30, 0xffffff80
	ds_read_b128 v[182:185], v149 offset:49152
	ds_read_b128 v[190:193], v149 offset:50176
	ds_read_b128 v[194:197], v149 offset:51200
	ds_read_b128 v[198:201], v149 offset:52224
	global_load_lds_dwordx4 v134, s[100:101] offset:128
	s_add_i32 m0, s30, 0x1f80
	s_add_i32 s30, s59, s38
	global_load_lds_dwordx4 v132, s[100:101] offset:128
	s_add_i32 m0, s30, 0xffffff80
	s_add_u32 s100, s100, s4
	s_addc_u32 s101, s101, s5
	global_load_lds_dwordx4 v134, s[100:101] offset:128
	s_add_i32 m0, s30, 0x1f80
	ds_read_b128 v[210:213], v149 offset:55296
	global_load_lds_dwordx4 v132, s[100:101] offset:128
	s_add_i32 m0, s46, 0xffffff80
	ds_read_b128 v[206:209], v149 offset:54272
	global_load_lds_dwordx4 v128, vcc offset:128
	s_add_i32 m0, s47, 0xffffff80
	ds_read_b128 v[202:205], v149 offset:53248
	global_load_lds_dwordx4 v130, vcc offset:128
	ds_read_b128 v[214:217], v149 offset:56320
	s_waitcnt vmcnt(8) lgkmcnt(0)
	s_setprio 1
	s_barrier
	v_mfma_f32_16x16x32_bf16 v[60:63], v[150:153], v[182:185], v[60:63]
	v_mfma_f32_16x16x32_bf16 v[52:55], v[158:161], v[182:185], v[52:55]
	v_mfma_f32_16x16x32_bf16 v[44:47], v[150:153], v[194:197], v[44:47]
	v_mfma_f32_16x16x32_bf16 v[36:39], v[158:161], v[194:197], v[36:39]
	v_mfma_f32_16x16x32_bf16 v[28:31], v[150:153], v[202:205], v[28:31]
	v_mfma_f32_16x16x32_bf16 v[20:23], v[158:161], v[202:205], v[20:23]
	v_mfma_f32_16x16x32_bf16 v[12:15], v[150:153], v[210:213], v[12:15]
	v_mfma_f32_16x16x32_bf16 v[4:7], v[158:161], v[210:213], v[4:7]
	v_mfma_f32_16x16x32_bf16 v[60:63], v[154:157], v[190:193], v[60:63]
	v_mfma_f32_16x16x32_bf16 v[52:55], v[162:165], v[190:193], v[52:55]
	v_mfma_f32_16x16x32_bf16 v[44:47], v[154:157], v[198:201], v[44:47]
	v_mfma_f32_16x16x32_bf16 v[36:39], v[162:165], v[198:201], v[36:39]
	v_mfma_f32_16x16x32_bf16 v[28:31], v[154:157], v[206:209], v[28:31]
	v_mfma_f32_16x16x32_bf16 v[20:23], v[162:165], v[206:209], v[20:23]
	v_mfma_f32_16x16x32_bf16 v[12:15], v[154:157], v[214:217], v[12:15]
	v_mfma_f32_16x16x32_bf16 v[4:7], v[162:165], v[214:217], v[4:7]
	v_mfma_f32_16x16x32_bf16 v[56:59], v[166:169], v[182:185], v[56:59]
	v_mfma_f32_16x16x32_bf16 v[48:51], v[174:177], v[182:185], v[48:51]
	v_mfma_f32_16x16x32_bf16 v[40:43], v[166:169], v[194:197], v[40:43]
	v_mfma_f32_16x16x32_bf16 v[32:35], v[174:177], v[194:197], v[32:35]
	v_mfma_f32_16x16x32_bf16 v[24:27], v[166:169], v[202:205], v[24:27]
	v_mfma_f32_16x16x32_bf16 v[16:19], v[174:177], v[202:205], v[16:19]
	v_mfma_f32_16x16x32_bf16 v[8:11], v[166:169], v[210:213], v[8:11]
	v_mfma_f32_16x16x32_bf16 v[0:3], v[174:177], v[210:213], v[0:3]
	v_mfma_f32_16x16x32_bf16 v[56:59], v[170:173], v[190:193], v[56:59]
	v_mfma_f32_16x16x32_bf16 v[48:51], v[178:181], v[190:193], v[48:51]
	v_mfma_f32_16x16x32_bf16 v[40:43], v[170:173], v[198:201], v[40:43]
	v_mfma_f32_16x16x32_bf16 v[32:35], v[178:181], v[198:201], v[32:35]
	v_mfma_f32_16x16x32_bf16 v[24:27], v[170:173], v[206:209], v[24:27]
	v_mfma_f32_16x16x32_bf16 v[16:19], v[178:181], v[206:209], v[16:19]
	v_mfma_f32_16x16x32_bf16 v[8:11], v[170:173], v[214:217], v[8:11]
	v_mfma_f32_16x16x32_bf16 v[0:3], v[178:181], v[214:217], v[0:3]
	s_setprio 0
	s_barrier
	s_add_u32 s10, s10, 0x100
	s_addc_u32 s11, s11, 0
	s_add_u32 s34, s34, 0x100
	s_addc_u32 s35, s35, 0
	s_cmp_ge_i32 s57, s49
	s_mov_b32 s30, s57
	s_cbranch_scc0 .LBB0_1815

; #define PG8_STAGE(bufoff, gbase, voff) do { _Pragma("unroll") for (int _i = 0; _i < 2; ++_i) \
;         __builtin_amdgcn_global_load_lds((const unsigned*)((const char*)(gbase) + (voff)[_i]), (PG8_LAS unsigned*)(lds + (bufoff) + ldsw + _i * 8192), 16, 0, 0); } while (0)
; #define PG8_LDA(dst, b, h) do { _Pragma("unroll") for (int m = 0; m < 4; ++m) _Pragma("unroll") for (int k = 0; k < 2; ++k) dst[m][k] = *(const PG8_LAS bf16x8*)(lds + PG8_SA(b, h) + aoff + m * 2048 + k * 1024); } while (0)
; #define PG8_LDB(dst, b, h) do { _Pragma("unroll") for (int n = 0; n < 2; ++n) _Pragma("unroll") for (int k = 0; k < 2; ++k) dst[n][k] = *(const PG8_LAS bf16x8*)(lds + PG8_SB(b, h) + boff + n * 2048 + k * 1024); } while (0)
; #define PG8_MMA(ai, bj, At, Bt) do { __builtin_amdgcn_s_setprio(1); _Pragma("unroll") for (int m = 0; m < 4; ++m) _Pragma("unroll") for (int n = 0; n < 2; ++n) _Pragma("unroll") for (int k = 0; k < 2; ++k) \
;         acc[ai][bj][m][n] = __builtin_amdgcn_mfma_f32_16x16x32_bf16(Bt[n][k], At[m][k], acc[ai][bj][m][n], 0, 0, 0); __builtin_amdgcn_s_setprio(0); } while (0)
; #define PG8_WAIT_V(n) asm volatile("s_waitcnt vmcnt(" #n ")" ::: "memory")
; #define PG8_WAIT_L(n) asm volatile("s_waitcnt lgkmcnt(" #n ")" ::: "memory")
; #define PG8_BAR __builtin_amdgcn_s_barrier()
; #define PG8_SCHED __builtin_amdgcn_sched_barrier(0)
; template <class Epi, class Sched, bool ALIGN_EPI = false, bool SP2 = false>
; __device__ __forceinline__ void gemm_phase(PG8_LAS unsigned char* lds, const Gemm g, const Sched& S, const Epi& E) {
;     ...
;             PG8_LDB(B0, 0, 0); PG8_LDB(B1, 0, 1); PG8_SCHED; PG8_LDA(At, 0, 0); PG8_STAGE(PG8_SA(1, 1), a1 + hstepA, voffA);
;             PG8_WAIT_V(8); PG8_WAIT_L(0); PG8_BAR; PG8_MMA(0, 0, At, B0); PG8_MMA(0, 1, At, B1); PG8_BAR; PG8_SCHED;
;             PG8_LDA(At, 0, 1); PG8_STAGE(PG8_SB(0, 0), b2, voffB); PG8_STAGE(PG8_SB(0, 1), b2 + hstep, voffB); PG8_STAGE(PG8_SA(0, 0), a2, voffA);
;             PG8_WAIT_V(8); PG8_WAIT_L(0); PG8_BAR; PG8_MMA(1, 0, At, B0); PG8_MMA(1, 1, At, B1); PG8_BAR; PG8_SCHED;
.LBB0_1897:
	ds_read_b128 v[128:131], v169
	ds_read_b128 v[132:135], v169 offset:1024
	ds_read_b128 v[136:139], v169 offset:2048
	ds_read_b128 v[140:143], v169 offset:3072
	ds_read_b128 v[160:163], v170
	ds_read_b128 v[172:175], v170 offset:1024
	ds_read_b128 v[176:179], v170 offset:2048
	ds_read_b128 v[180:183], v170 offset:3072
	s_add_i32 s63, s38, 2
	s_add_u32 s64, s36, 0xfff50080
	s_addc_u32 s39, s37, -1
	s_cmp_eq_u32 s53, s38
	s_cselect_b32 s38, s4, s64
	s_cselect_b32 s39, s5, s39
	s_cselect_b32 s65, s35, s62
	s_cselect_b32 s64, s34, s61
	s_add_i32 m0, s44, 0xc000
	ds_read_b128 v[184:187], v171
	ds_read_b128 v[188:191], v171 offset:1024
	ds_read_b128 v[192:195], v171 offset:2048
	ds_read_b128 v[196:199], v171 offset:3072
	ds_read_b128 v[200:203], v171 offset:4096
	ds_read_b128 v[204:207], v171 offset:5120
	ds_read_b128 v[208:211], v171 offset:6144
	global_load_lds_dwordx4 v152, s[36:37]
	s_add_i32 m0, s44, 0xe000
	ds_read_b128 v[212:215], v171 offset:7168
	global_load_lds_dwordx4 v154, s[36:37]
	s_waitcnt vmcnt(8) lgkmcnt(0)
	s_setprio 1
	s_barrier
	v_mfma_f32_16x16x32_bf16 v[124:127], v[128:131], v[184:187], v[124:127]
	v_mfma_f32_16x16x32_bf16 v[120:123], v[136:139], v[184:187], v[120:123]
	v_mfma_f32_16x16x32_bf16 v[108:111], v[128:131], v[192:195], v[108:111]
	v_mfma_f32_16x16x32_bf16 v[104:107], v[136:139], v[192:195], v[104:107]
	v_mfma_f32_16x16x32_bf16 v[92:95], v[128:131], v[200:203], v[92:95]
	v_mfma_f32_16x16x32_bf16 v[88:91], v[136:139], v[200:203], v[88:91]
	v_mfma_f32_16x16x32_bf16 v[76:79], v[128:131], v[208:211], v[76:79]
	v_mfma_f32_16x16x32_bf16 v[72:75], v[136:139], v[208:211], v[72:75]
	v_mfma_f32_16x16x32_bf16 v[124:127], v[132:135], v[188:191], v[124:127]
	v_mfma_f32_16x16x32_bf16 v[120:123], v[140:143], v[188:191], v[120:123]
	v_mfma_f32_16x16x32_bf16 v[108:111], v[132:135], v[196:199], v[108:111]
	v_mfma_f32_16x16x32_bf16 v[104:107], v[140:143], v[196:199], v[104:107]
	v_mfma_f32_16x16x32_bf16 v[92:95], v[132:135], v[204:207], v[92:95]
	v_mfma_f32_16x16x32_bf16 v[88:91], v[140:143], v[204:207], v[88:91]
	v_mfma_f32_16x16x32_bf16 v[76:79], v[132:135], v[212:215], v[76:79]
	v_mfma_f32_16x16x32_bf16 v[72:75], v[140:143], v[212:215], v[72:75]
	v_mfma_f32_16x16x32_bf16 v[116:119], v[160:163], v[184:187], v[116:119]
	v_mfma_f32_16x16x32_bf16 v[112:115], v[176:179], v[184:187], v[112:115]
	v_mfma_f32_16x16x32_bf16 v[100:103], v[160:163], v[192:195], v[100:103]
	v_mfma_f32_16x16x32_bf16 v[96:99], v[176:179], v[192:195], v[96:99]
	v_mfma_f32_16x16x32_bf16 v[84:87], v[160:163], v[200:203], v[84:87]
	v_mfma_f32_16x16x32_bf16 v[80:83], v[176:179], v[200:203], v[80:83]
	v_mfma_f32_16x16x32_bf16 v[68:71], v[160:163], v[208:211], v[68:71]
	v_mfma_f32_16x16x32_bf16 v[64:67], v[176:179], v[208:211], v[64:67]
	v_mfma_f32_16x16x32_bf16 v[116:119], v[172:175], v[188:191], v[116:119]
	v_mfma_f32_16x16x32_bf16 v[112:115], v[180:183], v[188:191], v[112:115]
	v_mfma_f32_16x16x32_bf16 v[100:103], v[172:175], v[196:199], v[100:103]
	v_mfma_f32_16x16x32_bf16 v[96:99], v[180:183], v[196:199], v[96:99]
	v_mfma_f32_16x16x32_bf16 v[84:87], v[172:175], v[204:207], v[84:87]
	v_mfma_f32_16x16x32_bf16 v[80:83], v[180:183], v[204:207], v[80:83]
	v_mfma_f32_16x16x32_bf16 v[68:71], v[172:175], v[212:215], v[68:71]
	v_mfma_f32_16x16x32_bf16 v[64:67], v[180:183], v[212:215], v[64:67]
	s_setprio 0
	s_barrier
	s_add_i32 s66, s54, s42
	s_mov_b32 m0, s66
	ds_read_b128 v[184:187], v171 offset:16384
	ds_read_b128 v[188:191], v171 offset:17408
	ds_read_b128 v[192:195], v171 offset:18432
	ds_read_b128 v[196:199], v171 offset:19456
	global_load_lds_dwordx4 v150, s[64:65]
	s_add_i32 m0, s66, 0x2000
	s_mov_b64 s[100:101], s[64:65]
	s_add_i32 s66, s55, s42
	global_load_lds_dwordx4 v148, s[64:65]
	s_mov_b32 m0, s66
	s_add_u32 s64, s64, s6
	s_addc_u32 s65, s65, s7
	global_load_lds_dwordx4 v150, s[64:65]
	s_add_i32 m0, s66, 0x2000
	ds_read_b128 v[208:211], v171 offset:22528
	global_load_lds_dwordx4 v148, s[64:65]
	s_mov_b32 m0, s44
	ds_read_b128 v[204:207], v171 offset:21504
	global_load_lds_dwordx4 v144, s[38:39]
	s_mov_b32 m0, s45
	ds_read_b128 v[200:203], v171 offset:20480
	global_load_lds_dwordx4 v146, s[38:39]
	ds_read_b128 v[212:215], v171 offset:23552
	s_waitcnt vmcnt(8) lgkmcnt(0)
	s_setprio 1
	s_barrier
	v_mfma_f32_16x16x32_bf16 v[60:63], v[128:131], v[184:187], v[60:63]
	v_mfma_f32_16x16x32_bf16 v[56:59], v[136:139], v[184:187], v[56:59]
	v_mfma_f32_16x16x32_bf16 v[44:47], v[128:131], v[192:195], v[44:47]
	v_mfma_f32_16x16x32_bf16 v[40:43], v[136:139], v[192:195], v[40:43]
	v_mfma_f32_16x16x32_bf16 v[28:31], v[128:131], v[200:203], v[28:31]
	v_mfma_f32_16x16x32_bf16 v[24:27], v[136:139], v[200:203], v[24:27]
	v_mfma_f32_16x16x32_bf16 v[12:15], v[128:131], v[208:211], v[12:15]
	v_mfma_f32_16x16x32_bf16 v[8:11], v[136:139], v[208:211], v[8:11]
	v_mfma_f32_16x16x32_bf16 v[60:63], v[132:135], v[188:191], v[60:63]
	v_mfma_f32_16x16x32_bf16 v[56:59], v[140:143], v[188:191], v[56:59]
	v_mfma_f32_16x16x32_bf16 v[44:47], v[132:135], v[196:199], v[44:47]
	v_mfma_f32_16x16x32_bf16 v[40:43], v[140:143], v[196:199], v[40:43]
	v_mfma_f32_16x16x32_bf16 v[28:31], v[132:135], v[204:207], v[28:31]
	v_mfma_f32_16x16x32_bf16 v[24:27], v[140:143], v[204:207], v[24:27]
	v_mfma_f32_16x16x32_bf16 v[12:15], v[132:135], v[212:215], v[12:15]
	v_mfma_f32_16x16x32_bf16 v[8:11], v[140:143], v[212:215], v[8:11]
	v_mfma_f32_16x16x32_bf16 v[52:55], v[160:163], v[184:187], v[52:55]
	v_mfma_f32_16x16x32_bf16 v[48:51], v[176:179], v[184:187], v[48:51]
	v_mfma_f32_16x16x32_bf16 v[36:39], v[160:163], v[192:195], v[36:39]
	v_mfma_f32_16x16x32_bf16 v[32:35], v[176:179], v[192:195], v[32:35]
	v_mfma_f32_16x16x32_bf16 v[20:23], v[160:163], v[200:203], v[20:23]
	v_mfma_f32_16x16x32_bf16 v[16:19], v[176:179], v[200:203], v[16:19]
	v_mfma_f32_16x16x32_bf16 v[4:7], v[160:163], v[208:211], v[4:7]
	v_mfma_f32_16x16x32_bf16 v[0:3], v[176:179], v[208:211], v[0:3]
	v_mfma_f32_16x16x32_bf16 v[52:55], v[172:175], v[188:191], v[52:55]
	v_mfma_f32_16x16x32_bf16 v[48:51], v[180:183], v[188:191], v[48:51]
	v_mfma_f32_16x16x32_bf16 v[36:39], v[172:175], v[196:199], v[36:39]
	v_mfma_f32_16x16x32_bf16 v[32:35], v[180:183], v[196:199], v[32:35]
	v_mfma_f32_16x16x32_bf16 v[20:23], v[172:175], v[204:207], v[20:23]
	v_mfma_f32_16x16x32_bf16 v[16:19], v[180:183], v[204:207], v[16:19]
	v_mfma_f32_16x16x32_bf16 v[4:7], v[172:175], v[212:215], v[4:7]
	v_mfma_f32_16x16x32_bf16 v[0:3], v[180:183], v[212:215], v[0:3]
	s_setprio 0
	s_barrier
; #define PG8_STAGE(bufoff, gbase, voff) do { _Pragma("unroll") for (int _i = 0; _i < 2; ++_i) \
;         __builtin_amdgcn_global_load_lds((const unsigned*)((const char*)(gbase) + (voff)[_i]), (PG8_LAS unsigned*)(lds + (bufoff) + ldsw + _i * 8192), 16, 0, 0); } while (0)
; #define PG8_LDA(dst, b, h) do { _Pragma("unroll") for (int m = 0; m < 4; ++m) _Pragma("unroll") for (int k = 0; k < 2; ++k) dst[m][k] = *(const PG8_LAS bf16x8*)(lds + PG8_SA(b, h) + aoff + m * 2048 + k * 1024); } while (0)
; #define PG8_LDB(dst, b, h) do { _Pragma("unroll") for (int n = 0; n < 2; ++n) _Pragma("unroll") for (int k = 0; k < 2; ++k) dst[n][k] = *(const PG8_LAS bf16x8*)(lds + PG8_SB(b, h) + boff + n * 2048 + k * 1024); } while (0)
; #define PG8_MMA(ai, bj, At, Bt) do { __builtin_amdgcn_s_setprio(1); _Pragma("unroll") for (int m = 0; m < 4; ++m) _Pragma("unroll") for (int n = 0; n < 2; ++n) _Pragma("unroll") for (int k = 0; k < 2; ++k) \
;         acc[ai][bj][m][n] = __builtin_amdgcn_mfma_f32_16x16x32_bf16(Bt[n][k], At[m][k], acc[ai][bj][m][n], 0, 0, 0); __builtin_amdgcn_s_setprio(0); } while (0)
; #define PG8_WAIT_V(n) asm volatile("s_waitcnt vmcnt(" #n ")" ::: "memory")
; #define PG8_WAIT_L(n) asm volatile("s_waitcnt lgkmcnt(" #n ")" ::: "memory")
; #define PG8_BAR __builtin_amdgcn_s_barrier()
; template <class Epi, class Sched, bool ALIGN_EPI = false, bool SP2 = false>
; __device__ __forceinline__ void gemm_phase(PG8_LAS unsigned char* lds, const Gemm g, const Sched& S, const Epi& E) {
;     ...
;         for (int t = 0; t < nt; t += 2) {
;             const bool last = (t == nt - 2);
;             const char* a1 = cA + (size_t)(t + 1) * kstep;
;             const char* a2 = last ? nA : cA + (size_t)(t + 2) * kstep; const char* b2 = last ? nB : cB + (size_t)(t + 2) * kstep;
;             const char* a3 = a2 + kstep; const char* b3 = b2 + kstep;
;     ...
;             PG8_LDB(B0, 1, 0); PG8_LDB(B1, 1, 1); PG8_SCHED; PG8_LDA(At, 1, 0); PG8_STAGE(PG8_SA(0, 1), a2 + hstepA, voffA);
;             PG8_WAIT_V(8); PG8_WAIT_L(0); PG8_BAR; PG8_MMA(0, 0, At, B0); PG8_MMA(0, 1, At, B1); PG8_BAR; PG8_SCHED;
;             PG8_LDA(At, 1, 1); PG8_STAGE(PG8_SB(1, 0), b3, voffB); PG8_STAGE(PG8_SB(1, 1), b3 + hstep, voffB); PG8_STAGE(PG8_SA(1, 0), a3, voffA);
;             PG8_WAIT_V(8); PG8_WAIT_L(0); PG8_BAR; PG8_MMA(1, 0, At, B0); PG8_MMA(1, 1, At, B1); PG8_BAR; PG8_SCHED;
	s_add_i32 s64, 0, 0x18000
	s_add_i32 s65, 0, 0x1c000
	v_add_u32_e32 v140, s64, v167
	v_add_u32_e32 v180, s65, v167
	ds_read_b128 v[128:131], v140
	ds_read_b128 v[132:135], v140 offset:1024
	ds_read_b128 v[136:139], v140 offset:2048
	ds_read_b128 v[140:143], v140 offset:3072
	ds_read_b128 v[160:163], v180
	ds_read_b128 v[172:175], v180 offset:1024
	ds_read_b128 v[176:179], v180 offset:2048
	ds_read_b128 v[180:183], v180 offset:3072
	s_mov_b64 vcc, s[38:39]
	s_add_u32 s38, s38, 0xb0000
	s_addc_u32 s39, s39, 0
	s_mov_b32 m0, s46
	ds_read_b128 v[184:187], v171 offset:32768
	ds_read_b128 v[188:191], v171 offset:33792
	ds_read_b128 v[192:195], v171 offset:34816
	ds_read_b128 v[196:199], v171 offset:35840
	ds_read_b128 v[200:203], v171 offset:36864
	ds_read_b128 v[204:207], v171 offset:37888
	ds_read_b128 v[208:211], v171 offset:38912
	global_load_lds_dwordx4 v144, s[38:39]
	s_mov_b32 m0, s47
	ds_read_b128 v[212:215], v171 offset:39936
	global_load_lds_dwordx4 v146, s[38:39]
	s_waitcnt vmcnt(8) lgkmcnt(0)
	s_setprio 1
	s_barrier
	v_mfma_f32_16x16x32_bf16 v[124:127], v[128:131], v[184:187], v[124:127]
	v_mfma_f32_16x16x32_bf16 v[120:123], v[136:139], v[184:187], v[120:123]
	v_mfma_f32_16x16x32_bf16 v[108:111], v[128:131], v[192:195], v[108:111]
	v_mfma_f32_16x16x32_bf16 v[104:107], v[136:139], v[192:195], v[104:107]
	v_mfma_f32_16x16x32_bf16 v[92:95], v[128:131], v[200:203], v[92:95]
	v_mfma_f32_16x16x32_bf16 v[88:91], v[136:139], v[200:203], v[88:91]
	v_mfma_f32_16x16x32_bf16 v[76:79], v[128:131], v[208:211], v[76:79]
	v_mfma_f32_16x16x32_bf16 v[72:75], v[136:139], v[208:211], v[72:75]
	v_mfma_f32_16x16x32_bf16 v[124:127], v[132:135], v[188:191], v[124:127]
	v_mfma_f32_16x16x32_bf16 v[120:123], v[140:143], v[188:191], v[120:123]
	v_mfma_f32_16x16x32_bf16 v[108:111], v[132:135], v[196:199], v[108:111]
	v_mfma_f32_16x16x32_bf16 v[104:107], v[140:143], v[196:199], v[104:107]
	v_mfma_f32_16x16x32_bf16 v[92:95], v[132:135], v[204:207], v[92:95]
	v_mfma_f32_16x16x32_bf16 v[88:91], v[140:143], v[204:207], v[88:91]
	v_mfma_f32_16x16x32_bf16 v[76:79], v[132:135], v[212:215], v[76:79]
	v_mfma_f32_16x16x32_bf16 v[72:75], v[140:143], v[212:215], v[72:75]
	v_mfma_f32_16x16x32_bf16 v[116:119], v[160:163], v[184:187], v[116:119]
	v_mfma_f32_16x16x32_bf16 v[112:115], v[176:179], v[184:187], v[112:115]
	v_mfma_f32_16x16x32_bf16 v[100:103], v[160:163], v[192:195], v[100:103]
	v_mfma_f32_16x16x32_bf16 v[96:99], v[176:179], v[192:195], v[96:99]
	v_mfma_f32_16x16x32_bf16 v[84:87], v[160:163], v[200:203], v[84:87]
	v_mfma_f32_16x16x32_bf16 v[80:83], v[176:179], v[200:203], v[80:83]
	v_mfma_f32_16x16x32_bf16 v[68:71], v[160:163], v[208:211], v[68:71]
	v_mfma_f32_16x16x32_bf16 v[64:67], v[176:179], v[208:211], v[64:67]
	v_mfma_f32_16x16x32_bf16 v[116:119], v[172:175], v[188:191], v[116:119]
	v_mfma_f32_16x16x32_bf16 v[112:115], v[180:183], v[188:191], v[112:115]
	v_mfma_f32_16x16x32_bf16 v[100:103], v[172:175], v[196:199], v[100:103]
	v_mfma_f32_16x16x32_bf16 v[96:99], v[180:183], v[196:199], v[96:99]
	v_mfma_f32_16x16x32_bf16 v[84:87], v[172:175], v[204:207], v[84:87]
	v_mfma_f32_16x16x32_bf16 v[80:83], v[180:183], v[204:207], v[80:83]
	v_mfma_f32_16x16x32_bf16 v[68:71], v[172:175], v[212:215], v[68:71]
	v_mfma_f32_16x16x32_bf16 v[64:67], v[180:183], v[212:215], v[64:67]
	s_setprio 0
	s_barrier
	s_add_i32 s38, s64, s42
	s_add_i32 m0, s38, 0xffffff80
	ds_read_b128 v[184:187], v171 offset:49152
	ds_read_b128 v[188:191], v171 offset:50176
	ds_read_b128 v[192:195], v171 offset:51200
	ds_read_b128 v[196:199], v171 offset:52224
	global_load_lds_dwordx4 v150, s[100:101] offset:128
	s_add_i32 m0, s38, 0x1f80
	s_add_i32 s38, s65, s42
	global_load_lds_dwordx4 v148, s[100:101] offset:128
	s_add_i32 m0, s38, 0xffffff80
	s_add_u32 s100, s100, s6
	s_addc_u32 s101, s101, s7
	global_load_lds_dwordx4 v150, s[100:101] offset:128
	s_add_i32 m0, s38, 0x1f80
	ds_read_b128 v[208:211], v171 offset:55296
	global_load_lds_dwordx4 v148, s[100:101] offset:128
	s_add_i32 m0, s50, 0xffffff80
	ds_read_b128 v[204:207], v171 offset:54272
	global_load_lds_dwordx4 v144, vcc offset:128
	s_add_i32 m0, s51, 0xffffff80
	ds_read_b128 v[200:203], v171 offset:53248
	global_load_lds_dwordx4 v146, vcc offset:128
	ds_read_b128 v[212:215], v171 offset:56320
	s_waitcnt vmcnt(8) lgkmcnt(0)
	s_setprio 1
	s_barrier
	v_mfma_f32_16x16x32_bf16 v[60:63], v[128:131], v[184:187], v[60:63]
	v_mfma_f32_16x16x32_bf16 v[56:59], v[136:139], v[184:187], v[56:59]
	v_mfma_f32_16x16x32_bf16 v[44:47], v[128:131], v[192:195], v[44:47]
	v_mfma_f32_16x16x32_bf16 v[40:43], v[136:139], v[192:195], v[40:43]
	v_mfma_f32_16x16x32_bf16 v[28:31], v[128:131], v[200:203], v[28:31]
	v_mfma_f32_16x16x32_bf16 v[24:27], v[136:139], v[200:203], v[24:27]
	v_mfma_f32_16x16x32_bf16 v[12:15], v[128:131], v[208:211], v[12:15]
	v_mfma_f32_16x16x32_bf16 v[8:11], v[136:139], v[208:211], v[8:11]
	v_mfma_f32_16x16x32_bf16 v[60:63], v[132:135], v[188:191], v[60:63]
	v_mfma_f32_16x16x32_bf16 v[56:59], v[140:143], v[188:191], v[56:59]
	v_mfma_f32_16x16x32_bf16 v[44:47], v[132:135], v[196:199], v[44:47]
	v_mfma_f32_16x16x32_bf16 v[40:43], v[140:143], v[196:199], v[40:43]
	v_mfma_f32_16x16x32_bf16 v[28:31], v[132:135], v[204:207], v[28:31]
	v_mfma_f32_16x16x32_bf16 v[24:27], v[140:143], v[204:207], v[24:27]
	v_mfma_f32_16x16x32_bf16 v[12:15], v[132:135], v[212:215], v[12:15]
	v_mfma_f32_16x16x32_bf16 v[8:11], v[140:143], v[212:215], v[8:11]
	v_mfma_f32_16x16x32_bf16 v[52:55], v[160:163], v[184:187], v[52:55]
	v_mfma_f32_16x16x32_bf16 v[48:51], v[176:179], v[184:187], v[48:51]
	v_mfma_f32_16x16x32_bf16 v[36:39], v[160:163], v[192:195], v[36:39]
	v_mfma_f32_16x16x32_bf16 v[32:35], v[176:179], v[192:195], v[32:35]
	v_mfma_f32_16x16x32_bf16 v[20:23], v[160:163], v[200:203], v[20:23]
	v_mfma_f32_16x16x32_bf16 v[16:19], v[176:179], v[200:203], v[16:19]
	v_mfma_f32_16x16x32_bf16 v[4:7], v[160:163], v[208:211], v[4:7]
	v_mfma_f32_16x16x32_bf16 v[0:3], v[176:179], v[208:211], v[0:3]
	v_mfma_f32_16x16x32_bf16 v[52:55], v[172:175], v[188:191], v[52:55]
	v_mfma_f32_16x16x32_bf16 v[48:51], v[180:183], v[188:191], v[48:51]
	v_mfma_f32_16x16x32_bf16 v[36:39], v[172:175], v[196:199], v[36:39]
	v_mfma_f32_16x16x32_bf16 v[32:35], v[180:183], v[196:199], v[32:35]
	v_mfma_f32_16x16x32_bf16 v[20:23], v[172:175], v[204:207], v[20:23]
	v_mfma_f32_16x16x32_bf16 v[16:19], v[180:183], v[204:207], v[16:19]
	v_mfma_f32_16x16x32_bf16 v[4:7], v[172:175], v[212:215], v[4:7]
	v_mfma_f32_16x16x32_bf16 v[0:3], v[180:183], v[212:215], v[0:3]
	s_setprio 0
	s_barrier
	s_add_u32 s36, s36, 0x100
	s_addc_u32 s37, s37, 0
	s_add_u32 s61, s61, 0x100
	s_addc_u32 s62, s62, 0
	s_cmp_ge_i32 s63, s52
	s_mov_b32 s38, s63
	s_cbranch_scc0 .LBB0_1897
